# v17 + GEMM main loops: per-segment s_setprio toggles removed, one static s_setprio 1 for the second-dispatched wave half (wr==1) around each K-loop
# speedup vs baseline: 1.0045x; 1.0021x over previous
.LBB0_175:
	s_ashr_i32 s43, s42, 31
	s_lshl_b64 s[10:11], s[42:43], 20
	s_add_u32 s44, s51, s10
	s_addc_u32 s45, s52, s11
	s_and_b64 s[10:11], s[38:39], exec
	s_cselect_b32 s3, s45, s27
	s_cselect_b32 s10, s44, s26
	s_ashr_i32 s29, s28, 31
	s_lshl_b64 s[36:37], s[28:29], 20
	s_add_u32 s46, s7, s36
	s_addc_u32 s47, s53, s37
	s_and_b64 s[36:37], s[38:39], exec
	s_cselect_b32 s11, s47, s35
	s_cselect_b32 s21, s46, s34
	s_add_u32 s26, s26, 0x80080
	s_addc_u32 s27, s27, 0
	s_add_u32 s22, s34, 0x100
	v_mov_b32_e32 v4, 0
	s_addc_u32 s29, s35, 0
	s_mov_b32 s33, -2
	v_mov_b32_e32 v5, v4
	v_mov_b32_e32 v6, v4
	v_mov_b32_e32 v7, v4
	v_mov_b32_e32 v8, v4
	v_mov_b32_e32 v9, v4
	v_mov_b32_e32 v10, v4
	v_mov_b32_e32 v11, v4
	v_mov_b32_e32 v20, v4
	v_mov_b32_e32 v21, v4
	v_mov_b32_e32 v22, v4
	v_mov_b32_e32 v23, v4
	v_mov_b32_e32 v24, v4
	v_mov_b32_e32 v25, v4
	v_mov_b32_e32 v26, v4
	v_mov_b32_e32 v27, v4
	v_mov_b32_e32 v36, v4
	v_mov_b32_e32 v37, v4
	v_mov_b32_e32 v38, v4
	v_mov_b32_e32 v39, v4
	v_mov_b32_e32 v40, v4
	v_mov_b32_e32 v41, v4
	v_mov_b32_e32 v42, v4
	v_mov_b32_e32 v43, v4
	v_mov_b32_e32 v52, v4
	v_mov_b32_e32 v53, v4
	v_mov_b32_e32 v54, v4
	v_mov_b32_e32 v55, v4
	v_mov_b32_e32 v56, v4
	v_mov_b32_e32 v57, v4
	v_mov_b32_e32 v58, v4
	v_mov_b32_e32 v59, v4
	v_mov_b32_e32 v12, v4
	v_mov_b32_e32 v13, v4
	v_mov_b32_e32 v14, v4
	v_mov_b32_e32 v15, v4
	v_mov_b32_e32 v16, v4
	v_mov_b32_e32 v17, v4
	v_mov_b32_e32 v18, v4
	v_mov_b32_e32 v19, v4
	v_mov_b32_e32 v28, v4
	v_mov_b32_e32 v29, v4
	v_mov_b32_e32 v30, v4
	v_mov_b32_e32 v31, v4
	v_mov_b32_e32 v32, v4
	v_mov_b32_e32 v33, v4
	v_mov_b32_e32 v34, v4
	v_mov_b32_e32 v35, v4
	v_mov_b32_e32 v44, v4
	v_mov_b32_e32 v45, v4
	v_mov_b32_e32 v46, v4
	v_mov_b32_e32 v47, v4
	v_mov_b32_e32 v48, v4
	v_mov_b32_e32 v49, v4
	v_mov_b32_e32 v50, v4
	v_mov_b32_e32 v51, v4
	v_mov_b32_e32 v60, v4
	v_mov_b32_e32 v61, v4
	v_mov_b32_e32 v62, v4
	v_mov_b32_e32 v63, v4
	v_mov_b32_e32 v64, v4
	v_mov_b32_e32 v65, v4
	v_mov_b32_e32 v66, v4
	v_mov_b32_e32 v67, v4
	v_mov_b32_e32 v68, v4
	v_mov_b32_e32 v69, v4
	v_mov_b32_e32 v70, v4
	v_mov_b32_e32 v71, v4
	v_mov_b32_e32 v72, v4
	v_mov_b32_e32 v73, v4
	v_mov_b32_e32 v74, v4
	v_mov_b32_e32 v75, v4
	v_mov_b32_e32 v84, v4
	v_mov_b32_e32 v85, v4
	v_mov_b32_e32 v86, v4
	v_mov_b32_e32 v87, v4
	v_mov_b32_e32 v88, v4
	v_mov_b32_e32 v89, v4
	v_mov_b32_e32 v90, v4
	v_mov_b32_e32 v91, v4
	v_mov_b32_e32 v100, v4
	v_mov_b32_e32 v101, v4
	v_mov_b32_e32 v102, v4
	v_mov_b32_e32 v103, v4
	v_mov_b32_e32 v104, v4
	v_mov_b32_e32 v105, v4
	v_mov_b32_e32 v106, v4
	v_mov_b32_e32 v107, v4
	v_mov_b32_e32 v116, v4
	v_mov_b32_e32 v117, v4
	v_mov_b32_e32 v118, v4
	v_mov_b32_e32 v119, v4
	v_mov_b32_e32 v120, v4
	v_mov_b32_e32 v121, v4
	v_mov_b32_e32 v122, v4
	v_mov_b32_e32 v123, v4
	v_mov_b32_e32 v76, v4
	v_mov_b32_e32 v77, v4
	v_mov_b32_e32 v78, v4
	v_mov_b32_e32 v79, v4
	v_mov_b32_e32 v80, v4
	v_mov_b32_e32 v81, v4
	v_mov_b32_e32 v82, v4
	v_mov_b32_e32 v83, v4
	v_mov_b32_e32 v92, v4
	v_mov_b32_e32 v93, v4
	v_mov_b32_e32 v94, v4
	v_mov_b32_e32 v95, v4
	v_mov_b32_e32 v96, v4
	v_mov_b32_e32 v97, v4
	v_mov_b32_e32 v98, v4
	v_mov_b32_e32 v99, v4
	v_mov_b32_e32 v108, v4
	v_mov_b32_e32 v109, v4
	v_mov_b32_e32 v110, v4
	v_mov_b32_e32 v111, v4
	v_mov_b32_e32 v112, v4
	v_mov_b32_e32 v113, v4
	v_mov_b32_e32 v114, v4
	v_mov_b32_e32 v115, v4
	v_mov_b32_e32 v124, v4
	v_mov_b32_e32 v125, v4
	v_mov_b32_e32 v126, v4
	v_mov_b32_e32 v127, v4
	v_mov_b32_e32 v128, v4
	v_mov_b32_e32 v129, v4
	v_mov_b32_e32 v130, v4
	v_mov_b32_e32 v131, v4
	v_lshl_add_u32 v148, s2, 8, v150
	v_ashrrev_i32_e32 v149, 31, v148
	v_lshl_add_u64 v[144:145], v[148:149], 2, s[40:41]
	global_load_dword v244, v[144:145], off
	global_load_dword v245, v[144:145], off offset:64
	global_load_dword v246, v[144:145], off offset:128
	global_load_dword v247, v[144:145], off offset:192
	global_load_dword v248, v[144:145], off offset:512
	global_load_dword v249, v[144:145], off offset:576
	global_load_dword v250, v[144:145], off offset:640
	global_load_dword v251, v[144:145], off offset:704
	s_cmp_lg_u64 s[12:13], 0
	s_cbranch_scc1 .Lsp_g176
	s_setprio 1
.Lsp_g176:
.LBB0_176:
	s_add_u32 s34, s26, 0xfff80080
	s_addc_u32 s35, s27, -1
	s_add_i32 s43, 0, 0x10000
	s_cmp_eq_u32 s33, 28
	s_cselect_b32 s37, s3, s35
	s_cselect_b32 s36, s10, s34
	s_cselect_b32 s35, s11, s29
	s_cselect_b32 s34, s21, s22
	s_add_i32 s66, 0, 0x14000
	v_add_u32_e32 v158, s43, v151
	v_add_u32_e32 v182, s66, v151
	ds_read_b128 v[142:145], v158
	ds_read_b128 v[146:149], v158 offset:1024
	ds_read_b128 v[154:157], v158 offset:2048
	ds_read_b128 v[158:161], v158 offset:3072
	ds_read_b128 v[162:165], v182
	ds_read_b128 v[166:169], v182 offset:1024
	ds_read_b128 v[178:181], v182 offset:2048
	ds_read_b128 v[182:185], v182 offset:3072
	v_lshl_add_u64 v[228:229], s[26:27], 0, v[138:139]
	s_add_i32 m0, s56, 0xc000
	ds_read_b128 v[186:189], v153
	ds_read_b128 v[190:193], v153 offset:1024
	ds_read_b128 v[194:197], v153 offset:2048
	ds_read_b128 v[208:211], v153 offset:3072
	ds_read_b128 v[212:215], v153 offset:4096
	ds_read_b128 v[216:219], v153 offset:5120
	ds_read_b128 v[220:223], v153 offset:6144
	ds_read_b128 v[224:227], v153 offset:7168
	global_load_lds_dwordx4 v[228:229], off
	v_lshl_add_u64 v[228:229], s[26:27], 0, v[140:141]
	s_add_i32 m0, s56, 0xe000
	s_nop 0
	global_load_lds_dwordx4 v[228:229], off
	s_waitcnt vmcnt(8)
	s_waitcnt lgkmcnt(0)
	s_barrier
	s_waitcnt lgkmcnt(0)
	v_mfma_f32_16x16x32_bf16 v[128:131], v[142:145], v[186:189], v[128:131]
	v_mfma_f32_16x16x32_bf16 v[128:131], v[146:149], v[190:193], v[128:131]
	v_mfma_f32_16x16x32_bf16 v[124:127], v[158:161], v[190:193], v[124:127]
	v_mfma_f32_16x16x32_bf16 v[124:127], v[154:157], v[186:189], v[124:127]
	v_mfma_f32_16x16x32_bf16 v[108:111], v[154:157], v[194:197], v[108:111]
	v_mfma_f32_16x16x32_bf16 v[108:111], v[158:161], v[208:211], v[108:111]
	v_mfma_f32_16x16x32_bf16 v[112:115], v[146:149], v[208:211], v[112:115]
	v_mfma_f32_16x16x32_bf16 v[112:115], v[142:145], v[194:197], v[112:115]
	v_mfma_f32_16x16x32_bf16 v[96:99], v[142:145], v[212:215], v[96:99]
	v_mfma_f32_16x16x32_bf16 v[96:99], v[146:149], v[216:219], v[96:99]
	v_mfma_f32_16x16x32_bf16 v[92:95], v[158:161], v[216:219], v[92:95]
	v_mfma_f32_16x16x32_bf16 v[92:95], v[154:157], v[212:215], v[92:95]
	v_mfma_f32_16x16x32_bf16 v[76:79], v[154:157], v[220:223], v[76:79]
	v_mfma_f32_16x16x32_bf16 v[76:79], v[158:161], v[224:227], v[76:79]
	v_mfma_f32_16x16x32_bf16 v[80:83], v[146:149], v[224:227], v[80:83]
	v_mfma_f32_16x16x32_bf16 v[80:83], v[142:145], v[220:223], v[80:83]
	v_mfma_f32_16x16x32_bf16 v[120:123], v[162:165], v[186:189], v[120:123]
	v_mfma_f32_16x16x32_bf16 v[120:123], v[166:169], v[190:193], v[120:123]
	v_mfma_f32_16x16x32_bf16 v[116:119], v[182:185], v[190:193], v[116:119]
	v_mfma_f32_16x16x32_bf16 v[116:119], v[178:181], v[186:189], v[116:119]
	v_mfma_f32_16x16x32_bf16 v[100:103], v[178:181], v[194:197], v[100:103]
	v_mfma_f32_16x16x32_bf16 v[100:103], v[182:185], v[208:211], v[100:103]
	v_mfma_f32_16x16x32_bf16 v[104:107], v[166:169], v[208:211], v[104:107]
	v_mfma_f32_16x16x32_bf16 v[104:107], v[162:165], v[194:197], v[104:107]
	v_mfma_f32_16x16x32_bf16 v[88:91], v[162:165], v[212:215], v[88:91]
	v_mfma_f32_16x16x32_bf16 v[88:91], v[166:169], v[216:219], v[88:91]
	v_mfma_f32_16x16x32_bf16 v[84:87], v[182:185], v[216:219], v[84:87]
	v_mfma_f32_16x16x32_bf16 v[84:87], v[178:181], v[212:215], v[84:87]
	v_mfma_f32_16x16x32_bf16 v[68:71], v[178:181], v[220:223], v[68:71]
	v_mfma_f32_16x16x32_bf16 v[68:71], v[182:185], v[224:227], v[68:71]
	v_mfma_f32_16x16x32_bf16 v[72:75], v[166:169], v[224:227], v[72:75]
	v_mfma_f32_16x16x32_bf16 v[72:75], v[162:165], v[220:223], v[72:75]
	s_barrier
	s_add_i32 s43, s43, s54
	v_lshl_add_u64 v[228:229], s[34:35], 0, v[2:3]
	s_mov_b32 m0, s43
	ds_read_b128 v[186:189], v153 offset:16384
	ds_read_b128 v[190:193], v153 offset:17408
	ds_read_b128 v[194:197], v153 offset:18432
	ds_read_b128 v[208:211], v153 offset:19456
	ds_read_b128 v[212:215], v153 offset:20480
	ds_read_b128 v[216:219], v153 offset:21504
	ds_read_b128 v[220:223], v153 offset:22528
	ds_read_b128 v[224:227], v153 offset:23552
	global_load_lds_dwordx4 v[228:229], off
	s_add_i32 m0, s43, 0x2000
	s_add_u32 s64, s34, 0x80000
	v_lshl_add_u64 v[230:231], s[34:35], 0, v[132:133]
	s_addc_u32 s65, s35, 0
	s_add_i32 s43, s66, s54
	global_load_lds_dwordx4 v[230:231], off
	v_lshl_add_u64 v[232:233], s[64:65], 0, v[2:3]
	s_mov_b32 m0, s43
	v_lshl_add_u64 v[234:235], s[36:37], 0, v[134:135]
	global_load_lds_dwordx4 v[232:233], off
	v_lshl_add_u64 v[232:233], s[64:65], 0, v[132:133]
	s_add_i32 m0, s43, 0x2000
	s_nop 0
	global_load_lds_dwordx4 v[232:233], off
	v_lshl_add_u64 v[232:233], s[36:37], 0, v[136:137]
	s_mov_b32 m0, s56
	s_nop 0
	global_load_lds_dwordx4 v[232:233], off
	s_mov_b32 m0, s57
	s_nop 0
	global_load_lds_dwordx4 v[234:235], off
	s_waitcnt vmcnt(8)
	s_waitcnt lgkmcnt(0)
	s_barrier
	s_waitcnt lgkmcnt(0)
	v_mfma_f32_16x16x32_bf16 v[64:67], v[142:145], v[186:189], v[64:67]
	v_mfma_f32_16x16x32_bf16 v[64:67], v[146:149], v[190:193], v[64:67]
	v_mfma_f32_16x16x32_bf16 v[60:63], v[158:161], v[190:193], v[60:63]
	v_mfma_f32_16x16x32_bf16 v[60:63], v[154:157], v[186:189], v[60:63]
	v_mfma_f32_16x16x32_bf16 v[44:47], v[154:157], v[194:197], v[44:47]
	v_mfma_f32_16x16x32_bf16 v[44:47], v[158:161], v[208:211], v[44:47]
	v_mfma_f32_16x16x32_bf16 v[48:51], v[146:149], v[208:211], v[48:51]
	v_mfma_f32_16x16x32_bf16 v[48:51], v[142:145], v[194:197], v[48:51]
	v_mfma_f32_16x16x32_bf16 v[32:35], v[142:145], v[212:215], v[32:35]
	v_mfma_f32_16x16x32_bf16 v[32:35], v[146:149], v[216:219], v[32:35]
	v_mfma_f32_16x16x32_bf16 v[28:31], v[158:161], v[216:219], v[28:31]
	v_mfma_f32_16x16x32_bf16 v[28:31], v[154:157], v[212:215], v[28:31]
	v_mfma_f32_16x16x32_bf16 v[12:15], v[154:157], v[220:223], v[12:15]
	v_mfma_f32_16x16x32_bf16 v[12:15], v[158:161], v[224:227], v[12:15]
	v_mfma_f32_16x16x32_bf16 v[16:19], v[146:149], v[224:227], v[16:19]
	v_mfma_f32_16x16x32_bf16 v[16:19], v[142:145], v[220:223], v[16:19]
	v_mfma_f32_16x16x32_bf16 v[56:59], v[162:165], v[186:189], v[56:59]
	v_mfma_f32_16x16x32_bf16 v[56:59], v[166:169], v[190:193], v[56:59]
	v_mfma_f32_16x16x32_bf16 v[52:55], v[182:185], v[190:193], v[52:55]
	v_mfma_f32_16x16x32_bf16 v[52:55], v[178:181], v[186:189], v[52:55]
	v_mfma_f32_16x16x32_bf16 v[36:39], v[178:181], v[194:197], v[36:39]
	v_mfma_f32_16x16x32_bf16 v[36:39], v[182:185], v[208:211], v[36:39]
	v_mfma_f32_16x16x32_bf16 v[40:43], v[166:169], v[208:211], v[40:43]
	v_mfma_f32_16x16x32_bf16 v[40:43], v[162:165], v[194:197], v[40:43]
	v_mfma_f32_16x16x32_bf16 v[24:27], v[162:165], v[212:215], v[24:27]
	v_mfma_f32_16x16x32_bf16 v[24:27], v[166:169], v[216:219], v[24:27]
	v_mfma_f32_16x16x32_bf16 v[20:23], v[182:185], v[216:219], v[20:23]
	v_mfma_f32_16x16x32_bf16 v[20:23], v[178:181], v[212:215], v[20:23]
	v_mfma_f32_16x16x32_bf16 v[4:7], v[178:181], v[220:223], v[4:7]
	v_mfma_f32_16x16x32_bf16 v[4:7], v[182:185], v[224:227], v[4:7]
	v_mfma_f32_16x16x32_bf16 v[8:11], v[166:169], v[224:227], v[8:11]
	v_mfma_f32_16x16x32_bf16 v[8:11], v[162:165], v[220:223], v[8:11]
	s_barrier
	s_add_i32 s43, 0, 0x18000
	s_add_i32 s64, 0, 0x1c000
	v_add_u32_e32 v158, s43, v151
	v_add_u32_e32 v182, s64, v151
	ds_read_b128 v[142:145], v158
	ds_read_b128 v[146:149], v158 offset:1024
	ds_read_b128 v[154:157], v158 offset:2048
	ds_read_b128 v[158:161], v158 offset:3072
	ds_read_b128 v[162:165], v182
	ds_read_b128 v[166:169], v182 offset:1024
	ds_read_b128 v[178:181], v182 offset:2048
	ds_read_b128 v[182:185], v182 offset:3072
	s_add_u32 s36, s36, 0x80000
	s_addc_u32 s37, s37, 0
	s_mov_b32 m0, s58
	v_lshl_add_u64 v[236:237], s[36:37], 0, v[136:137]
	ds_read_b128 v[186:189], v153 offset:32768
	ds_read_b128 v[190:193], v153 offset:33792
	ds_read_b128 v[194:197], v153 offset:34816
	ds_read_b128 v[208:211], v153 offset:35840
	ds_read_b128 v[212:215], v153 offset:36864
	ds_read_b128 v[216:219], v153 offset:37888
	ds_read_b128 v[220:223], v153 offset:38912
	ds_read_b128 v[224:227], v153 offset:39936
	global_load_lds_dwordx4 v[236:237], off
	v_lshl_add_u64 v[236:237], s[36:37], 0, v[134:135]
	s_mov_b32 m0, s59
	s_nop 0
	global_load_lds_dwordx4 v[236:237], off
	s_waitcnt vmcnt(8)
	s_waitcnt lgkmcnt(0)
	s_barrier
	s_waitcnt lgkmcnt(0)
	v_mfma_f32_16x16x32_bf16 v[128:131], v[142:145], v[186:189], v[128:131]
	v_mfma_f32_16x16x32_bf16 v[128:131], v[146:149], v[190:193], v[128:131]
	v_mfma_f32_16x16x32_bf16 v[124:127], v[158:161], v[190:193], v[124:127]
	v_mfma_f32_16x16x32_bf16 v[124:127], v[154:157], v[186:189], v[124:127]
	v_mfma_f32_16x16x32_bf16 v[108:111], v[154:157], v[194:197], v[108:111]
	v_mfma_f32_16x16x32_bf16 v[108:111], v[158:161], v[208:211], v[108:111]
	v_mfma_f32_16x16x32_bf16 v[112:115], v[146:149], v[208:211], v[112:115]
	v_mfma_f32_16x16x32_bf16 v[112:115], v[142:145], v[194:197], v[112:115]
	v_mfma_f32_16x16x32_bf16 v[96:99], v[142:145], v[212:215], v[96:99]
	v_mfma_f32_16x16x32_bf16 v[96:99], v[146:149], v[216:219], v[96:99]
	v_mfma_f32_16x16x32_bf16 v[92:95], v[158:161], v[216:219], v[92:95]
	v_mfma_f32_16x16x32_bf16 v[92:95], v[154:157], v[212:215], v[92:95]
	v_mfma_f32_16x16x32_bf16 v[76:79], v[154:157], v[220:223], v[76:79]
	v_mfma_f32_16x16x32_bf16 v[76:79], v[158:161], v[224:227], v[76:79]
	v_mfma_f32_16x16x32_bf16 v[80:83], v[146:149], v[224:227], v[80:83]
	v_mfma_f32_16x16x32_bf16 v[80:83], v[142:145], v[220:223], v[80:83]
	v_mfma_f32_16x16x32_bf16 v[120:123], v[162:165], v[186:189], v[120:123]
	v_mfma_f32_16x16x32_bf16 v[120:123], v[166:169], v[190:193], v[120:123]
	v_mfma_f32_16x16x32_bf16 v[116:119], v[182:185], v[190:193], v[116:119]
	v_mfma_f32_16x16x32_bf16 v[116:119], v[178:181], v[186:189], v[116:119]
	v_mfma_f32_16x16x32_bf16 v[100:103], v[178:181], v[194:197], v[100:103]
	v_mfma_f32_16x16x32_bf16 v[100:103], v[182:185], v[208:211], v[100:103]
	v_mfma_f32_16x16x32_bf16 v[104:107], v[166:169], v[208:211], v[104:107]
	v_mfma_f32_16x16x32_bf16 v[104:107], v[162:165], v[194:197], v[104:107]
	v_mfma_f32_16x16x32_bf16 v[88:91], v[162:165], v[212:215], v[88:91]
	v_mfma_f32_16x16x32_bf16 v[88:91], v[166:169], v[216:219], v[88:91]
	v_mfma_f32_16x16x32_bf16 v[84:87], v[182:185], v[216:219], v[84:87]
	v_mfma_f32_16x16x32_bf16 v[84:87], v[178:181], v[212:215], v[84:87]
	v_mfma_f32_16x16x32_bf16 v[68:71], v[178:181], v[220:223], v[68:71]
	v_mfma_f32_16x16x32_bf16 v[68:71], v[182:185], v[224:227], v[68:71]
	v_mfma_f32_16x16x32_bf16 v[72:75], v[166:169], v[224:227], v[72:75]
	v_mfma_f32_16x16x32_bf16 v[72:75], v[162:165], v[220:223], v[72:75]
	s_barrier
	s_add_i32 s36, s43, s54
	v_lshl_add_u64 v[228:229], v[228:229], 0, s[18:19]
	s_mov_b32 m0, s36
	ds_read_b128 v[186:189], v153 offset:49152
	ds_read_b128 v[190:193], v153 offset:50176
	ds_read_b128 v[194:197], v153 offset:51200
	ds_read_b128 v[208:211], v153 offset:52224
	ds_read_b128 v[212:215], v153 offset:53248
	ds_read_b128 v[216:219], v153 offset:54272
	ds_read_b128 v[220:223], v153 offset:55296
	ds_read_b128 v[224:227], v153 offset:56320
	global_load_lds_dwordx4 v[228:229], off
	s_add_i32 m0, s36, 0x2000
	s_add_u32 s34, s34, 0x80080
	v_lshl_add_u64 v[228:229], v[230:231], 0, s[18:19]
	s_addc_u32 s35, s35, 0
	s_add_i32 s36, s64, s54
	global_load_lds_dwordx4 v[228:229], off
	v_lshl_add_u64 v[228:229], s[34:35], 0, v[2:3]
	s_mov_b32 m0, s36
	s_nop 0
	global_load_lds_dwordx4 v[228:229], off
	v_lshl_add_u64 v[228:229], s[34:35], 0, v[132:133]
	s_add_i32 m0, s36, 0x2000
	s_nop 0
	global_load_lds_dwordx4 v[228:229], off
	v_lshl_add_u64 v[228:229], v[232:233], 0, s[18:19]
	s_mov_b32 m0, s60
	s_nop 0
	global_load_lds_dwordx4 v[228:229], off
	v_lshl_add_u64 v[228:229], v[234:235], 0, s[18:19]
	s_mov_b32 m0, s61
	s_nop 0
	global_load_lds_dwordx4 v[228:229], off
	s_waitcnt vmcnt(8)
	s_waitcnt lgkmcnt(0)
	s_barrier
	s_waitcnt lgkmcnt(0)
	v_mfma_f32_16x16x32_bf16 v[64:67], v[142:145], v[186:189], v[64:67]
	v_mfma_f32_16x16x32_bf16 v[64:67], v[146:149], v[190:193], v[64:67]
	v_mfma_f32_16x16x32_bf16 v[60:63], v[158:161], v[190:193], v[60:63]
	v_mfma_f32_16x16x32_bf16 v[60:63], v[154:157], v[186:189], v[60:63]
	v_mfma_f32_16x16x32_bf16 v[44:47], v[154:157], v[194:197], v[44:47]
	v_mfma_f32_16x16x32_bf16 v[44:47], v[158:161], v[208:211], v[44:47]
	v_mfma_f32_16x16x32_bf16 v[48:51], v[146:149], v[208:211], v[48:51]
	v_mfma_f32_16x16x32_bf16 v[48:51], v[142:145], v[194:197], v[48:51]
	v_mfma_f32_16x16x32_bf16 v[32:35], v[142:145], v[212:215], v[32:35]
	v_mfma_f32_16x16x32_bf16 v[32:35], v[146:149], v[216:219], v[32:35]
	v_mfma_f32_16x16x32_bf16 v[28:31], v[158:161], v[216:219], v[28:31]
	v_mfma_f32_16x16x32_bf16 v[28:31], v[154:157], v[212:215], v[28:31]
	v_mfma_f32_16x16x32_bf16 v[12:15], v[154:157], v[220:223], v[12:15]
	v_mfma_f32_16x16x32_bf16 v[12:15], v[158:161], v[224:227], v[12:15]
	v_mfma_f32_16x16x32_bf16 v[16:19], v[146:149], v[224:227], v[16:19]
	v_mfma_f32_16x16x32_bf16 v[16:19], v[142:145], v[220:223], v[16:19]
	v_mfma_f32_16x16x32_bf16 v[56:59], v[162:165], v[186:189], v[56:59]
	v_mfma_f32_16x16x32_bf16 v[56:59], v[166:169], v[190:193], v[56:59]
	v_mfma_f32_16x16x32_bf16 v[52:55], v[182:185], v[190:193], v[52:55]
	v_mfma_f32_16x16x32_bf16 v[52:55], v[178:181], v[186:189], v[52:55]
	v_mfma_f32_16x16x32_bf16 v[36:39], v[178:181], v[194:197], v[36:39]
	v_mfma_f32_16x16x32_bf16 v[36:39], v[182:185], v[208:211], v[36:39]
	v_mfma_f32_16x16x32_bf16 v[40:43], v[166:169], v[208:211], v[40:43]
	v_mfma_f32_16x16x32_bf16 v[40:43], v[162:165], v[194:197], v[40:43]
	v_mfma_f32_16x16x32_bf16 v[24:27], v[162:165], v[212:215], v[24:27]
	v_mfma_f32_16x16x32_bf16 v[24:27], v[166:169], v[216:219], v[24:27]
	v_mfma_f32_16x16x32_bf16 v[20:23], v[182:185], v[216:219], v[20:23]
	v_mfma_f32_16x16x32_bf16 v[20:23], v[178:181], v[212:215], v[20:23]
	v_mfma_f32_16x16x32_bf16 v[4:7], v[178:181], v[220:223], v[4:7]
	v_mfma_f32_16x16x32_bf16 v[4:7], v[182:185], v[224:227], v[4:7]
	v_mfma_f32_16x16x32_bf16 v[8:11], v[166:169], v[224:227], v[8:11]
	v_mfma_f32_16x16x32_bf16 v[8:11], v[162:165], v[220:223], v[8:11]
	s_barrier
	s_add_i32 s33, s33, 2
	s_add_u32 s26, s26, 0x100
	s_addc_u32 s27, s27, 0
	s_add_u32 s22, s22, 0x100
	s_addc_u32 s29, s29, 0
	s_cmp_gt_u32 s33, 29
	s_cbranch_scc0 .LBB0_176
	s_setprio 0
	s_and_b64 vcc, exec, s[12:13]
	s_cbranch_vccz .LBB0_179
	s_barrier

.LBB0_197:
	s_ashr_i32 s43, s42, 31
	s_lshl_b64 s[10:11], s[42:43], 20
	s_add_u32 s44, s51, s10
	s_addc_u32 s45, s52, s11
	s_and_b64 s[10:11], s[38:39], exec
	s_cselect_b32 s3, s45, s27
	s_cselect_b32 s10, s44, s26
	s_ashr_i32 s29, s28, 31
	s_lshl_b64 s[36:37], s[28:29], 20
	s_add_u32 s46, s7, s36
	s_addc_u32 s47, s53, s37
	s_and_b64 s[36:37], s[38:39], exec
	s_cselect_b32 s11, s47, s35
	s_cselect_b32 s21, s46, s34
	s_add_u32 s26, s26, 0x80080
	s_addc_u32 s27, s27, 0
	s_add_u32 s22, s34, 0x100
	v_mov_b32_e32 v4, 0
	s_addc_u32 s29, s35, 0
	s_mov_b32 s33, -2
	v_mov_b32_e32 v5, v4
	v_mov_b32_e32 v6, v4
	v_mov_b32_e32 v7, v4
	v_mov_b32_e32 v8, v4
	v_mov_b32_e32 v9, v4
	v_mov_b32_e32 v10, v4
	v_mov_b32_e32 v11, v4
	v_mov_b32_e32 v20, v4
	v_mov_b32_e32 v21, v4
	v_mov_b32_e32 v22, v4
	v_mov_b32_e32 v23, v4
	v_mov_b32_e32 v24, v4
	v_mov_b32_e32 v25, v4
	v_mov_b32_e32 v26, v4
	v_mov_b32_e32 v27, v4
	v_mov_b32_e32 v36, v4
	v_mov_b32_e32 v37, v4
	v_mov_b32_e32 v38, v4
	v_mov_b32_e32 v39, v4
	v_mov_b32_e32 v40, v4
	v_mov_b32_e32 v41, v4
	v_mov_b32_e32 v42, v4
	v_mov_b32_e32 v43, v4
	v_mov_b32_e32 v52, v4
	v_mov_b32_e32 v53, v4
	v_mov_b32_e32 v54, v4
	v_mov_b32_e32 v55, v4
	v_mov_b32_e32 v56, v4
	v_mov_b32_e32 v57, v4
	v_mov_b32_e32 v58, v4
	v_mov_b32_e32 v59, v4
	v_mov_b32_e32 v12, v4
	v_mov_b32_e32 v13, v4
	v_mov_b32_e32 v14, v4
	v_mov_b32_e32 v15, v4
	v_mov_b32_e32 v16, v4
	v_mov_b32_e32 v17, v4
	v_mov_b32_e32 v18, v4
	v_mov_b32_e32 v19, v4
	v_mov_b32_e32 v28, v4
	v_mov_b32_e32 v29, v4
	v_mov_b32_e32 v30, v4
	v_mov_b32_e32 v31, v4
	v_mov_b32_e32 v32, v4
	v_mov_b32_e32 v33, v4
	v_mov_b32_e32 v34, v4
	v_mov_b32_e32 v35, v4
	v_mov_b32_e32 v44, v4
	v_mov_b32_e32 v45, v4
	v_mov_b32_e32 v46, v4
	v_mov_b32_e32 v47, v4
	v_mov_b32_e32 v48, v4
	v_mov_b32_e32 v49, v4
	v_mov_b32_e32 v50, v4
	v_mov_b32_e32 v51, v4
	v_mov_b32_e32 v60, v4
	v_mov_b32_e32 v61, v4
	v_mov_b32_e32 v62, v4
	v_mov_b32_e32 v63, v4
	v_mov_b32_e32 v64, v4
	v_mov_b32_e32 v65, v4
	v_mov_b32_e32 v66, v4
	v_mov_b32_e32 v67, v4
	v_mov_b32_e32 v68, v4
	v_mov_b32_e32 v69, v4
	v_mov_b32_e32 v70, v4
	v_mov_b32_e32 v71, v4
	v_mov_b32_e32 v72, v4
	v_mov_b32_e32 v73, v4
	v_mov_b32_e32 v74, v4
	v_mov_b32_e32 v75, v4
	v_mov_b32_e32 v84, v4
	v_mov_b32_e32 v85, v4
	v_mov_b32_e32 v86, v4
	v_mov_b32_e32 v87, v4
	v_mov_b32_e32 v88, v4
	v_mov_b32_e32 v89, v4
	v_mov_b32_e32 v90, v4
	v_mov_b32_e32 v91, v4
	v_mov_b32_e32 v100, v4
	v_mov_b32_e32 v101, v4
	v_mov_b32_e32 v102, v4
	v_mov_b32_e32 v103, v4
	v_mov_b32_e32 v104, v4
	v_mov_b32_e32 v105, v4
	v_mov_b32_e32 v106, v4
	v_mov_b32_e32 v107, v4
	v_mov_b32_e32 v116, v4
	v_mov_b32_e32 v117, v4
	v_mov_b32_e32 v118, v4
	v_mov_b32_e32 v119, v4
	v_mov_b32_e32 v120, v4
	v_mov_b32_e32 v121, v4
	v_mov_b32_e32 v122, v4
	v_mov_b32_e32 v123, v4
	v_mov_b32_e32 v76, v4
	v_mov_b32_e32 v77, v4
	v_mov_b32_e32 v78, v4
	v_mov_b32_e32 v79, v4
	v_mov_b32_e32 v80, v4
	v_mov_b32_e32 v81, v4
	v_mov_b32_e32 v82, v4
	v_mov_b32_e32 v83, v4
	v_mov_b32_e32 v92, v4
	v_mov_b32_e32 v93, v4
	v_mov_b32_e32 v94, v4
	v_mov_b32_e32 v95, v4
	v_mov_b32_e32 v96, v4
	v_mov_b32_e32 v97, v4
	v_mov_b32_e32 v98, v4
	v_mov_b32_e32 v99, v4
	v_mov_b32_e32 v108, v4
	v_mov_b32_e32 v109, v4
	v_mov_b32_e32 v110, v4
	v_mov_b32_e32 v111, v4
	v_mov_b32_e32 v112, v4
	v_mov_b32_e32 v113, v4
	v_mov_b32_e32 v114, v4
	v_mov_b32_e32 v115, v4
	v_mov_b32_e32 v124, v4
	v_mov_b32_e32 v125, v4
	v_mov_b32_e32 v126, v4
	v_mov_b32_e32 v127, v4
	v_mov_b32_e32 v128, v4
	v_mov_b32_e32 v129, v4
	v_mov_b32_e32 v130, v4
	v_mov_b32_e32 v131, v4
	v_lshl_add_u32 v142, s2, 8, v151
	v_ashrrev_i32_e32 v143, 31, v142
	v_lshl_add_u64 v[144:145], v[142:143], 2, s[40:41]
	global_load_dword v244, v[144:145], off
	global_load_dword v245, v[144:145], off offset:64
	global_load_dword v246, v[144:145], off offset:128
	global_load_dword v247, v[144:145], off offset:192
	global_load_dword v248, v[144:145], off offset:512
	global_load_dword v249, v[144:145], off offset:576
	global_load_dword v250, v[144:145], off offset:640
	global_load_dword v251, v[144:145], off offset:704
	s_cmp_lg_u64 s[12:13], 0
	s_cbranch_scc1 .Lsp_g198
	s_setprio 1
.Lsp_g198:
.LBB0_198:
	s_add_u32 s34, s26, 0xfff80080
	s_addc_u32 s35, s27, -1
	s_add_i32 s43, 0, 0x10000
	s_cmp_eq_u32 s33, 28
	s_cselect_b32 s37, s3, s35
	s_cselect_b32 s36, s10, s34
	s_cselect_b32 s35, s11, s29
	s_cselect_b32 s34, s21, s22
	s_add_i32 s66, 0, 0x14000
	v_add_u32_e32 v164, s43, v152
	v_add_u32_e32 v168, s66, v152
	ds_read_b128 v[142:145], v164
	ds_read_b128 v[146:149], v164 offset:1024
	ds_read_b128 v[160:163], v164 offset:2048
	ds_read_b128 v[164:167], v164 offset:3072
	ds_read_b128 v[178:181], v168
	ds_read_b128 v[182:185], v168 offset:1024
	ds_read_b128 v[186:189], v168 offset:2048
	ds_read_b128 v[190:193], v168 offset:3072
	v_lshl_add_u64 v[168:169], s[26:27], 0, v[138:139]
	s_add_i32 m0, s56, 0xc000
	ds_read_b128 v[194:197], v159
	ds_read_b128 v[208:211], v159 offset:1024
	ds_read_b128 v[212:215], v159 offset:2048
	ds_read_b128 v[216:219], v159 offset:3072
	ds_read_b128 v[220:223], v159 offset:4096
	ds_read_b128 v[224:227], v159 offset:5120
	ds_read_b128 v[228:231], v159 offset:6144
	ds_read_b128 v[232:235], v159 offset:7168
	global_load_lds_dwordx4 v[168:169], off
	v_lshl_add_u64 v[168:169], s[26:27], 0, v[140:141]
	s_add_i32 m0, s56, 0xe000
	s_nop 0
	global_load_lds_dwordx4 v[168:169], off
	s_waitcnt vmcnt(8)
	s_waitcnt lgkmcnt(0)
	s_barrier
	s_waitcnt lgkmcnt(0)
	v_mfma_f32_16x16x32_bf16 v[128:131], v[142:145], v[194:197], v[128:131]
	v_mfma_f32_16x16x32_bf16 v[128:131], v[146:149], v[208:211], v[128:131]
	v_mfma_f32_16x16x32_bf16 v[124:127], v[164:167], v[208:211], v[124:127]
	v_mfma_f32_16x16x32_bf16 v[124:127], v[160:163], v[194:197], v[124:127]
	v_mfma_f32_16x16x32_bf16 v[108:111], v[160:163], v[212:215], v[108:111]
	v_mfma_f32_16x16x32_bf16 v[108:111], v[164:167], v[216:219], v[108:111]
	v_mfma_f32_16x16x32_bf16 v[112:115], v[146:149], v[216:219], v[112:115]
	v_mfma_f32_16x16x32_bf16 v[112:115], v[142:145], v[212:215], v[112:115]
	v_mfma_f32_16x16x32_bf16 v[96:99], v[142:145], v[220:223], v[96:99]
	v_mfma_f32_16x16x32_bf16 v[96:99], v[146:149], v[224:227], v[96:99]
	v_mfma_f32_16x16x32_bf16 v[92:95], v[164:167], v[224:227], v[92:95]
	v_mfma_f32_16x16x32_bf16 v[92:95], v[160:163], v[220:223], v[92:95]
	v_mfma_f32_16x16x32_bf16 v[76:79], v[160:163], v[228:231], v[76:79]
	v_mfma_f32_16x16x32_bf16 v[76:79], v[164:167], v[232:235], v[76:79]
	v_mfma_f32_16x16x32_bf16 v[80:83], v[146:149], v[232:235], v[80:83]
	v_mfma_f32_16x16x32_bf16 v[80:83], v[142:145], v[228:231], v[80:83]
	v_mfma_f32_16x16x32_bf16 v[120:123], v[178:181], v[194:197], v[120:123]
	v_mfma_f32_16x16x32_bf16 v[120:123], v[182:185], v[208:211], v[120:123]
	v_mfma_f32_16x16x32_bf16 v[116:119], v[190:193], v[208:211], v[116:119]
	v_mfma_f32_16x16x32_bf16 v[116:119], v[186:189], v[194:197], v[116:119]
	v_mfma_f32_16x16x32_bf16 v[100:103], v[186:189], v[212:215], v[100:103]
	v_mfma_f32_16x16x32_bf16 v[100:103], v[190:193], v[216:219], v[100:103]
	v_mfma_f32_16x16x32_bf16 v[104:107], v[182:185], v[216:219], v[104:107]
	v_mfma_f32_16x16x32_bf16 v[104:107], v[178:181], v[212:215], v[104:107]
	v_mfma_f32_16x16x32_bf16 v[88:91], v[178:181], v[220:223], v[88:91]
	v_mfma_f32_16x16x32_bf16 v[88:91], v[182:185], v[224:227], v[88:91]
	v_mfma_f32_16x16x32_bf16 v[84:87], v[190:193], v[224:227], v[84:87]
	v_mfma_f32_16x16x32_bf16 v[84:87], v[186:189], v[220:223], v[84:87]
	v_mfma_f32_16x16x32_bf16 v[68:71], v[186:189], v[228:231], v[68:71]
	v_mfma_f32_16x16x32_bf16 v[68:71], v[190:193], v[232:235], v[68:71]
	v_mfma_f32_16x16x32_bf16 v[72:75], v[182:185], v[232:235], v[72:75]
	v_mfma_f32_16x16x32_bf16 v[72:75], v[178:181], v[228:231], v[72:75]
	s_barrier
	s_add_i32 s43, s43, s54
	v_lshl_add_u64 v[168:169], s[34:35], 0, v[2:3]
	s_mov_b32 m0, s43
	ds_read_b128 v[194:197], v159 offset:16384
	ds_read_b128 v[208:211], v159 offset:17408
	ds_read_b128 v[212:215], v159 offset:18432
	ds_read_b128 v[216:219], v159 offset:19456
	ds_read_b128 v[220:223], v159 offset:20480
	ds_read_b128 v[224:227], v159 offset:21504
	ds_read_b128 v[228:231], v159 offset:22528
	ds_read_b128 v[232:235], v159 offset:23552
	global_load_lds_dwordx4 v[168:169], off
	s_add_i32 m0, s43, 0x2000
	s_add_u32 s64, s34, 0x80000
	v_lshl_add_u64 v[236:237], s[34:35], 0, v[132:133]
	s_addc_u32 s65, s35, 0
	s_add_i32 s43, s66, s54
	global_load_lds_dwordx4 v[236:237], off
	v_lshl_add_u64 v[238:239], s[64:65], 0, v[2:3]
	s_mov_b32 m0, s43
	v_lshl_add_u64 v[240:241], s[36:37], 0, v[134:135]
	global_load_lds_dwordx4 v[238:239], off
	v_lshl_add_u64 v[238:239], s[64:65], 0, v[132:133]
	s_add_i32 m0, s43, 0x2000
	s_nop 0
	global_load_lds_dwordx4 v[238:239], off
	v_lshl_add_u64 v[238:239], s[36:37], 0, v[136:137]
	s_mov_b32 m0, s56
	s_nop 0
	global_load_lds_dwordx4 v[238:239], off
	s_mov_b32 m0, s57
	s_nop 0
	global_load_lds_dwordx4 v[240:241], off
	s_waitcnt vmcnt(8)
	s_waitcnt lgkmcnt(0)
	s_barrier
	s_waitcnt lgkmcnt(0)
	v_mfma_f32_16x16x32_bf16 v[64:67], v[142:145], v[194:197], v[64:67]
	v_mfma_f32_16x16x32_bf16 v[64:67], v[146:149], v[208:211], v[64:67]
	v_mfma_f32_16x16x32_bf16 v[60:63], v[164:167], v[208:211], v[60:63]
	v_mfma_f32_16x16x32_bf16 v[60:63], v[160:163], v[194:197], v[60:63]
	v_mfma_f32_16x16x32_bf16 v[44:47], v[160:163], v[212:215], v[44:47]
	v_mfma_f32_16x16x32_bf16 v[44:47], v[164:167], v[216:219], v[44:47]
	v_mfma_f32_16x16x32_bf16 v[48:51], v[146:149], v[216:219], v[48:51]
	v_mfma_f32_16x16x32_bf16 v[48:51], v[142:145], v[212:215], v[48:51]
	v_mfma_f32_16x16x32_bf16 v[32:35], v[142:145], v[220:223], v[32:35]
	v_mfma_f32_16x16x32_bf16 v[32:35], v[146:149], v[224:227], v[32:35]
	v_mfma_f32_16x16x32_bf16 v[28:31], v[164:167], v[224:227], v[28:31]
	v_mfma_f32_16x16x32_bf16 v[28:31], v[160:163], v[220:223], v[28:31]
	v_mfma_f32_16x16x32_bf16 v[12:15], v[160:163], v[228:231], v[12:15]
	v_mfma_f32_16x16x32_bf16 v[12:15], v[164:167], v[232:235], v[12:15]
	v_mfma_f32_16x16x32_bf16 v[16:19], v[146:149], v[232:235], v[16:19]
	v_mfma_f32_16x16x32_bf16 v[16:19], v[142:145], v[228:231], v[16:19]
	v_mfma_f32_16x16x32_bf16 v[56:59], v[178:181], v[194:197], v[56:59]
	v_mfma_f32_16x16x32_bf16 v[56:59], v[182:185], v[208:211], v[56:59]
	v_mfma_f32_16x16x32_bf16 v[52:55], v[190:193], v[208:211], v[52:55]
	v_mfma_f32_16x16x32_bf16 v[52:55], v[186:189], v[194:197], v[52:55]
	v_mfma_f32_16x16x32_bf16 v[36:39], v[186:189], v[212:215], v[36:39]
	v_mfma_f32_16x16x32_bf16 v[36:39], v[190:193], v[216:219], v[36:39]
	v_mfma_f32_16x16x32_bf16 v[40:43], v[182:185], v[216:219], v[40:43]
	v_mfma_f32_16x16x32_bf16 v[40:43], v[178:181], v[212:215], v[40:43]
	v_mfma_f32_16x16x32_bf16 v[24:27], v[178:181], v[220:223], v[24:27]
	v_mfma_f32_16x16x32_bf16 v[24:27], v[182:185], v[224:227], v[24:27]
	v_mfma_f32_16x16x32_bf16 v[20:23], v[190:193], v[224:227], v[20:23]
	v_mfma_f32_16x16x32_bf16 v[20:23], v[186:189], v[220:223], v[20:23]
	v_mfma_f32_16x16x32_bf16 v[4:7], v[186:189], v[228:231], v[4:7]
	v_mfma_f32_16x16x32_bf16 v[4:7], v[190:193], v[232:235], v[4:7]
	v_mfma_f32_16x16x32_bf16 v[8:11], v[182:185], v[232:235], v[8:11]
	v_mfma_f32_16x16x32_bf16 v[8:11], v[178:181], v[228:231], v[8:11]
	s_barrier
	s_add_i32 s43, 0, 0x18000
	s_add_i32 s64, 0, 0x1c000
	v_add_u32_e32 v164, s43, v152
	v_add_u32_e32 v190, s64, v152
	ds_read_b128 v[142:145], v164
	ds_read_b128 v[146:149], v164 offset:1024
	ds_read_b128 v[160:163], v164 offset:2048
	ds_read_b128 v[164:167], v164 offset:3072
	ds_read_b128 v[178:181], v190
	ds_read_b128 v[182:185], v190 offset:1024
	ds_read_b128 v[186:189], v190 offset:2048
	ds_read_b128 v[190:193], v190 offset:3072
	s_add_u32 s36, s36, 0x80000
	s_addc_u32 s37, s37, 0
	s_mov_b32 m0, s58
	v_lshl_add_u64 v[242:243], s[36:37], 0, v[136:137]
	ds_read_b128 v[194:197], v159 offset:32768
	ds_read_b128 v[208:211], v159 offset:33792
	ds_read_b128 v[212:215], v159 offset:34816
	ds_read_b128 v[216:219], v159 offset:35840
	ds_read_b128 v[220:223], v159 offset:36864
	ds_read_b128 v[224:227], v159 offset:37888
	ds_read_b128 v[228:231], v159 offset:38912
	ds_read_b128 v[232:235], v159 offset:39936
	global_load_lds_dwordx4 v[242:243], off
	v_lshl_add_u64 v[242:243], s[36:37], 0, v[134:135]
	s_mov_b32 m0, s59
	s_nop 0
	global_load_lds_dwordx4 v[242:243], off
	s_waitcnt vmcnt(8)
	s_waitcnt lgkmcnt(0)
	s_barrier
	s_waitcnt lgkmcnt(0)
	v_mfma_f32_16x16x32_bf16 v[128:131], v[142:145], v[194:197], v[128:131]
	v_mfma_f32_16x16x32_bf16 v[128:131], v[146:149], v[208:211], v[128:131]
	v_mfma_f32_16x16x32_bf16 v[124:127], v[164:167], v[208:211], v[124:127]
	v_mfma_f32_16x16x32_bf16 v[124:127], v[160:163], v[194:197], v[124:127]
	v_mfma_f32_16x16x32_bf16 v[108:111], v[160:163], v[212:215], v[108:111]
	v_mfma_f32_16x16x32_bf16 v[108:111], v[164:167], v[216:219], v[108:111]
	v_mfma_f32_16x16x32_bf16 v[112:115], v[146:149], v[216:219], v[112:115]
	v_mfma_f32_16x16x32_bf16 v[112:115], v[142:145], v[212:215], v[112:115]
	v_mfma_f32_16x16x32_bf16 v[96:99], v[142:145], v[220:223], v[96:99]
	v_mfma_f32_16x16x32_bf16 v[96:99], v[146:149], v[224:227], v[96:99]
	v_mfma_f32_16x16x32_bf16 v[92:95], v[164:167], v[224:227], v[92:95]
	v_mfma_f32_16x16x32_bf16 v[92:95], v[160:163], v[220:223], v[92:95]
	v_mfma_f32_16x16x32_bf16 v[76:79], v[160:163], v[228:231], v[76:79]
	v_mfma_f32_16x16x32_bf16 v[76:79], v[164:167], v[232:235], v[76:79]
	v_mfma_f32_16x16x32_bf16 v[80:83], v[146:149], v[232:235], v[80:83]
	v_mfma_f32_16x16x32_bf16 v[80:83], v[142:145], v[228:231], v[80:83]
	v_mfma_f32_16x16x32_bf16 v[120:123], v[178:181], v[194:197], v[120:123]
	v_mfma_f32_16x16x32_bf16 v[120:123], v[182:185], v[208:211], v[120:123]
	v_mfma_f32_16x16x32_bf16 v[116:119], v[190:193], v[208:211], v[116:119]
	v_mfma_f32_16x16x32_bf16 v[116:119], v[186:189], v[194:197], v[116:119]
	v_mfma_f32_16x16x32_bf16 v[100:103], v[186:189], v[212:215], v[100:103]
	v_mfma_f32_16x16x32_bf16 v[100:103], v[190:193], v[216:219], v[100:103]
	v_mfma_f32_16x16x32_bf16 v[104:107], v[182:185], v[216:219], v[104:107]
	v_mfma_f32_16x16x32_bf16 v[104:107], v[178:181], v[212:215], v[104:107]
	v_mfma_f32_16x16x32_bf16 v[88:91], v[178:181], v[220:223], v[88:91]
	v_mfma_f32_16x16x32_bf16 v[88:91], v[182:185], v[224:227], v[88:91]
	v_mfma_f32_16x16x32_bf16 v[84:87], v[190:193], v[224:227], v[84:87]
	v_mfma_f32_16x16x32_bf16 v[84:87], v[186:189], v[220:223], v[84:87]
	v_mfma_f32_16x16x32_bf16 v[68:71], v[186:189], v[228:231], v[68:71]
	v_mfma_f32_16x16x32_bf16 v[68:71], v[190:193], v[232:235], v[68:71]
	v_mfma_f32_16x16x32_bf16 v[72:75], v[182:185], v[232:235], v[72:75]
	v_mfma_f32_16x16x32_bf16 v[72:75], v[178:181], v[228:231], v[72:75]
	s_barrier
	s_add_i32 s36, s43, s54
	v_lshl_add_u64 v[168:169], v[168:169], 0, s[18:19]
	s_mov_b32 m0, s36
	ds_read_b128 v[194:197], v159 offset:49152
	ds_read_b128 v[208:211], v159 offset:50176
	ds_read_b128 v[212:215], v159 offset:51200
	ds_read_b128 v[216:219], v159 offset:52224
	ds_read_b128 v[220:223], v159 offset:53248
	ds_read_b128 v[224:227], v159 offset:54272
	ds_read_b128 v[228:231], v159 offset:55296
	ds_read_b128 v[232:235], v159 offset:56320
	global_load_lds_dwordx4 v[168:169], off
	s_add_i32 m0, s36, 0x2000
	s_add_u32 s34, s34, 0x80080
	v_lshl_add_u64 v[168:169], v[236:237], 0, s[18:19]
	s_addc_u32 s35, s35, 0
	s_add_i32 s36, s64, s54
	global_load_lds_dwordx4 v[168:169], off
	v_lshl_add_u64 v[168:169], s[34:35], 0, v[2:3]
	s_mov_b32 m0, s36
	s_nop 0
	global_load_lds_dwordx4 v[168:169], off
	v_lshl_add_u64 v[168:169], s[34:35], 0, v[132:133]
	s_add_i32 m0, s36, 0x2000
	s_nop 0
	global_load_lds_dwordx4 v[168:169], off
	v_lshl_add_u64 v[168:169], v[238:239], 0, s[18:19]
	s_mov_b32 m0, s60
	s_nop 0
	global_load_lds_dwordx4 v[168:169], off
	v_lshl_add_u64 v[168:169], v[240:241], 0, s[18:19]
	s_mov_b32 m0, s61
	s_nop 0
	global_load_lds_dwordx4 v[168:169], off
	s_waitcnt vmcnt(8)
	s_waitcnt lgkmcnt(0)
	s_barrier
	s_waitcnt lgkmcnt(0)
	v_mfma_f32_16x16x32_bf16 v[64:67], v[142:145], v[194:197], v[64:67]
	v_mfma_f32_16x16x32_bf16 v[64:67], v[146:149], v[208:211], v[64:67]
	v_mfma_f32_16x16x32_bf16 v[60:63], v[164:167], v[208:211], v[60:63]
	v_mfma_f32_16x16x32_bf16 v[60:63], v[160:163], v[194:197], v[60:63]
	v_mfma_f32_16x16x32_bf16 v[44:47], v[160:163], v[212:215], v[44:47]
	v_mfma_f32_16x16x32_bf16 v[44:47], v[164:167], v[216:219], v[44:47]
	v_mfma_f32_16x16x32_bf16 v[48:51], v[146:149], v[216:219], v[48:51]
	v_mfma_f32_16x16x32_bf16 v[48:51], v[142:145], v[212:215], v[48:51]
	v_mfma_f32_16x16x32_bf16 v[32:35], v[142:145], v[220:223], v[32:35]
	v_mfma_f32_16x16x32_bf16 v[32:35], v[146:149], v[224:227], v[32:35]
	v_mfma_f32_16x16x32_bf16 v[28:31], v[164:167], v[224:227], v[28:31]
	v_mfma_f32_16x16x32_bf16 v[28:31], v[160:163], v[220:223], v[28:31]
	v_mfma_f32_16x16x32_bf16 v[12:15], v[160:163], v[228:231], v[12:15]
	v_mfma_f32_16x16x32_bf16 v[12:15], v[164:167], v[232:235], v[12:15]
	v_mfma_f32_16x16x32_bf16 v[16:19], v[146:149], v[232:235], v[16:19]
	v_mfma_f32_16x16x32_bf16 v[16:19], v[142:145], v[228:231], v[16:19]
	v_mfma_f32_16x16x32_bf16 v[56:59], v[178:181], v[194:197], v[56:59]
	v_mfma_f32_16x16x32_bf16 v[56:59], v[182:185], v[208:211], v[56:59]
	v_mfma_f32_16x16x32_bf16 v[52:55], v[190:193], v[208:211], v[52:55]
	v_mfma_f32_16x16x32_bf16 v[52:55], v[186:189], v[194:197], v[52:55]
	v_mfma_f32_16x16x32_bf16 v[36:39], v[186:189], v[212:215], v[36:39]
	v_mfma_f32_16x16x32_bf16 v[36:39], v[190:193], v[216:219], v[36:39]
	v_mfma_f32_16x16x32_bf16 v[40:43], v[182:185], v[216:219], v[40:43]
	v_mfma_f32_16x16x32_bf16 v[40:43], v[178:181], v[212:215], v[40:43]
	v_mfma_f32_16x16x32_bf16 v[24:27], v[178:181], v[220:223], v[24:27]
	v_mfma_f32_16x16x32_bf16 v[24:27], v[182:185], v[224:227], v[24:27]
	v_mfma_f32_16x16x32_bf16 v[20:23], v[190:193], v[224:227], v[20:23]
	v_mfma_f32_16x16x32_bf16 v[20:23], v[186:189], v[220:223], v[20:23]
	v_mfma_f32_16x16x32_bf16 v[4:7], v[186:189], v[228:231], v[4:7]
	v_mfma_f32_16x16x32_bf16 v[4:7], v[190:193], v[232:235], v[4:7]
	v_mfma_f32_16x16x32_bf16 v[8:11], v[182:185], v[232:235], v[8:11]
	v_mfma_f32_16x16x32_bf16 v[8:11], v[178:181], v[228:231], v[8:11]
	s_barrier
	s_add_i32 s33, s33, 2
	s_add_u32 s26, s26, 0x100
	s_addc_u32 s27, s27, 0
	s_add_u32 s22, s22, 0x100
	s_addc_u32 s29, s29, 0
	s_cmp_gt_u32 s33, 29
	s_cbranch_scc0 .LBB0_198
	s_setprio 0
	s_and_b64 vcc, exec, s[12:13]
	s_cbranch_vccz .LBB0_201
	s_barrier

.LBB0_707:
	s_ashr_i32 s27, s26, 31
	s_lshl_b64 s[34:35], s[26:27], 20
	s_add_u32 s34, s59, s34
	s_addc_u32 s35, s60, s35
	s_and_b64 s[36:37], s[38:39], exec
	s_cselect_b32 s27, s35, s41
	s_cselect_b32 s51, s34, s40
	s_ashr_i32 s13, s12, 31
	s_lshl_b64 s[36:37], s[12:13], 20
	s_add_u32 s36, s1, s36
	s_addc_u32 s37, s7, s37
	s_and_b64 s[44:45], s[38:39], exec
	s_cselect_b32 s13, s37, s43
	s_cselect_b32 s52, s36, s42
	s_add_u32 s40, s40, 0x80080
	s_addc_u32 s41, s41, 0
	s_add_u32 s53, s42, 0x100
	v_mov_b32_e32 v4, 0
	s_addc_u32 s54, s43, 0
	s_mov_b32 s55, -2
	v_mov_b32_e32 v5, v4
	v_mov_b32_e32 v6, v4
	v_mov_b32_e32 v7, v4
	v_mov_b32_e32 v8, v4
	v_mov_b32_e32 v9, v4
	v_mov_b32_e32 v10, v4
	v_mov_b32_e32 v11, v4
	v_mov_b32_e32 v12, v4
	v_mov_b32_e32 v13, v4
	v_mov_b32_e32 v14, v4
	v_mov_b32_e32 v15, v4
	v_mov_b32_e32 v20, v4
	v_mov_b32_e32 v21, v4
	v_mov_b32_e32 v22, v4
	v_mov_b32_e32 v23, v4
	v_mov_b32_e32 v28, v4
	v_mov_b32_e32 v29, v4
	v_mov_b32_e32 v30, v4
	v_mov_b32_e32 v31, v4
	v_mov_b32_e32 v36, v4
	v_mov_b32_e32 v37, v4
	v_mov_b32_e32 v38, v4
	v_mov_b32_e32 v39, v4
	v_mov_b32_e32 v44, v4
	v_mov_b32_e32 v45, v4
	v_mov_b32_e32 v46, v4
	v_mov_b32_e32 v47, v4
	v_mov_b32_e32 v52, v4
	v_mov_b32_e32 v53, v4
	v_mov_b32_e32 v54, v4
	v_mov_b32_e32 v55, v4
	v_mov_b32_e32 v16, v4
	v_mov_b32_e32 v17, v4
	v_mov_b32_e32 v18, v4
	v_mov_b32_e32 v19, v4
	v_mov_b32_e32 v24, v4
	v_mov_b32_e32 v25, v4
	v_mov_b32_e32 v26, v4
	v_mov_b32_e32 v27, v4
	v_mov_b32_e32 v32, v4
	v_mov_b32_e32 v33, v4
	v_mov_b32_e32 v34, v4
	v_mov_b32_e32 v35, v4
	v_mov_b32_e32 v40, v4
	v_mov_b32_e32 v41, v4
	v_mov_b32_e32 v42, v4
	v_mov_b32_e32 v43, v4
	v_mov_b32_e32 v48, v4
	v_mov_b32_e32 v49, v4
	v_mov_b32_e32 v50, v4
	v_mov_b32_e32 v51, v4
	v_mov_b32_e32 v56, v4
	v_mov_b32_e32 v57, v4
	v_mov_b32_e32 v58, v4
	v_mov_b32_e32 v59, v4
	v_mov_b32_e32 v60, v4
	v_mov_b32_e32 v61, v4
	v_mov_b32_e32 v62, v4
	v_mov_b32_e32 v63, v4
	v_mov_b32_e32 v64, v4
	v_mov_b32_e32 v65, v4
	v_mov_b32_e32 v66, v4
	v_mov_b32_e32 v67, v4
	v_mov_b32_e32 v68, v4
	v_mov_b32_e32 v69, v4
	v_mov_b32_e32 v70, v4
	v_mov_b32_e32 v71, v4
	v_mov_b32_e32 v72, v4
	v_mov_b32_e32 v73, v4
	v_mov_b32_e32 v74, v4
	v_mov_b32_e32 v75, v4
	v_mov_b32_e32 v76, v4
	v_mov_b32_e32 v77, v4
	v_mov_b32_e32 v78, v4
	v_mov_b32_e32 v79, v4
	v_mov_b32_e32 v84, v4
	v_mov_b32_e32 v85, v4
	v_mov_b32_e32 v86, v4
	v_mov_b32_e32 v87, v4
	v_mov_b32_e32 v92, v4
	v_mov_b32_e32 v93, v4
	v_mov_b32_e32 v94, v4
	v_mov_b32_e32 v95, v4
	v_mov_b32_e32 v100, v4
	v_mov_b32_e32 v101, v4
	v_mov_b32_e32 v102, v4
	v_mov_b32_e32 v103, v4
	v_mov_b32_e32 v108, v4
	v_mov_b32_e32 v109, v4
	v_mov_b32_e32 v110, v4
	v_mov_b32_e32 v111, v4
	v_mov_b32_e32 v116, v4
	v_mov_b32_e32 v117, v4
	v_mov_b32_e32 v118, v4
	v_mov_b32_e32 v119, v4
	v_mov_b32_e32 v80, v4
	v_mov_b32_e32 v81, v4
	v_mov_b32_e32 v82, v4
	v_mov_b32_e32 v83, v4
	v_mov_b32_e32 v88, v4
	v_mov_b32_e32 v89, v4
	v_mov_b32_e32 v90, v4
	v_mov_b32_e32 v91, v4
	v_mov_b32_e32 v96, v4
	v_mov_b32_e32 v97, v4
	v_mov_b32_e32 v98, v4
	v_mov_b32_e32 v99, v4
	v_mov_b32_e32 v104, v4
	v_mov_b32_e32 v105, v4
	v_mov_b32_e32 v106, v4
	v_mov_b32_e32 v107, v4
	v_mov_b32_e32 v112, v4
	v_mov_b32_e32 v113, v4
	v_mov_b32_e32 v114, v4
	v_mov_b32_e32 v115, v4
	v_mov_b32_e32 v120, v4
	v_mov_b32_e32 v121, v4
	v_mov_b32_e32 v122, v4
	v_mov_b32_e32 v123, v4
	v_mov_b32_e32 v124, v4
	v_mov_b32_e32 v125, v4
	v_mov_b32_e32 v126, v4
	v_mov_b32_e32 v127, v4
	v_mov_b32_e32 v128, v4
	v_mov_b32_e32 v129, v4
	v_mov_b32_e32 v130, v4
	v_mov_b32_e32 v131, v4
	s_cmp_lg_u64 s[8:9], 0
	s_cbranch_scc1 .Lsp_g708
	s_setprio 1
.Lsp_g708:
.LBB0_708:
	s_add_u32 s42, s40, 0xfff80080
	s_addc_u32 s43, s41, -1
	s_add_i32 s61, 0, 0x10000
	s_cmp_eq_u32 s55, 28
	s_cselect_b32 s45, s27, s43
	s_cselect_b32 s44, s51, s42
	v_add_u32_e32 v142, s61, v144
	s_cselect_b32 s43, s13, s54
	s_cselect_b32 s42, s52, s53
	s_add_i32 s65, 0, 0x14000
	ds_read_b128 v[148:151], v142
	ds_read_b128 v[152:155], v142 offset:1024
	ds_read_b128 v[156:159], v142 offset:2048
	ds_read_b128 v[160:163], v142 offset:3072
	v_add_u32_e32 v142, s65, v144
	ds_read_b128 v[164:167], v142
	ds_read_b128 v[178:181], v142 offset:1024
	ds_read_b128 v[182:185], v142 offset:2048
	ds_read_b128 v[186:189], v142 offset:3072
	v_lshl_add_u64 v[142:143], s[40:41], 0, v[138:139]
	s_add_i32 m0, s21, 0xc000
	ds_read_b128 v[190:193], v146
	ds_read_b128 v[194:197], v146 offset:1024
	ds_read_b128 v[208:211], v146 offset:2048
	ds_read_b128 v[212:215], v146 offset:3072
	ds_read_b128 v[216:219], v146 offset:4096
	ds_read_b128 v[220:223], v146 offset:5120
	ds_read_b128 v[224:227], v146 offset:6144
	ds_read_b128 v[228:231], v146 offset:7168
	global_load_lds_dwordx4 v[142:143], off
	v_lshl_add_u64 v[142:143], s[40:41], 0, v[140:141]
	s_add_i32 m0, s21, 0xe000
	s_nop 0
	global_load_lds_dwordx4 v[142:143], off
	s_waitcnt vmcnt(8)
	s_waitcnt lgkmcnt(0)
	s_barrier
	s_waitcnt lgkmcnt(0)
	v_mfma_f32_16x16x32_bf16 v[128:131], v[148:151], v[190:193], v[128:131]
	v_mfma_f32_16x16x32_bf16 v[128:131], v[152:155], v[194:197], v[128:131]
	v_mfma_f32_16x16x32_bf16 v[124:127], v[160:163], v[194:197], v[124:127]
	v_mfma_f32_16x16x32_bf16 v[124:127], v[156:159], v[190:193], v[124:127]
	v_mfma_f32_16x16x32_bf16 v[112:115], v[156:159], v[208:211], v[112:115]
	v_mfma_f32_16x16x32_bf16 v[112:115], v[160:163], v[212:215], v[112:115]
	v_mfma_f32_16x16x32_bf16 v[120:123], v[152:155], v[212:215], v[120:123]
	v_mfma_f32_16x16x32_bf16 v[120:123], v[148:151], v[208:211], v[120:123]
	v_mfma_f32_16x16x32_bf16 v[104:107], v[148:151], v[216:219], v[104:107]
	v_mfma_f32_16x16x32_bf16 v[104:107], v[152:155], v[220:223], v[104:107]
	v_mfma_f32_16x16x32_bf16 v[96:99], v[160:163], v[220:223], v[96:99]
	v_mfma_f32_16x16x32_bf16 v[96:99], v[156:159], v[216:219], v[96:99]
	v_mfma_f32_16x16x32_bf16 v[80:83], v[156:159], v[224:227], v[80:83]
	v_mfma_f32_16x16x32_bf16 v[80:83], v[160:163], v[228:231], v[80:83]
	v_mfma_f32_16x16x32_bf16 v[88:91], v[152:155], v[228:231], v[88:91]
	v_mfma_f32_16x16x32_bf16 v[88:91], v[148:151], v[224:227], v[88:91]
	v_mfma_f32_16x16x32_bf16 v[116:119], v[164:167], v[190:193], v[116:119]
	v_mfma_f32_16x16x32_bf16 v[116:119], v[178:181], v[194:197], v[116:119]
	v_mfma_f32_16x16x32_bf16 v[108:111], v[186:189], v[194:197], v[108:111]
	v_mfma_f32_16x16x32_bf16 v[108:111], v[182:185], v[190:193], v[108:111]
	v_mfma_f32_16x16x32_bf16 v[92:95], v[182:185], v[208:211], v[92:95]
	v_mfma_f32_16x16x32_bf16 v[92:95], v[186:189], v[212:215], v[92:95]
	v_mfma_f32_16x16x32_bf16 v[100:103], v[178:181], v[212:215], v[100:103]
	v_mfma_f32_16x16x32_bf16 v[100:103], v[164:167], v[208:211], v[100:103]
	v_mfma_f32_16x16x32_bf16 v[84:87], v[164:167], v[216:219], v[84:87]
	v_mfma_f32_16x16x32_bf16 v[84:87], v[178:181], v[220:223], v[84:87]
	v_mfma_f32_16x16x32_bf16 v[76:79], v[186:189], v[220:223], v[76:79]
	v_mfma_f32_16x16x32_bf16 v[76:79], v[182:185], v[216:219], v[76:79]
	v_mfma_f32_16x16x32_bf16 v[68:71], v[182:185], v[224:227], v[68:71]
	v_mfma_f32_16x16x32_bf16 v[68:71], v[186:189], v[228:231], v[68:71]
	v_mfma_f32_16x16x32_bf16 v[72:75], v[178:181], v[228:231], v[72:75]
	v_mfma_f32_16x16x32_bf16 v[72:75], v[164:167], v[224:227], v[72:75]
	s_barrier
	s_add_i32 s61, s61, s11
	v_lshl_add_u64 v[142:143], s[42:43], 0, v[2:3]
	s_mov_b32 m0, s61
	ds_read_b128 v[190:193], v146 offset:16384
	ds_read_b128 v[194:197], v146 offset:17408
	ds_read_b128 v[208:211], v146 offset:18432
	ds_read_b128 v[212:215], v146 offset:19456
	ds_read_b128 v[216:219], v146 offset:20480
	ds_read_b128 v[220:223], v146 offset:21504
	ds_read_b128 v[224:227], v146 offset:22528
	ds_read_b128 v[228:231], v146 offset:23552
	global_load_lds_dwordx4 v[142:143], off
	s_add_i32 m0, s61, 0x2000
	s_add_u32 s62, s42, 0x80000
	v_lshl_add_u64 v[168:169], s[42:43], 0, v[136:137]
	s_addc_u32 s63, s43, 0
	s_add_i32 s61, s65, s11
	global_load_lds_dwordx4 v[168:169], off
	v_lshl_add_u64 v[232:233], s[62:63], 0, v[2:3]
	s_mov_b32 m0, s61
	v_lshl_add_u64 v[234:235], s[44:45], 0, v[134:135]
	global_load_lds_dwordx4 v[232:233], off
	v_lshl_add_u64 v[232:233], s[62:63], 0, v[136:137]
	s_add_i32 m0, s61, 0x2000
	s_nop 0
	global_load_lds_dwordx4 v[232:233], off
	v_lshl_add_u64 v[232:233], s[44:45], 0, v[132:133]
	s_mov_b32 m0, s21
	s_nop 0
	global_load_lds_dwordx4 v[232:233], off
	s_mov_b32 m0, s22
	s_nop 0
	global_load_lds_dwordx4 v[234:235], off
	s_waitcnt vmcnt(8)
	s_waitcnt lgkmcnt(0)
	s_barrier
	s_waitcnt lgkmcnt(0)
	v_mfma_f32_16x16x32_bf16 v[64:67], v[148:151], v[190:193], v[64:67]
	v_mfma_f32_16x16x32_bf16 v[64:67], v[152:155], v[194:197], v[64:67]
	v_mfma_f32_16x16x32_bf16 v[60:63], v[160:163], v[194:197], v[60:63]
	v_mfma_f32_16x16x32_bf16 v[60:63], v[156:159], v[190:193], v[60:63]
	v_mfma_f32_16x16x32_bf16 v[48:51], v[156:159], v[208:211], v[48:51]
	v_mfma_f32_16x16x32_bf16 v[48:51], v[160:163], v[212:215], v[48:51]
	v_mfma_f32_16x16x32_bf16 v[56:59], v[152:155], v[212:215], v[56:59]
	v_mfma_f32_16x16x32_bf16 v[56:59], v[148:151], v[208:211], v[56:59]
	v_mfma_f32_16x16x32_bf16 v[40:43], v[148:151], v[216:219], v[40:43]
	v_mfma_f32_16x16x32_bf16 v[40:43], v[152:155], v[220:223], v[40:43]
	v_mfma_f32_16x16x32_bf16 v[32:35], v[160:163], v[220:223], v[32:35]
	v_mfma_f32_16x16x32_bf16 v[32:35], v[156:159], v[216:219], v[32:35]
	v_mfma_f32_16x16x32_bf16 v[16:19], v[156:159], v[224:227], v[16:19]
	v_mfma_f32_16x16x32_bf16 v[16:19], v[160:163], v[228:231], v[16:19]
	v_mfma_f32_16x16x32_bf16 v[24:27], v[152:155], v[228:231], v[24:27]
	v_mfma_f32_16x16x32_bf16 v[24:27], v[148:151], v[224:227], v[24:27]
	v_mfma_f32_16x16x32_bf16 v[52:55], v[164:167], v[190:193], v[52:55]
	v_mfma_f32_16x16x32_bf16 v[52:55], v[178:181], v[194:197], v[52:55]
	v_mfma_f32_16x16x32_bf16 v[44:47], v[186:189], v[194:197], v[44:47]
	v_mfma_f32_16x16x32_bf16 v[44:47], v[182:185], v[190:193], v[44:47]
	v_mfma_f32_16x16x32_bf16 v[28:31], v[182:185], v[208:211], v[28:31]
	v_mfma_f32_16x16x32_bf16 v[28:31], v[186:189], v[212:215], v[28:31]
	v_mfma_f32_16x16x32_bf16 v[36:39], v[178:181], v[212:215], v[36:39]
	v_mfma_f32_16x16x32_bf16 v[36:39], v[164:167], v[208:211], v[36:39]
	v_mfma_f32_16x16x32_bf16 v[20:23], v[164:167], v[216:219], v[20:23]
	v_mfma_f32_16x16x32_bf16 v[20:23], v[178:181], v[220:223], v[20:23]
	v_mfma_f32_16x16x32_bf16 v[12:15], v[186:189], v[220:223], v[12:15]
	v_mfma_f32_16x16x32_bf16 v[12:15], v[182:185], v[216:219], v[12:15]
	v_mfma_f32_16x16x32_bf16 v[4:7], v[182:185], v[224:227], v[4:7]
	v_mfma_f32_16x16x32_bf16 v[4:7], v[186:189], v[228:231], v[4:7]
	v_mfma_f32_16x16x32_bf16 v[8:11], v[178:181], v[228:231], v[8:11]
	v_mfma_f32_16x16x32_bf16 v[8:11], v[164:167], v[224:227], v[8:11]
	s_barrier
	s_add_i32 s61, 0, 0x18000
	v_add_u32_e32 v147, s61, v144
	s_add_i32 s62, 0, 0x1c000
	ds_read_b128 v[148:151], v147
	ds_read_b128 v[152:155], v147 offset:1024
	ds_read_b128 v[156:159], v147 offset:2048
	ds_read_b128 v[160:163], v147 offset:3072
	v_add_u32_e32 v147, s62, v144
	ds_read_b128 v[164:167], v147
	ds_read_b128 v[178:181], v147 offset:1024
	ds_read_b128 v[182:185], v147 offset:2048
	ds_read_b128 v[186:189], v147 offset:3072
	s_add_u32 s44, s44, 0x80000
	s_addc_u32 s45, s45, 0
	s_mov_b32 m0, s33
	v_lshl_add_u64 v[236:237], s[44:45], 0, v[132:133]
	ds_read_b128 v[190:193], v146 offset:32768
	ds_read_b128 v[194:197], v146 offset:33792
	ds_read_b128 v[208:211], v146 offset:34816
	ds_read_b128 v[212:215], v146 offset:35840
	ds_read_b128 v[216:219], v146 offset:36864
	ds_read_b128 v[220:223], v146 offset:37888
	ds_read_b128 v[224:227], v146 offset:38912
	ds_read_b128 v[228:231], v146 offset:39936
	global_load_lds_dwordx4 v[236:237], off
	v_lshl_add_u64 v[236:237], s[44:45], 0, v[134:135]
	s_mov_b32 m0, s46
	s_nop 0
	global_load_lds_dwordx4 v[236:237], off
	s_waitcnt vmcnt(8)
	s_waitcnt lgkmcnt(0)
	s_barrier
	s_waitcnt lgkmcnt(0)
	v_mfma_f32_16x16x32_bf16 v[128:131], v[148:151], v[190:193], v[128:131]
	v_mfma_f32_16x16x32_bf16 v[128:131], v[152:155], v[194:197], v[128:131]
	v_mfma_f32_16x16x32_bf16 v[124:127], v[160:163], v[194:197], v[124:127]
	v_mfma_f32_16x16x32_bf16 v[124:127], v[156:159], v[190:193], v[124:127]
	v_mfma_f32_16x16x32_bf16 v[112:115], v[156:159], v[208:211], v[112:115]
	v_mfma_f32_16x16x32_bf16 v[112:115], v[160:163], v[212:215], v[112:115]
	v_mfma_f32_16x16x32_bf16 v[120:123], v[152:155], v[212:215], v[120:123]
	v_mfma_f32_16x16x32_bf16 v[120:123], v[148:151], v[208:211], v[120:123]
	v_mfma_f32_16x16x32_bf16 v[104:107], v[148:151], v[216:219], v[104:107]
	v_mfma_f32_16x16x32_bf16 v[104:107], v[152:155], v[220:223], v[104:107]
	v_mfma_f32_16x16x32_bf16 v[96:99], v[160:163], v[220:223], v[96:99]
	v_mfma_f32_16x16x32_bf16 v[96:99], v[156:159], v[216:219], v[96:99]
	v_mfma_f32_16x16x32_bf16 v[80:83], v[156:159], v[224:227], v[80:83]
	v_mfma_f32_16x16x32_bf16 v[80:83], v[160:163], v[228:231], v[80:83]
	v_mfma_f32_16x16x32_bf16 v[88:91], v[152:155], v[228:231], v[88:91]
	v_mfma_f32_16x16x32_bf16 v[88:91], v[148:151], v[224:227], v[88:91]
	v_mfma_f32_16x16x32_bf16 v[116:119], v[164:167], v[190:193], v[116:119]
	v_mfma_f32_16x16x32_bf16 v[116:119], v[178:181], v[194:197], v[116:119]
	v_mfma_f32_16x16x32_bf16 v[108:111], v[186:189], v[194:197], v[108:111]
	v_mfma_f32_16x16x32_bf16 v[108:111], v[182:185], v[190:193], v[108:111]
	v_mfma_f32_16x16x32_bf16 v[92:95], v[182:185], v[208:211], v[92:95]
	v_mfma_f32_16x16x32_bf16 v[92:95], v[186:189], v[212:215], v[92:95]
	v_mfma_f32_16x16x32_bf16 v[100:103], v[178:181], v[212:215], v[100:103]
	v_mfma_f32_16x16x32_bf16 v[100:103], v[164:167], v[208:211], v[100:103]
	v_mfma_f32_16x16x32_bf16 v[84:87], v[164:167], v[216:219], v[84:87]
	v_mfma_f32_16x16x32_bf16 v[84:87], v[178:181], v[220:223], v[84:87]
	v_mfma_f32_16x16x32_bf16 v[76:79], v[186:189], v[220:223], v[76:79]
	v_mfma_f32_16x16x32_bf16 v[76:79], v[182:185], v[216:219], v[76:79]
	v_mfma_f32_16x16x32_bf16 v[68:71], v[182:185], v[224:227], v[68:71]
	v_mfma_f32_16x16x32_bf16 v[68:71], v[186:189], v[228:231], v[68:71]
	v_mfma_f32_16x16x32_bf16 v[72:75], v[178:181], v[228:231], v[72:75]
	v_mfma_f32_16x16x32_bf16 v[72:75], v[164:167], v[224:227], v[72:75]
	s_barrier
	s_add_i32 s44, s61, s11
	v_lshl_add_u64 v[142:143], v[142:143], 0, s[18:19]
	s_mov_b32 m0, s44
	ds_read_b128 v[190:193], v146 offset:49152
	ds_read_b128 v[194:197], v146 offset:50176
	ds_read_b128 v[208:211], v146 offset:51200
	ds_read_b128 v[212:215], v146 offset:52224
	ds_read_b128 v[216:219], v146 offset:53248
	ds_read_b128 v[220:223], v146 offset:54272
	ds_read_b128 v[224:227], v146 offset:55296
	ds_read_b128 v[228:231], v146 offset:56320
	global_load_lds_dwordx4 v[142:143], off
	s_add_i32 m0, s44, 0x2000
	s_add_u32 s42, s42, 0x80080
	v_lshl_add_u64 v[142:143], v[168:169], 0, s[18:19]
	s_addc_u32 s43, s43, 0
	s_add_i32 s44, s62, s11
	global_load_lds_dwordx4 v[142:143], off
	v_lshl_add_u64 v[142:143], s[42:43], 0, v[2:3]
	s_mov_b32 m0, s44
	s_nop 0
	global_load_lds_dwordx4 v[142:143], off
	v_lshl_add_u64 v[142:143], s[42:43], 0, v[136:137]
	s_add_i32 m0, s44, 0x2000
	s_nop 0
	global_load_lds_dwordx4 v[142:143], off
	v_lshl_add_u64 v[142:143], v[232:233], 0, s[18:19]
	s_mov_b32 m0, s47
	s_nop 0
	global_load_lds_dwordx4 v[142:143], off
	v_lshl_add_u64 v[142:143], v[234:235], 0, s[18:19]
	s_mov_b32 m0, s48
	s_nop 0
	global_load_lds_dwordx4 v[142:143], off
	s_waitcnt vmcnt(8)
	s_waitcnt lgkmcnt(0)
	s_barrier
	s_waitcnt lgkmcnt(0)
	v_mfma_f32_16x16x32_bf16 v[64:67], v[148:151], v[190:193], v[64:67]
	v_mfma_f32_16x16x32_bf16 v[64:67], v[152:155], v[194:197], v[64:67]
	v_mfma_f32_16x16x32_bf16 v[60:63], v[160:163], v[194:197], v[60:63]
	v_mfma_f32_16x16x32_bf16 v[60:63], v[156:159], v[190:193], v[60:63]
	v_mfma_f32_16x16x32_bf16 v[48:51], v[156:159], v[208:211], v[48:51]
	v_mfma_f32_16x16x32_bf16 v[48:51], v[160:163], v[212:215], v[48:51]
	v_mfma_f32_16x16x32_bf16 v[56:59], v[152:155], v[212:215], v[56:59]
	v_mfma_f32_16x16x32_bf16 v[56:59], v[148:151], v[208:211], v[56:59]
	v_mfma_f32_16x16x32_bf16 v[40:43], v[148:151], v[216:219], v[40:43]
	v_mfma_f32_16x16x32_bf16 v[40:43], v[152:155], v[220:223], v[40:43]
	v_mfma_f32_16x16x32_bf16 v[32:35], v[160:163], v[220:223], v[32:35]
	v_mfma_f32_16x16x32_bf16 v[32:35], v[156:159], v[216:219], v[32:35]
	v_mfma_f32_16x16x32_bf16 v[16:19], v[156:159], v[224:227], v[16:19]
	v_mfma_f32_16x16x32_bf16 v[16:19], v[160:163], v[228:231], v[16:19]
	v_mfma_f32_16x16x32_bf16 v[24:27], v[152:155], v[228:231], v[24:27]
	v_mfma_f32_16x16x32_bf16 v[24:27], v[148:151], v[224:227], v[24:27]
	v_mfma_f32_16x16x32_bf16 v[52:55], v[164:167], v[190:193], v[52:55]
	v_mfma_f32_16x16x32_bf16 v[52:55], v[178:181], v[194:197], v[52:55]
	v_mfma_f32_16x16x32_bf16 v[44:47], v[186:189], v[194:197], v[44:47]
	v_mfma_f32_16x16x32_bf16 v[44:47], v[182:185], v[190:193], v[44:47]
	v_mfma_f32_16x16x32_bf16 v[28:31], v[182:185], v[208:211], v[28:31]
	v_mfma_f32_16x16x32_bf16 v[28:31], v[186:189], v[212:215], v[28:31]
	v_mfma_f32_16x16x32_bf16 v[36:39], v[178:181], v[212:215], v[36:39]
	v_mfma_f32_16x16x32_bf16 v[36:39], v[164:167], v[208:211], v[36:39]
	v_mfma_f32_16x16x32_bf16 v[20:23], v[164:167], v[216:219], v[20:23]
	v_mfma_f32_16x16x32_bf16 v[20:23], v[178:181], v[220:223], v[20:23]
	v_mfma_f32_16x16x32_bf16 v[12:15], v[186:189], v[220:223], v[12:15]
	v_mfma_f32_16x16x32_bf16 v[12:15], v[182:185], v[216:219], v[12:15]
	v_mfma_f32_16x16x32_bf16 v[4:7], v[182:185], v[224:227], v[4:7]
	v_mfma_f32_16x16x32_bf16 v[4:7], v[186:189], v[228:231], v[4:7]
	v_mfma_f32_16x16x32_bf16 v[8:11], v[178:181], v[228:231], v[8:11]
	v_mfma_f32_16x16x32_bf16 v[8:11], v[164:167], v[224:227], v[8:11]
	s_barrier
	s_add_i32 s55, s55, 2
	s_add_u32 s40, s40, 0x100
	s_addc_u32 s41, s41, 0
	s_add_u32 s53, s53, 0x100
	s_addc_u32 s54, s54, 0
	s_cmp_gt_u32 s55, 29
	s_cbranch_scc0 .LBB0_708
	s_setprio 0
	s_and_b64 vcc, exec, s[8:9]
	s_cbranch_vccz .LBB0_711
	s_barrier

.LBB0_721:
	s_add_i32 s67, s67, 1
	s_mov_b32 s69, s4
	s_mul_i32 s4, s67, s24
	s_add_i32 s4, s4, s23
	s_cmpk_lt_i32 s4, 0x100
	s_mov_b32 s68, s22
	s_cselect_b64 s[36:37], -1, 0
	s_bfe_u32 s22, s4, 0x30003
	s_ashr_i32 s4, s4, 6
	s_ashr_i32 s5, s4, 31
	s_mov_b64 s[40:41], s[8:9]
	s_lshl_b64 s[8:9], s[4:5], 20
	s_mov_b64 s[38:39], s[12:13]
	s_add_u32 s12, s10, s8
	s_addc_u32 s13, s11, s9
	s_and_b64 s[8:9], s[36:37], exec
	s_cselect_b32 s5, s13, s39
	s_cselect_b32 s70, s12, s38
	s_lshl_b32 s8, s22, 20
	s_add_u32 s8, s1, s8
	s_addc_u32 s9, s7, 0
	s_and_b64 s[42:43], s[36:37], exec
	v_mov_b32_e32 v4, 0
	s_cselect_b32 s71, s9, s41
	s_cselect_b32 s72, s8, s40
	s_mov_b64 s[42:43], -1
	s_mov_b64 s[44:45], 0
	s_mov_b32 s46, 0
	v_mov_b32_e32 v5, v4
	v_mov_b32_e32 v6, v4
	v_mov_b32_e32 v7, v4
	v_mov_b32_e32 v8, v4
	v_mov_b32_e32 v9, v4
	v_mov_b32_e32 v10, v4
	v_mov_b32_e32 v11, v4
	v_mov_b32_e32 v12, v4
	v_mov_b32_e32 v13, v4
	v_mov_b32_e32 v14, v4
	v_mov_b32_e32 v15, v4
	v_mov_b32_e32 v16, v4
	v_mov_b32_e32 v17, v4
	v_mov_b32_e32 v18, v4
	v_mov_b32_e32 v19, v4
	v_mov_b32_e32 v28, v4
	v_mov_b32_e32 v29, v4
	v_mov_b32_e32 v30, v4
	v_mov_b32_e32 v31, v4
	v_mov_b32_e32 v32, v4
	v_mov_b32_e32 v33, v4
	v_mov_b32_e32 v34, v4
	v_mov_b32_e32 v35, v4
	v_mov_b32_e32 v44, v4
	v_mov_b32_e32 v45, v4
	v_mov_b32_e32 v46, v4
	v_mov_b32_e32 v47, v4
	v_mov_b32_e32 v48, v4
	v_mov_b32_e32 v49, v4
	v_mov_b32_e32 v50, v4
	v_mov_b32_e32 v51, v4
	v_mov_b32_e32 v20, v4
	v_mov_b32_e32 v21, v4
	v_mov_b32_e32 v22, v4
	v_mov_b32_e32 v23, v4
	v_mov_b32_e32 v24, v4
	v_mov_b32_e32 v25, v4
	v_mov_b32_e32 v26, v4
	v_mov_b32_e32 v27, v4
	v_mov_b32_e32 v36, v4
	v_mov_b32_e32 v37, v4
	v_mov_b32_e32 v38, v4
	v_mov_b32_e32 v39, v4
	v_mov_b32_e32 v40, v4
	v_mov_b32_e32 v41, v4
	v_mov_b32_e32 v42, v4
	v_mov_b32_e32 v43, v4
	v_mov_b32_e32 v52, v4
	v_mov_b32_e32 v53, v4
	v_mov_b32_e32 v54, v4
	v_mov_b32_e32 v55, v4
	v_mov_b32_e32 v56, v4
	v_mov_b32_e32 v57, v4
	v_mov_b32_e32 v58, v4
	v_mov_b32_e32 v59, v4
	v_mov_b32_e32 v60, v4
	v_mov_b32_e32 v61, v4
	v_mov_b32_e32 v62, v4
	v_mov_b32_e32 v63, v4
	v_mov_b32_e32 v64, v4
	v_mov_b32_e32 v65, v4
	v_mov_b32_e32 v66, v4
	v_mov_b32_e32 v67, v4
	v_mov_b32_e32 v68, v4
	v_mov_b32_e32 v69, v4
	v_mov_b32_e32 v70, v4
	v_mov_b32_e32 v71, v4
	v_mov_b32_e32 v72, v4
	v_mov_b32_e32 v73, v4
	v_mov_b32_e32 v74, v4
	v_mov_b32_e32 v75, v4
	v_mov_b32_e32 v76, v4
	v_mov_b32_e32 v77, v4
	v_mov_b32_e32 v78, v4
	v_mov_b32_e32 v79, v4
	v_mov_b32_e32 v80, v4
	v_mov_b32_e32 v81, v4
	v_mov_b32_e32 v82, v4
	v_mov_b32_e32 v83, v4
	v_mov_b32_e32 v88, v4
	v_mov_b32_e32 v89, v4
	v_mov_b32_e32 v90, v4
	v_mov_b32_e32 v91, v4
	v_mov_b32_e32 v96, v4
	v_mov_b32_e32 v97, v4
	v_mov_b32_e32 v98, v4
	v_mov_b32_e32 v99, v4
	v_mov_b32_e32 v104, v4
	v_mov_b32_e32 v105, v4
	v_mov_b32_e32 v106, v4
	v_mov_b32_e32 v107, v4
	v_mov_b32_e32 v112, v4
	v_mov_b32_e32 v113, v4
	v_mov_b32_e32 v114, v4
	v_mov_b32_e32 v115, v4
	v_mov_b32_e32 v84, v4
	v_mov_b32_e32 v85, v4
	v_mov_b32_e32 v86, v4
	v_mov_b32_e32 v87, v4
	v_mov_b32_e32 v92, v4
	v_mov_b32_e32 v93, v4
	v_mov_b32_e32 v94, v4
	v_mov_b32_e32 v95, v4
	v_mov_b32_e32 v100, v4
	v_mov_b32_e32 v101, v4
	v_mov_b32_e32 v102, v4
	v_mov_b32_e32 v103, v4
	v_mov_b32_e32 v108, v4
	v_mov_b32_e32 v109, v4
	v_mov_b32_e32 v110, v4
	v_mov_b32_e32 v111, v4
	v_mov_b32_e32 v116, v4
	v_mov_b32_e32 v117, v4
	v_mov_b32_e32 v118, v4
	v_mov_b32_e32 v119, v4
	v_mov_b32_e32 v120, v4
	v_mov_b32_e32 v121, v4
	v_mov_b32_e32 v122, v4
	v_mov_b32_e32 v123, v4
	v_mov_b32_e32 v124, v4
	v_mov_b32_e32 v125, v4
	v_mov_b32_e32 v126, v4
	v_mov_b32_e32 v127, v4
	v_mov_b32_e32 v128, v4
	v_mov_b32_e32 v129, v4
	v_mov_b32_e32 v130, v4
	v_mov_b32_e32 v131, v4
	s_cmp_lg_u64 s[34:35], 0
	s_cbranch_scc1 .Lsp_g722
	s_setprio 1
.Lsp_g722:
.LBB0_722:
	s_add_u32 s47, s38, s46
	s_addc_u32 s52, s39, 0
	s_add_u32 s50, s47, 0x100
	s_addc_u32 s51, s52, 0
	s_and_b64 s[48:49], s[44:45], exec
	s_cselect_b32 s49, s5, s51
	s_cselect_b32 s48, s70, s50
	s_add_u32 s46, s40, s46
	s_addc_u32 s50, s41, 0
	s_add_u32 s46, s46, 0x100
	s_addc_u32 s50, s50, 0
	s_add_i32 s83, 0, 0x10000
	s_and_b64 s[44:45], s[44:45], exec
	s_cselect_b32 s51, s71, s50
	s_cselect_b32 s50, s72, s46
	s_add_i32 s45, 0, 0x14000
	s_add_u32 s54, s47, 0x80080
	s_addc_u32 s55, s52, 0
	s_add_i32 s82, s83, s21
	s_add_i32 m0, s33, 0xc000
	s_add_i32 s85, s33, 0xe000
	s_add_i32 s77, s82, 0x2000
	v_add_u32_e32 v2, s83, v136
	s_add_u32 s52, s50, 0x80000
	ds_read_b128 v[140:143], v2
	ds_read_b128 v[144:147], v2 offset:1024
	ds_read_b128 v[148:151], v2 offset:2048
	ds_read_b128 v[152:155], v2 offset:3072
	v_add_u32_e32 v2, s45, v136
	s_addc_u32 s53, s51, 0
	s_add_i32 s81, s45, s21
	ds_read_b128 v[156:159], v2
	ds_read_b128 v[160:163], v2 offset:1024
	ds_read_b128 v[164:167], v2 offset:2048
	ds_read_b128 v[178:181], v2 offset:3072
	s_add_i32 s80, s81, 0x2000
	s_add_i32 s76, 0, 0x18000
	s_add_i32 s75, 0, 0x1c000
	s_add_u32 s46, s48, 0x80000
	s_addc_u32 s47, s49, 0
	s_add_i32 s74, s76, s21
	s_add_i32 s73, s74, 0x2000
	s_add_u32 s44, s50, 0x80080
	s_addc_u32 s45, s51, 0
	s_add_i32 s84, s75, s21
	s_add_i32 s83, s84, 0x2000
	v_lshl_add_u64 v[168:169], s[54:55], 0, v[134:135]
	ds_read_b128 v[182:185], v138
	ds_read_b128 v[186:189], v138 offset:1024
	ds_read_b128 v[190:193], v138 offset:2048
	ds_read_b128 v[194:197], v138 offset:3072
	ds_read_b128 v[208:211], v138 offset:4096
	ds_read_b128 v[212:215], v138 offset:5120
	ds_read_b128 v[216:219], v138 offset:6144
	ds_read_b128 v[220:223], v138 offset:7168
	global_load_lds_dwordx4 v[168:169], off
	v_lshl_add_u64 v[168:169], s[54:55], 0, v[132:133]
	s_mov_b32 m0, s85
	s_nop 0
	global_load_lds_dwordx4 v[168:169], off
	s_waitcnt vmcnt(8)
	s_waitcnt lgkmcnt(0)
	s_barrier
	s_waitcnt lgkmcnt(0)
	v_mfma_f32_16x16x32_bf16 v[128:131], v[140:143], v[182:185], v[128:131]
	v_mfma_f32_16x16x32_bf16 v[128:131], v[144:147], v[186:189], v[128:131]
	v_mfma_f32_16x16x32_bf16 v[124:127], v[152:155], v[186:189], v[124:127]
	v_mfma_f32_16x16x32_bf16 v[124:127], v[148:151], v[182:185], v[124:127]
	v_mfma_f32_16x16x32_bf16 v[116:119], v[148:151], v[190:193], v[116:119]
	v_mfma_f32_16x16x32_bf16 v[116:119], v[152:155], v[194:197], v[116:119]
	v_mfma_f32_16x16x32_bf16 v[120:123], v[144:147], v[194:197], v[120:123]
	v_mfma_f32_16x16x32_bf16 v[120:123], v[140:143], v[190:193], v[120:123]
	v_mfma_f32_16x16x32_bf16 v[108:111], v[140:143], v[208:211], v[108:111]
	v_mfma_f32_16x16x32_bf16 v[108:111], v[144:147], v[212:215], v[108:111]
	v_mfma_f32_16x16x32_bf16 v[100:103], v[152:155], v[212:215], v[100:103]
	v_mfma_f32_16x16x32_bf16 v[100:103], v[148:151], v[208:211], v[100:103]
	v_mfma_f32_16x16x32_bf16 v[84:87], v[148:151], v[216:219], v[84:87]
	v_mfma_f32_16x16x32_bf16 v[84:87], v[152:155], v[220:223], v[84:87]
	v_mfma_f32_16x16x32_bf16 v[92:95], v[144:147], v[220:223], v[92:95]
	v_mfma_f32_16x16x32_bf16 v[92:95], v[140:143], v[216:219], v[92:95]
	v_mfma_f32_16x16x32_bf16 v[112:115], v[156:159], v[182:185], v[112:115]
	v_mfma_f32_16x16x32_bf16 v[112:115], v[160:163], v[186:189], v[112:115]
	v_mfma_f32_16x16x32_bf16 v[104:107], v[178:181], v[186:189], v[104:107]
	v_mfma_f32_16x16x32_bf16 v[104:107], v[164:167], v[182:185], v[104:107]
	v_mfma_f32_16x16x32_bf16 v[88:91], v[164:167], v[190:193], v[88:91]
	v_mfma_f32_16x16x32_bf16 v[88:91], v[178:181], v[194:197], v[88:91]
	v_mfma_f32_16x16x32_bf16 v[96:99], v[160:163], v[194:197], v[96:99]
	v_mfma_f32_16x16x32_bf16 v[96:99], v[156:159], v[190:193], v[96:99]
	v_mfma_f32_16x16x32_bf16 v[80:83], v[156:159], v[208:211], v[80:83]
	v_mfma_f32_16x16x32_bf16 v[80:83], v[160:163], v[212:215], v[80:83]
	v_mfma_f32_16x16x32_bf16 v[76:79], v[178:181], v[212:215], v[76:79]
	v_mfma_f32_16x16x32_bf16 v[76:79], v[164:167], v[208:211], v[76:79]
	v_mfma_f32_16x16x32_bf16 v[68:71], v[164:167], v[216:219], v[68:71]
	v_mfma_f32_16x16x32_bf16 v[68:71], v[178:181], v[220:223], v[68:71]
	v_mfma_f32_16x16x32_bf16 v[72:75], v[160:163], v[220:223], v[72:75]
	v_mfma_f32_16x16x32_bf16 v[72:75], v[156:159], v[216:219], v[72:75]
	s_barrier
	s_mov_b32 m0, s82
	v_lshl_add_u64 v[168:169], s[50:51], 0, v[134:135]
	ds_read_b128 v[182:185], v138 offset:16384
	ds_read_b128 v[186:189], v138 offset:17408
	ds_read_b128 v[190:193], v138 offset:18432
	ds_read_b128 v[194:197], v138 offset:19456
	ds_read_b128 v[208:211], v138 offset:20480
	ds_read_b128 v[212:215], v138 offset:21504
	ds_read_b128 v[216:219], v138 offset:22528
	ds_read_b128 v[220:223], v138 offset:23552
	global_load_lds_dwordx4 v[168:169], off
	v_lshl_add_u64 v[224:225], s[50:51], 0, v[132:133]
	s_mov_b32 m0, s77
	v_lshl_add_u64 v[226:227], s[52:53], 0, v[134:135]
	global_load_lds_dwordx4 v[224:225], off
	s_mov_b32 m0, s81
	v_lshl_add_u64 v[228:229], s[48:49], 0, v[132:133]
	global_load_lds_dwordx4 v[226:227], off
	v_lshl_add_u64 v[226:227], s[52:53], 0, v[132:133]
	s_mov_b32 m0, s80
	s_nop 0
	global_load_lds_dwordx4 v[226:227], off
	v_lshl_add_u64 v[226:227], s[48:49], 0, v[134:135]
	s_mov_b32 m0, s33
	s_nop 0
	global_load_lds_dwordx4 v[226:227], off
	s_mov_b32 m0, s61
	s_nop 0
	global_load_lds_dwordx4 v[228:229], off
	s_waitcnt vmcnt(8)
	s_waitcnt lgkmcnt(0)
	s_barrier
	s_waitcnt lgkmcnt(0)
	v_mfma_f32_16x16x32_bf16 v[64:67], v[140:143], v[182:185], v[64:67]
	v_mfma_f32_16x16x32_bf16 v[64:67], v[144:147], v[186:189], v[64:67]
	v_mfma_f32_16x16x32_bf16 v[60:63], v[152:155], v[186:189], v[60:63]
	v_mfma_f32_16x16x32_bf16 v[60:63], v[148:151], v[182:185], v[60:63]
	v_mfma_f32_16x16x32_bf16 v[52:55], v[148:151], v[190:193], v[52:55]
	v_mfma_f32_16x16x32_bf16 v[52:55], v[152:155], v[194:197], v[52:55]
	v_mfma_f32_16x16x32_bf16 v[56:59], v[144:147], v[194:197], v[56:59]
	v_mfma_f32_16x16x32_bf16 v[56:59], v[140:143], v[190:193], v[56:59]
	v_mfma_f32_16x16x32_bf16 v[40:43], v[140:143], v[208:211], v[40:43]
	v_mfma_f32_16x16x32_bf16 v[40:43], v[144:147], v[212:215], v[40:43]
	v_mfma_f32_16x16x32_bf16 v[36:39], v[152:155], v[212:215], v[36:39]
	v_mfma_f32_16x16x32_bf16 v[36:39], v[148:151], v[208:211], v[36:39]
	v_mfma_f32_16x16x32_bf16 v[20:23], v[148:151], v[216:219], v[20:23]
	v_mfma_f32_16x16x32_bf16 v[20:23], v[152:155], v[220:223], v[20:23]
	v_mfma_f32_16x16x32_bf16 v[24:27], v[144:147], v[220:223], v[24:27]
	v_mfma_f32_16x16x32_bf16 v[24:27], v[140:143], v[216:219], v[24:27]
	v_mfma_f32_16x16x32_bf16 v[48:51], v[156:159], v[182:185], v[48:51]
	v_mfma_f32_16x16x32_bf16 v[48:51], v[160:163], v[186:189], v[48:51]
	v_mfma_f32_16x16x32_bf16 v[44:47], v[178:181], v[186:189], v[44:47]
	v_mfma_f32_16x16x32_bf16 v[44:47], v[164:167], v[182:185], v[44:47]
	v_mfma_f32_16x16x32_bf16 v[28:31], v[164:167], v[190:193], v[28:31]
	v_mfma_f32_16x16x32_bf16 v[28:31], v[178:181], v[194:197], v[28:31]
	v_mfma_f32_16x16x32_bf16 v[32:35], v[160:163], v[194:197], v[32:35]
	v_mfma_f32_16x16x32_bf16 v[32:35], v[156:159], v[190:193], v[32:35]
	v_mfma_f32_16x16x32_bf16 v[16:19], v[156:159], v[208:211], v[16:19]
	v_mfma_f32_16x16x32_bf16 v[16:19], v[160:163], v[212:215], v[16:19]
	v_mfma_f32_16x16x32_bf16 v[12:15], v[178:181], v[212:215], v[12:15]
	v_mfma_f32_16x16x32_bf16 v[12:15], v[164:167], v[208:211], v[12:15]
	v_mfma_f32_16x16x32_bf16 v[4:7], v[164:167], v[216:219], v[4:7]
	v_mfma_f32_16x16x32_bf16 v[4:7], v[178:181], v[220:223], v[4:7]
	v_mfma_f32_16x16x32_bf16 v[8:11], v[160:163], v[220:223], v[8:11]
	v_mfma_f32_16x16x32_bf16 v[8:11], v[156:159], v[216:219], v[8:11]
	s_barrier
	v_add_u32_e32 v2, s76, v136
	ds_read_b128 v[140:143], v2
	ds_read_b128 v[144:147], v2 offset:1024
	ds_read_b128 v[148:151], v2 offset:2048
	ds_read_b128 v[152:155], v2 offset:3072
	v_add_u32_e32 v2, s75, v136
	ds_read_b128 v[156:159], v2
	ds_read_b128 v[160:163], v2 offset:1024
	ds_read_b128 v[164:167], v2 offset:2048
	ds_read_b128 v[178:181], v2 offset:3072
	s_mov_b32 m0, s62
	v_lshl_add_u64 v[230:231], s[46:47], 0, v[134:135]
	ds_read_b128 v[182:185], v138 offset:32768
	ds_read_b128 v[186:189], v138 offset:33792
	ds_read_b128 v[190:193], v138 offset:34816
	ds_read_b128 v[194:197], v138 offset:35840
	ds_read_b128 v[208:211], v138 offset:36864
	ds_read_b128 v[212:215], v138 offset:37888
	ds_read_b128 v[216:219], v138 offset:38912
	ds_read_b128 v[220:223], v138 offset:39936
	global_load_lds_dwordx4 v[230:231], off
	v_lshl_add_u64 v[230:231], s[46:47], 0, v[132:133]
	s_mov_b32 m0, s63
	s_nop 0
	global_load_lds_dwordx4 v[230:231], off
	s_waitcnt vmcnt(8)
	s_waitcnt lgkmcnt(0)
	s_barrier
	s_waitcnt lgkmcnt(0)
	v_mfma_f32_16x16x32_bf16 v[128:131], v[140:143], v[182:185], v[128:131]
	v_mfma_f32_16x16x32_bf16 v[128:131], v[144:147], v[186:189], v[128:131]
	v_mfma_f32_16x16x32_bf16 v[124:127], v[152:155], v[186:189], v[124:127]
	v_mfma_f32_16x16x32_bf16 v[124:127], v[148:151], v[182:185], v[124:127]
	v_mfma_f32_16x16x32_bf16 v[116:119], v[148:151], v[190:193], v[116:119]
	v_mfma_f32_16x16x32_bf16 v[116:119], v[152:155], v[194:197], v[116:119]
	v_mfma_f32_16x16x32_bf16 v[120:123], v[144:147], v[194:197], v[120:123]
	v_mfma_f32_16x16x32_bf16 v[120:123], v[140:143], v[190:193], v[120:123]
	v_mfma_f32_16x16x32_bf16 v[108:111], v[140:143], v[208:211], v[108:111]
	v_mfma_f32_16x16x32_bf16 v[108:111], v[144:147], v[212:215], v[108:111]
	v_mfma_f32_16x16x32_bf16 v[100:103], v[152:155], v[212:215], v[100:103]
	v_mfma_f32_16x16x32_bf16 v[100:103], v[148:151], v[208:211], v[100:103]
	v_mfma_f32_16x16x32_bf16 v[84:87], v[148:151], v[216:219], v[84:87]
	v_mfma_f32_16x16x32_bf16 v[84:87], v[152:155], v[220:223], v[84:87]
	v_mfma_f32_16x16x32_bf16 v[92:95], v[144:147], v[220:223], v[92:95]
	v_mfma_f32_16x16x32_bf16 v[92:95], v[140:143], v[216:219], v[92:95]
	v_mfma_f32_16x16x32_bf16 v[112:115], v[156:159], v[182:185], v[112:115]
	v_mfma_f32_16x16x32_bf16 v[112:115], v[160:163], v[186:189], v[112:115]
	v_mfma_f32_16x16x32_bf16 v[104:107], v[178:181], v[186:189], v[104:107]
	v_mfma_f32_16x16x32_bf16 v[104:107], v[164:167], v[182:185], v[104:107]
	v_mfma_f32_16x16x32_bf16 v[88:91], v[164:167], v[190:193], v[88:91]
	v_mfma_f32_16x16x32_bf16 v[88:91], v[178:181], v[194:197], v[88:91]
	v_mfma_f32_16x16x32_bf16 v[96:99], v[160:163], v[194:197], v[96:99]
	v_mfma_f32_16x16x32_bf16 v[96:99], v[156:159], v[190:193], v[96:99]
	v_mfma_f32_16x16x32_bf16 v[80:83], v[156:159], v[208:211], v[80:83]
	v_mfma_f32_16x16x32_bf16 v[80:83], v[160:163], v[212:215], v[80:83]
	v_mfma_f32_16x16x32_bf16 v[76:79], v[178:181], v[212:215], v[76:79]
	v_mfma_f32_16x16x32_bf16 v[76:79], v[164:167], v[208:211], v[76:79]
	v_mfma_f32_16x16x32_bf16 v[68:71], v[164:167], v[216:219], v[68:71]
	v_mfma_f32_16x16x32_bf16 v[68:71], v[178:181], v[220:223], v[68:71]
	v_mfma_f32_16x16x32_bf16 v[72:75], v[160:163], v[220:223], v[72:75]
	v_mfma_f32_16x16x32_bf16 v[72:75], v[156:159], v[216:219], v[72:75]
	s_barrier
	s_mov_b32 m0, s74
	v_lshl_add_u64 v[168:169], v[168:169], 0, s[18:19]
	ds_read_b128 v[182:185], v138 offset:49152
	ds_read_b128 v[186:189], v138 offset:50176
	ds_read_b128 v[190:193], v138 offset:51200
	ds_read_b128 v[194:197], v138 offset:52224
	ds_read_b128 v[208:211], v138 offset:53248
	ds_read_b128 v[212:215], v138 offset:54272
	ds_read_b128 v[216:219], v138 offset:55296
	ds_read_b128 v[220:223], v138 offset:56320
	global_load_lds_dwordx4 v[168:169], off
	v_lshl_add_u64 v[168:169], v[224:225], 0, s[18:19]
	s_mov_b32 m0, s73
	s_nop 0
	global_load_lds_dwordx4 v[168:169], off
	v_lshl_add_u64 v[168:169], s[44:45], 0, v[134:135]
	s_mov_b32 m0, s84
	s_nop 0
	global_load_lds_dwordx4 v[168:169], off
	v_lshl_add_u64 v[168:169], s[44:45], 0, v[132:133]
	s_mov_b32 m0, s83
	s_nop 0
	global_load_lds_dwordx4 v[168:169], off
	v_lshl_add_u64 v[168:169], v[226:227], 0, s[18:19]
	s_mov_b32 m0, s65
	s_nop 0
	global_load_lds_dwordx4 v[168:169], off
	v_lshl_add_u64 v[168:169], v[228:229], 0, s[18:19]
	s_mov_b32 m0, s66
	s_nop 0
	global_load_lds_dwordx4 v[168:169], off
	s_waitcnt vmcnt(8)
	s_waitcnt lgkmcnt(0)
	s_barrier
	s_waitcnt lgkmcnt(0)
	v_mfma_f32_16x16x32_bf16 v[64:67], v[140:143], v[182:185], v[64:67]
	v_mfma_f32_16x16x32_bf16 v[64:67], v[144:147], v[186:189], v[64:67]
	v_mfma_f32_16x16x32_bf16 v[60:63], v[152:155], v[186:189], v[60:63]
	v_mfma_f32_16x16x32_bf16 v[60:63], v[148:151], v[182:185], v[60:63]
	v_mfma_f32_16x16x32_bf16 v[52:55], v[148:151], v[190:193], v[52:55]
	v_mfma_f32_16x16x32_bf16 v[52:55], v[152:155], v[194:197], v[52:55]
	v_mfma_f32_16x16x32_bf16 v[56:59], v[144:147], v[194:197], v[56:59]
	v_mfma_f32_16x16x32_bf16 v[56:59], v[140:143], v[190:193], v[56:59]
	v_mfma_f32_16x16x32_bf16 v[40:43], v[140:143], v[208:211], v[40:43]
	v_mfma_f32_16x16x32_bf16 v[40:43], v[144:147], v[212:215], v[40:43]
	v_mfma_f32_16x16x32_bf16 v[36:39], v[152:155], v[212:215], v[36:39]
	v_mfma_f32_16x16x32_bf16 v[36:39], v[148:151], v[208:211], v[36:39]
	v_mfma_f32_16x16x32_bf16 v[20:23], v[148:151], v[216:219], v[20:23]
	v_mfma_f32_16x16x32_bf16 v[20:23], v[152:155], v[220:223], v[20:23]
	v_mfma_f32_16x16x32_bf16 v[24:27], v[144:147], v[220:223], v[24:27]
	v_mfma_f32_16x16x32_bf16 v[24:27], v[140:143], v[216:219], v[24:27]
	v_mfma_f32_16x16x32_bf16 v[48:51], v[156:159], v[182:185], v[48:51]
	v_mfma_f32_16x16x32_bf16 v[48:51], v[160:163], v[186:189], v[48:51]
	v_mfma_f32_16x16x32_bf16 v[44:47], v[178:181], v[186:189], v[44:47]
	v_mfma_f32_16x16x32_bf16 v[44:47], v[164:167], v[182:185], v[44:47]
	v_mfma_f32_16x16x32_bf16 v[28:31], v[164:167], v[190:193], v[28:31]
	v_mfma_f32_16x16x32_bf16 v[28:31], v[178:181], v[194:197], v[28:31]
	v_mfma_f32_16x16x32_bf16 v[32:35], v[160:163], v[194:197], v[32:35]
	v_mfma_f32_16x16x32_bf16 v[32:35], v[156:159], v[190:193], v[32:35]
	v_mfma_f32_16x16x32_bf16 v[16:19], v[156:159], v[208:211], v[16:19]
	v_mfma_f32_16x16x32_bf16 v[16:19], v[160:163], v[212:215], v[16:19]
	v_mfma_f32_16x16x32_bf16 v[12:15], v[178:181], v[212:215], v[12:15]
	v_mfma_f32_16x16x32_bf16 v[12:15], v[164:167], v[208:211], v[12:15]
	v_mfma_f32_16x16x32_bf16 v[4:7], v[164:167], v[216:219], v[4:7]
	v_mfma_f32_16x16x32_bf16 v[4:7], v[178:181], v[220:223], v[4:7]
	v_mfma_f32_16x16x32_bf16 v[8:11], v[160:163], v[220:223], v[8:11]
	v_mfma_f32_16x16x32_bf16 v[8:11], v[156:159], v[216:219], v[8:11]
	s_barrier
	s_movk_i32 s46, 0x100
	s_andn2_b64 vcc, exec, s[42:43]
	s_mov_b64 s[44:45], -1
	s_mov_b64 s[42:43], 0
	s_cbranch_vccz .LBB0_722
	s_setprio 0
	s_and_b64 vcc, exec, s[34:35]
	s_cbranch_vccz .LBB0_725
	s_barrier

.LBB0_747:
	s_ashr_i32 s27, s26, 31
	s_lshl_b64 s[34:35], s[26:27], 21
	s_add_u32 s34, s59, s34
	s_addc_u32 s35, s60, s35
	s_and_b64 s[36:37], s[38:39], exec
	s_cselect_b32 s27, s35, s41
	s_cselect_b32 s51, s34, s40
	s_ashr_i32 s13, s12, 31
	s_lshl_b64 s[36:37], s[12:13], 21
	s_add_u32 s36, s1, s36
	s_addc_u32 s37, s7, s37
	s_and_b64 s[44:45], s[38:39], exec
	s_cselect_b32 s13, s37, s43
	s_cselect_b32 s52, s36, s42
	s_add_u32 s40, s40, 0x100080
	s_addc_u32 s41, s41, 0
	s_add_u32 s53, s42, 0x100
	v_mov_b32_e32 v4, 0
	s_addc_u32 s54, s43, 0
	s_mov_b32 s55, -2
	v_mov_b32_e32 v5, v4
	v_mov_b32_e32 v6, v4
	v_mov_b32_e32 v7, v4
	v_mov_b32_e32 v8, v4
	v_mov_b32_e32 v9, v4
	v_mov_b32_e32 v10, v4
	v_mov_b32_e32 v11, v4
	v_mov_b32_e32 v12, v4
	v_mov_b32_e32 v13, v4
	v_mov_b32_e32 v14, v4
	v_mov_b32_e32 v15, v4
	v_mov_b32_e32 v20, v4
	v_mov_b32_e32 v21, v4
	v_mov_b32_e32 v22, v4
	v_mov_b32_e32 v23, v4
	v_mov_b32_e32 v28, v4
	v_mov_b32_e32 v29, v4
	v_mov_b32_e32 v30, v4
	v_mov_b32_e32 v31, v4
	v_mov_b32_e32 v36, v4
	v_mov_b32_e32 v37, v4
	v_mov_b32_e32 v38, v4
	v_mov_b32_e32 v39, v4
	v_mov_b32_e32 v44, v4
	v_mov_b32_e32 v45, v4
	v_mov_b32_e32 v46, v4
	v_mov_b32_e32 v47, v4
	v_mov_b32_e32 v52, v4
	v_mov_b32_e32 v53, v4
	v_mov_b32_e32 v54, v4
	v_mov_b32_e32 v55, v4
	v_mov_b32_e32 v16, v4
	v_mov_b32_e32 v17, v4
	v_mov_b32_e32 v18, v4
	v_mov_b32_e32 v19, v4
	v_mov_b32_e32 v24, v4
	v_mov_b32_e32 v25, v4
	v_mov_b32_e32 v26, v4
	v_mov_b32_e32 v27, v4
	v_mov_b32_e32 v32, v4
	v_mov_b32_e32 v33, v4
	v_mov_b32_e32 v34, v4
	v_mov_b32_e32 v35, v4
	v_mov_b32_e32 v40, v4
	v_mov_b32_e32 v41, v4
	v_mov_b32_e32 v42, v4
	v_mov_b32_e32 v43, v4
	v_mov_b32_e32 v48, v4
	v_mov_b32_e32 v49, v4
	v_mov_b32_e32 v50, v4
	v_mov_b32_e32 v51, v4
	v_mov_b32_e32 v56, v4
	v_mov_b32_e32 v57, v4
	v_mov_b32_e32 v58, v4
	v_mov_b32_e32 v59, v4
	v_mov_b32_e32 v60, v4
	v_mov_b32_e32 v61, v4
	v_mov_b32_e32 v62, v4
	v_mov_b32_e32 v63, v4
	v_mov_b32_e32 v64, v4
	v_mov_b32_e32 v65, v4
	v_mov_b32_e32 v66, v4
	v_mov_b32_e32 v67, v4
	v_mov_b32_e32 v68, v4
	v_mov_b32_e32 v69, v4
	v_mov_b32_e32 v70, v4
	v_mov_b32_e32 v71, v4
	v_mov_b32_e32 v72, v4
	v_mov_b32_e32 v73, v4
	v_mov_b32_e32 v74, v4
	v_mov_b32_e32 v75, v4
	v_mov_b32_e32 v76, v4
	v_mov_b32_e32 v77, v4
	v_mov_b32_e32 v78, v4
	v_mov_b32_e32 v79, v4
	v_mov_b32_e32 v84, v4
	v_mov_b32_e32 v85, v4
	v_mov_b32_e32 v86, v4
	v_mov_b32_e32 v87, v4
	v_mov_b32_e32 v92, v4
	v_mov_b32_e32 v93, v4
	v_mov_b32_e32 v94, v4
	v_mov_b32_e32 v95, v4
	v_mov_b32_e32 v100, v4
	v_mov_b32_e32 v101, v4
	v_mov_b32_e32 v102, v4
	v_mov_b32_e32 v103, v4
	v_mov_b32_e32 v108, v4
	v_mov_b32_e32 v109, v4
	v_mov_b32_e32 v110, v4
	v_mov_b32_e32 v111, v4
	v_mov_b32_e32 v116, v4
	v_mov_b32_e32 v117, v4
	v_mov_b32_e32 v118, v4
	v_mov_b32_e32 v119, v4
	v_mov_b32_e32 v80, v4
	v_mov_b32_e32 v81, v4
	v_mov_b32_e32 v82, v4
	v_mov_b32_e32 v83, v4
	v_mov_b32_e32 v88, v4
	v_mov_b32_e32 v89, v4
	v_mov_b32_e32 v90, v4
	v_mov_b32_e32 v91, v4
	v_mov_b32_e32 v96, v4
	v_mov_b32_e32 v97, v4
	v_mov_b32_e32 v98, v4
	v_mov_b32_e32 v99, v4
	v_mov_b32_e32 v104, v4
	v_mov_b32_e32 v105, v4
	v_mov_b32_e32 v106, v4
	v_mov_b32_e32 v107, v4
	v_mov_b32_e32 v112, v4
	v_mov_b32_e32 v113, v4
	v_mov_b32_e32 v114, v4
	v_mov_b32_e32 v115, v4
	v_mov_b32_e32 v120, v4
	v_mov_b32_e32 v121, v4
	v_mov_b32_e32 v122, v4
	v_mov_b32_e32 v123, v4
	v_mov_b32_e32 v124, v4
	v_mov_b32_e32 v125, v4
	v_mov_b32_e32 v126, v4
	v_mov_b32_e32 v127, v4
	v_mov_b32_e32 v128, v4
	v_mov_b32_e32 v129, v4
	v_mov_b32_e32 v130, v4
	v_mov_b32_e32 v131, v4
	s_cmp_lg_u64 s[8:9], 0
	s_cbranch_scc1 .Lsp_g748
	s_setprio 1
.Lsp_g748:
.LBB0_748:
	s_add_u32 s42, s40, 0xfff00080
	s_addc_u32 s43, s41, -1
	s_add_i32 s61, 0, 0x10000
	s_cmp_eq_u32 s55, 60
	s_cselect_b32 s45, s27, s43
	s_cselect_b32 s44, s51, s42
	v_add_u32_e32 v142, s61, v144
	s_cselect_b32 s43, s13, s54
	s_cselect_b32 s42, s52, s53
	s_add_i32 s65, 0, 0x14000
	ds_read_b128 v[148:151], v142
	ds_read_b128 v[152:155], v142 offset:1024
	ds_read_b128 v[156:159], v142 offset:2048
	ds_read_b128 v[160:163], v142 offset:3072
	v_add_u32_e32 v142, s65, v144
	ds_read_b128 v[164:167], v142
	ds_read_b128 v[178:181], v142 offset:1024
	ds_read_b128 v[182:185], v142 offset:2048
	ds_read_b128 v[186:189], v142 offset:3072
	v_lshl_add_u64 v[142:143], s[40:41], 0, v[138:139]
	s_add_i32 m0, s21, 0xc000
	ds_read_b128 v[190:193], v146
	ds_read_b128 v[194:197], v146 offset:1024
	ds_read_b128 v[208:211], v146 offset:2048
	ds_read_b128 v[212:215], v146 offset:3072
	ds_read_b128 v[216:219], v146 offset:4096
	ds_read_b128 v[220:223], v146 offset:5120
	ds_read_b128 v[224:227], v146 offset:6144
	ds_read_b128 v[228:231], v146 offset:7168
	global_load_lds_dwordx4 v[142:143], off
	v_lshl_add_u64 v[142:143], s[40:41], 0, v[140:141]
	s_add_i32 m0, s21, 0xe000
	s_nop 0
	global_load_lds_dwordx4 v[142:143], off
	s_waitcnt vmcnt(8)
	s_waitcnt lgkmcnt(0)
	s_barrier
	s_waitcnt lgkmcnt(0)
	v_mfma_f32_16x16x32_bf16 v[128:131], v[148:151], v[190:193], v[128:131]
	v_mfma_f32_16x16x32_bf16 v[128:131], v[152:155], v[194:197], v[128:131]
	v_mfma_f32_16x16x32_bf16 v[124:127], v[160:163], v[194:197], v[124:127]
	v_mfma_f32_16x16x32_bf16 v[124:127], v[156:159], v[190:193], v[124:127]
	v_mfma_f32_16x16x32_bf16 v[112:115], v[156:159], v[208:211], v[112:115]
	v_mfma_f32_16x16x32_bf16 v[112:115], v[160:163], v[212:215], v[112:115]
	v_mfma_f32_16x16x32_bf16 v[120:123], v[152:155], v[212:215], v[120:123]
	v_mfma_f32_16x16x32_bf16 v[120:123], v[148:151], v[208:211], v[120:123]
	v_mfma_f32_16x16x32_bf16 v[104:107], v[148:151], v[216:219], v[104:107]
	v_mfma_f32_16x16x32_bf16 v[104:107], v[152:155], v[220:223], v[104:107]
	v_mfma_f32_16x16x32_bf16 v[96:99], v[160:163], v[220:223], v[96:99]
	v_mfma_f32_16x16x32_bf16 v[96:99], v[156:159], v[216:219], v[96:99]
	v_mfma_f32_16x16x32_bf16 v[80:83], v[156:159], v[224:227], v[80:83]
	v_mfma_f32_16x16x32_bf16 v[80:83], v[160:163], v[228:231], v[80:83]
	v_mfma_f32_16x16x32_bf16 v[88:91], v[152:155], v[228:231], v[88:91]
	v_mfma_f32_16x16x32_bf16 v[88:91], v[148:151], v[224:227], v[88:91]
	v_mfma_f32_16x16x32_bf16 v[116:119], v[164:167], v[190:193], v[116:119]
	v_mfma_f32_16x16x32_bf16 v[116:119], v[178:181], v[194:197], v[116:119]
	v_mfma_f32_16x16x32_bf16 v[108:111], v[186:189], v[194:197], v[108:111]
	v_mfma_f32_16x16x32_bf16 v[108:111], v[182:185], v[190:193], v[108:111]
	v_mfma_f32_16x16x32_bf16 v[92:95], v[182:185], v[208:211], v[92:95]
	v_mfma_f32_16x16x32_bf16 v[92:95], v[186:189], v[212:215], v[92:95]
	v_mfma_f32_16x16x32_bf16 v[100:103], v[178:181], v[212:215], v[100:103]
	v_mfma_f32_16x16x32_bf16 v[100:103], v[164:167], v[208:211], v[100:103]
	v_mfma_f32_16x16x32_bf16 v[84:87], v[164:167], v[216:219], v[84:87]
	v_mfma_f32_16x16x32_bf16 v[84:87], v[178:181], v[220:223], v[84:87]
	v_mfma_f32_16x16x32_bf16 v[76:79], v[186:189], v[220:223], v[76:79]
	v_mfma_f32_16x16x32_bf16 v[76:79], v[182:185], v[216:219], v[76:79]
	v_mfma_f32_16x16x32_bf16 v[68:71], v[182:185], v[224:227], v[68:71]
	v_mfma_f32_16x16x32_bf16 v[68:71], v[186:189], v[228:231], v[68:71]
	v_mfma_f32_16x16x32_bf16 v[72:75], v[178:181], v[228:231], v[72:75]
	v_mfma_f32_16x16x32_bf16 v[72:75], v[164:167], v[224:227], v[72:75]
	s_barrier
	s_add_i32 s61, s61, s11
	v_lshl_add_u64 v[142:143], s[42:43], 0, v[2:3]
	s_mov_b32 m0, s61
	ds_read_b128 v[190:193], v146 offset:16384
	ds_read_b128 v[194:197], v146 offset:17408
	ds_read_b128 v[208:211], v146 offset:18432
	ds_read_b128 v[212:215], v146 offset:19456
	ds_read_b128 v[216:219], v146 offset:20480
	ds_read_b128 v[220:223], v146 offset:21504
	ds_read_b128 v[224:227], v146 offset:22528
	ds_read_b128 v[228:231], v146 offset:23552
	global_load_lds_dwordx4 v[142:143], off
	s_add_i32 m0, s61, 0x2000
	s_add_u32 s62, s42, 0x100000
	v_lshl_add_u64 v[168:169], s[42:43], 0, v[136:137]
	s_addc_u32 s63, s43, 0
	s_add_i32 s61, s65, s11
	global_load_lds_dwordx4 v[168:169], off
	v_lshl_add_u64 v[232:233], s[62:63], 0, v[2:3]
	s_mov_b32 m0, s61
	v_lshl_add_u64 v[234:235], s[44:45], 0, v[134:135]
	global_load_lds_dwordx4 v[232:233], off
	v_lshl_add_u64 v[232:233], s[62:63], 0, v[136:137]
	s_add_i32 m0, s61, 0x2000
	s_nop 0
	global_load_lds_dwordx4 v[232:233], off
	v_lshl_add_u64 v[232:233], s[44:45], 0, v[132:133]
	s_mov_b32 m0, s21
	s_nop 0
	global_load_lds_dwordx4 v[232:233], off
	s_mov_b32 m0, s22
	s_nop 0
	global_load_lds_dwordx4 v[234:235], off
	s_waitcnt vmcnt(8)
	s_waitcnt lgkmcnt(0)
	s_barrier
	s_waitcnt lgkmcnt(0)
	v_mfma_f32_16x16x32_bf16 v[64:67], v[148:151], v[190:193], v[64:67]
	v_mfma_f32_16x16x32_bf16 v[64:67], v[152:155], v[194:197], v[64:67]
	v_mfma_f32_16x16x32_bf16 v[60:63], v[160:163], v[194:197], v[60:63]
	v_mfma_f32_16x16x32_bf16 v[60:63], v[156:159], v[190:193], v[60:63]
	v_mfma_f32_16x16x32_bf16 v[48:51], v[156:159], v[208:211], v[48:51]
	v_mfma_f32_16x16x32_bf16 v[48:51], v[160:163], v[212:215], v[48:51]
	v_mfma_f32_16x16x32_bf16 v[56:59], v[152:155], v[212:215], v[56:59]
	v_mfma_f32_16x16x32_bf16 v[56:59], v[148:151], v[208:211], v[56:59]
	v_mfma_f32_16x16x32_bf16 v[40:43], v[148:151], v[216:219], v[40:43]
	v_mfma_f32_16x16x32_bf16 v[40:43], v[152:155], v[220:223], v[40:43]
	v_mfma_f32_16x16x32_bf16 v[32:35], v[160:163], v[220:223], v[32:35]
	v_mfma_f32_16x16x32_bf16 v[32:35], v[156:159], v[216:219], v[32:35]
	v_mfma_f32_16x16x32_bf16 v[16:19], v[156:159], v[224:227], v[16:19]
	v_mfma_f32_16x16x32_bf16 v[16:19], v[160:163], v[228:231], v[16:19]
	v_mfma_f32_16x16x32_bf16 v[24:27], v[152:155], v[228:231], v[24:27]
	v_mfma_f32_16x16x32_bf16 v[24:27], v[148:151], v[224:227], v[24:27]
	v_mfma_f32_16x16x32_bf16 v[52:55], v[164:167], v[190:193], v[52:55]
	v_mfma_f32_16x16x32_bf16 v[52:55], v[178:181], v[194:197], v[52:55]
	v_mfma_f32_16x16x32_bf16 v[44:47], v[186:189], v[194:197], v[44:47]
	v_mfma_f32_16x16x32_bf16 v[44:47], v[182:185], v[190:193], v[44:47]
	v_mfma_f32_16x16x32_bf16 v[28:31], v[182:185], v[208:211], v[28:31]
	v_mfma_f32_16x16x32_bf16 v[28:31], v[186:189], v[212:215], v[28:31]
	v_mfma_f32_16x16x32_bf16 v[36:39], v[178:181], v[212:215], v[36:39]
	v_mfma_f32_16x16x32_bf16 v[36:39], v[164:167], v[208:211], v[36:39]
	v_mfma_f32_16x16x32_bf16 v[20:23], v[164:167], v[216:219], v[20:23]
	v_mfma_f32_16x16x32_bf16 v[20:23], v[178:181], v[220:223], v[20:23]
	v_mfma_f32_16x16x32_bf16 v[12:15], v[186:189], v[220:223], v[12:15]
	v_mfma_f32_16x16x32_bf16 v[12:15], v[182:185], v[216:219], v[12:15]
	v_mfma_f32_16x16x32_bf16 v[4:7], v[182:185], v[224:227], v[4:7]
	v_mfma_f32_16x16x32_bf16 v[4:7], v[186:189], v[228:231], v[4:7]
	v_mfma_f32_16x16x32_bf16 v[8:11], v[178:181], v[228:231], v[8:11]
	v_mfma_f32_16x16x32_bf16 v[8:11], v[164:167], v[224:227], v[8:11]
	s_barrier
	s_add_i32 s61, 0, 0x18000
	v_add_u32_e32 v147, s61, v144
	s_add_i32 s62, 0, 0x1c000
	ds_read_b128 v[148:151], v147
	ds_read_b128 v[152:155], v147 offset:1024
	ds_read_b128 v[156:159], v147 offset:2048
	ds_read_b128 v[160:163], v147 offset:3072
	v_add_u32_e32 v147, s62, v144
	ds_read_b128 v[164:167], v147
	ds_read_b128 v[178:181], v147 offset:1024
	ds_read_b128 v[182:185], v147 offset:2048
	ds_read_b128 v[186:189], v147 offset:3072
	s_add_u32 s44, s44, 0x100000
	s_addc_u32 s45, s45, 0
	s_mov_b32 m0, s33
	v_lshl_add_u64 v[236:237], s[44:45], 0, v[132:133]
	ds_read_b128 v[190:193], v146 offset:32768
	ds_read_b128 v[194:197], v146 offset:33792
	ds_read_b128 v[208:211], v146 offset:34816
	ds_read_b128 v[212:215], v146 offset:35840
	ds_read_b128 v[216:219], v146 offset:36864
	ds_read_b128 v[220:223], v146 offset:37888
	ds_read_b128 v[224:227], v146 offset:38912
	ds_read_b128 v[228:231], v146 offset:39936
	global_load_lds_dwordx4 v[236:237], off
	v_lshl_add_u64 v[236:237], s[44:45], 0, v[134:135]
	s_mov_b32 m0, s46
	s_nop 0
	global_load_lds_dwordx4 v[236:237], off
	s_waitcnt vmcnt(8)
	s_waitcnt lgkmcnt(0)
	s_barrier
	s_waitcnt lgkmcnt(0)
	v_mfma_f32_16x16x32_bf16 v[128:131], v[148:151], v[190:193], v[128:131]
	v_mfma_f32_16x16x32_bf16 v[128:131], v[152:155], v[194:197], v[128:131]
	v_mfma_f32_16x16x32_bf16 v[124:127], v[160:163], v[194:197], v[124:127]
	v_mfma_f32_16x16x32_bf16 v[124:127], v[156:159], v[190:193], v[124:127]
	v_mfma_f32_16x16x32_bf16 v[112:115], v[156:159], v[208:211], v[112:115]
	v_mfma_f32_16x16x32_bf16 v[112:115], v[160:163], v[212:215], v[112:115]
	v_mfma_f32_16x16x32_bf16 v[120:123], v[152:155], v[212:215], v[120:123]
	v_mfma_f32_16x16x32_bf16 v[120:123], v[148:151], v[208:211], v[120:123]
	v_mfma_f32_16x16x32_bf16 v[104:107], v[148:151], v[216:219], v[104:107]
	v_mfma_f32_16x16x32_bf16 v[104:107], v[152:155], v[220:223], v[104:107]
	v_mfma_f32_16x16x32_bf16 v[96:99], v[160:163], v[220:223], v[96:99]
	v_mfma_f32_16x16x32_bf16 v[96:99], v[156:159], v[216:219], v[96:99]
	v_mfma_f32_16x16x32_bf16 v[80:83], v[156:159], v[224:227], v[80:83]
	v_mfma_f32_16x16x32_bf16 v[80:83], v[160:163], v[228:231], v[80:83]
	v_mfma_f32_16x16x32_bf16 v[88:91], v[152:155], v[228:231], v[88:91]
	v_mfma_f32_16x16x32_bf16 v[88:91], v[148:151], v[224:227], v[88:91]
	v_mfma_f32_16x16x32_bf16 v[116:119], v[164:167], v[190:193], v[116:119]
	v_mfma_f32_16x16x32_bf16 v[116:119], v[178:181], v[194:197], v[116:119]
	v_mfma_f32_16x16x32_bf16 v[108:111], v[186:189], v[194:197], v[108:111]
	v_mfma_f32_16x16x32_bf16 v[108:111], v[182:185], v[190:193], v[108:111]
	v_mfma_f32_16x16x32_bf16 v[92:95], v[182:185], v[208:211], v[92:95]
	v_mfma_f32_16x16x32_bf16 v[92:95], v[186:189], v[212:215], v[92:95]
	v_mfma_f32_16x16x32_bf16 v[100:103], v[178:181], v[212:215], v[100:103]
	v_mfma_f32_16x16x32_bf16 v[100:103], v[164:167], v[208:211], v[100:103]
	v_mfma_f32_16x16x32_bf16 v[84:87], v[164:167], v[216:219], v[84:87]
	v_mfma_f32_16x16x32_bf16 v[84:87], v[178:181], v[220:223], v[84:87]
	v_mfma_f32_16x16x32_bf16 v[76:79], v[186:189], v[220:223], v[76:79]
	v_mfma_f32_16x16x32_bf16 v[76:79], v[182:185], v[216:219], v[76:79]
	v_mfma_f32_16x16x32_bf16 v[68:71], v[182:185], v[224:227], v[68:71]
	v_mfma_f32_16x16x32_bf16 v[68:71], v[186:189], v[228:231], v[68:71]
	v_mfma_f32_16x16x32_bf16 v[72:75], v[178:181], v[228:231], v[72:75]
	v_mfma_f32_16x16x32_bf16 v[72:75], v[164:167], v[224:227], v[72:75]
	s_barrier
	s_add_i32 s44, s61, s11
	v_lshl_add_u64 v[142:143], v[142:143], 0, s[18:19]
	s_mov_b32 m0, s44
	ds_read_b128 v[190:193], v146 offset:49152
	ds_read_b128 v[194:197], v146 offset:50176
	ds_read_b128 v[208:211], v146 offset:51200
	ds_read_b128 v[212:215], v146 offset:52224
	ds_read_b128 v[216:219], v146 offset:53248
	ds_read_b128 v[220:223], v146 offset:54272
	ds_read_b128 v[224:227], v146 offset:55296
	ds_read_b128 v[228:231], v146 offset:56320
	global_load_lds_dwordx4 v[142:143], off
	s_add_i32 m0, s44, 0x2000
	s_add_u32 s42, s42, 0x100080
	v_lshl_add_u64 v[142:143], v[168:169], 0, s[18:19]
	s_addc_u32 s43, s43, 0
	s_add_i32 s44, s62, s11
	global_load_lds_dwordx4 v[142:143], off
	v_lshl_add_u64 v[142:143], s[42:43], 0, v[2:3]
	s_mov_b32 m0, s44
	s_nop 0
	global_load_lds_dwordx4 v[142:143], off
	v_lshl_add_u64 v[142:143], s[42:43], 0, v[136:137]
	s_add_i32 m0, s44, 0x2000
	s_nop 0
	global_load_lds_dwordx4 v[142:143], off
	v_lshl_add_u64 v[142:143], v[232:233], 0, s[18:19]
	s_mov_b32 m0, s47
	s_nop 0
	global_load_lds_dwordx4 v[142:143], off
	v_lshl_add_u64 v[142:143], v[234:235], 0, s[18:19]
	s_mov_b32 m0, s48
	s_nop 0
	global_load_lds_dwordx4 v[142:143], off
	s_waitcnt vmcnt(8)
	s_waitcnt lgkmcnt(0)
	s_barrier
	s_waitcnt lgkmcnt(0)
	v_mfma_f32_16x16x32_bf16 v[64:67], v[148:151], v[190:193], v[64:67]
	v_mfma_f32_16x16x32_bf16 v[64:67], v[152:155], v[194:197], v[64:67]
	v_mfma_f32_16x16x32_bf16 v[60:63], v[160:163], v[194:197], v[60:63]
	v_mfma_f32_16x16x32_bf16 v[60:63], v[156:159], v[190:193], v[60:63]
	v_mfma_f32_16x16x32_bf16 v[48:51], v[156:159], v[208:211], v[48:51]
	v_mfma_f32_16x16x32_bf16 v[48:51], v[160:163], v[212:215], v[48:51]
	v_mfma_f32_16x16x32_bf16 v[56:59], v[152:155], v[212:215], v[56:59]
	v_mfma_f32_16x16x32_bf16 v[56:59], v[148:151], v[208:211], v[56:59]
	v_mfma_f32_16x16x32_bf16 v[40:43], v[148:151], v[216:219], v[40:43]
	v_mfma_f32_16x16x32_bf16 v[40:43], v[152:155], v[220:223], v[40:43]
	v_mfma_f32_16x16x32_bf16 v[32:35], v[160:163], v[220:223], v[32:35]
	v_mfma_f32_16x16x32_bf16 v[32:35], v[156:159], v[216:219], v[32:35]
	v_mfma_f32_16x16x32_bf16 v[16:19], v[156:159], v[224:227], v[16:19]
	v_mfma_f32_16x16x32_bf16 v[16:19], v[160:163], v[228:231], v[16:19]
	v_mfma_f32_16x16x32_bf16 v[24:27], v[152:155], v[228:231], v[24:27]
	v_mfma_f32_16x16x32_bf16 v[24:27], v[148:151], v[224:227], v[24:27]
	v_mfma_f32_16x16x32_bf16 v[52:55], v[164:167], v[190:193], v[52:55]
	v_mfma_f32_16x16x32_bf16 v[52:55], v[178:181], v[194:197], v[52:55]
	v_mfma_f32_16x16x32_bf16 v[44:47], v[186:189], v[194:197], v[44:47]
	v_mfma_f32_16x16x32_bf16 v[44:47], v[182:185], v[190:193], v[44:47]
	v_mfma_f32_16x16x32_bf16 v[28:31], v[182:185], v[208:211], v[28:31]
	v_mfma_f32_16x16x32_bf16 v[28:31], v[186:189], v[212:215], v[28:31]
	v_mfma_f32_16x16x32_bf16 v[36:39], v[178:181], v[212:215], v[36:39]
	v_mfma_f32_16x16x32_bf16 v[36:39], v[164:167], v[208:211], v[36:39]
	v_mfma_f32_16x16x32_bf16 v[20:23], v[164:167], v[216:219], v[20:23]
	v_mfma_f32_16x16x32_bf16 v[20:23], v[178:181], v[220:223], v[20:23]
	v_mfma_f32_16x16x32_bf16 v[12:15], v[186:189], v[220:223], v[12:15]
	v_mfma_f32_16x16x32_bf16 v[12:15], v[182:185], v[216:219], v[12:15]
	v_mfma_f32_16x16x32_bf16 v[4:7], v[182:185], v[224:227], v[4:7]
	v_mfma_f32_16x16x32_bf16 v[4:7], v[186:189], v[228:231], v[4:7]
	v_mfma_f32_16x16x32_bf16 v[8:11], v[178:181], v[228:231], v[8:11]
	v_mfma_f32_16x16x32_bf16 v[8:11], v[164:167], v[224:227], v[8:11]
	s_barrier
	s_add_i32 s55, s55, 2
	s_add_u32 s40, s40, 0x100
	s_addc_u32 s41, s41, 0
	s_add_u32 s53, s53, 0x100
	s_addc_u32 s54, s54, 0
	s_cmp_gt_u32 s55, 61
	s_cbranch_scc0 .LBB0_748
	s_setprio 0
	s_and_b64 vcc, exec, s[8:9]
	s_cbranch_vccz .LBB0_751
	s_barrier

.LBB0_761:
	s_add_i32 s46, s46, 1
	s_mov_b32 s48, s2
	s_mul_i32 s2, s46, s24
	s_add_i32 s2, s2, s23
	s_cmpk_lt_i32 s2, 0x100
	s_mov_b32 s47, s22
	s_cselect_b64 s[34:35], -1, 0
	s_bfe_u32 s22, s2, 0x30003
	s_ashr_i32 s2, s2, 6
	s_ashr_i32 s3, s2, 31
	s_mov_b64 s[38:39], s[4:5]
	s_lshl_b64 s[4:5], s[2:3], 21
	s_mov_b64 s[36:37], s[8:9]
	s_add_u32 s8, s10, s4
	s_addc_u32 s9, s11, s5
	s_and_b64 s[4:5], s[34:35], exec
	s_cselect_b32 s3, s9, s37
	s_cselect_b32 s49, s8, s36
	s_lshl_b32 s4, s22, 21
	s_add_u32 s4, s1, s4
	s_addc_u32 s5, s7, 0
	s_and_b64 s[40:41], s[34:35], exec
	s_cselect_b32 s50, s5, s39
	s_cselect_b32 s51, s4, s38
	s_add_u32 s36, s36, 0x100080
	s_addc_u32 s37, s37, 0
	s_add_u32 s52, s38, 0x100
	v_mov_b32_e32 v4, 0
	s_addc_u32 s53, s39, 0
	s_mov_b32 s54, -2
	v_mov_b32_e32 v5, v4
	v_mov_b32_e32 v6, v4
	v_mov_b32_e32 v7, v4
	v_mov_b32_e32 v8, v4
	v_mov_b32_e32 v9, v4
	v_mov_b32_e32 v10, v4
	v_mov_b32_e32 v11, v4
	v_mov_b32_e32 v12, v4
	v_mov_b32_e32 v13, v4
	v_mov_b32_e32 v14, v4
	v_mov_b32_e32 v15, v4
	v_mov_b32_e32 v16, v4
	v_mov_b32_e32 v17, v4
	v_mov_b32_e32 v18, v4
	v_mov_b32_e32 v19, v4
	v_mov_b32_e32 v28, v4
	v_mov_b32_e32 v29, v4
	v_mov_b32_e32 v30, v4
	v_mov_b32_e32 v31, v4
	v_mov_b32_e32 v32, v4
	v_mov_b32_e32 v33, v4
	v_mov_b32_e32 v34, v4
	v_mov_b32_e32 v35, v4
	v_mov_b32_e32 v44, v4
	v_mov_b32_e32 v45, v4
	v_mov_b32_e32 v46, v4
	v_mov_b32_e32 v47, v4
	v_mov_b32_e32 v48, v4
	v_mov_b32_e32 v49, v4
	v_mov_b32_e32 v50, v4
	v_mov_b32_e32 v51, v4
	v_mov_b32_e32 v20, v4
	v_mov_b32_e32 v21, v4
	v_mov_b32_e32 v22, v4
	v_mov_b32_e32 v23, v4
	v_mov_b32_e32 v24, v4
	v_mov_b32_e32 v25, v4
	v_mov_b32_e32 v26, v4
	v_mov_b32_e32 v27, v4
	v_mov_b32_e32 v36, v4
	v_mov_b32_e32 v37, v4
	v_mov_b32_e32 v38, v4
	v_mov_b32_e32 v39, v4
	v_mov_b32_e32 v40, v4
	v_mov_b32_e32 v41, v4
	v_mov_b32_e32 v42, v4
	v_mov_b32_e32 v43, v4
	v_mov_b32_e32 v52, v4
	v_mov_b32_e32 v53, v4
	v_mov_b32_e32 v54, v4
	v_mov_b32_e32 v55, v4
	v_mov_b32_e32 v56, v4
	v_mov_b32_e32 v57, v4
	v_mov_b32_e32 v58, v4
	v_mov_b32_e32 v59, v4
	v_mov_b32_e32 v60, v4
	v_mov_b32_e32 v61, v4
	v_mov_b32_e32 v62, v4
	v_mov_b32_e32 v63, v4
	v_mov_b32_e32 v64, v4
	v_mov_b32_e32 v65, v4
	v_mov_b32_e32 v66, v4
	v_mov_b32_e32 v67, v4
	v_mov_b32_e32 v68, v4
	v_mov_b32_e32 v69, v4
	v_mov_b32_e32 v70, v4
	v_mov_b32_e32 v71, v4
	v_mov_b32_e32 v72, v4
	v_mov_b32_e32 v73, v4
	v_mov_b32_e32 v74, v4
	v_mov_b32_e32 v75, v4
	v_mov_b32_e32 v76, v4
	v_mov_b32_e32 v77, v4
	v_mov_b32_e32 v78, v4
	v_mov_b32_e32 v79, v4
	v_mov_b32_e32 v80, v4
	v_mov_b32_e32 v81, v4
	v_mov_b32_e32 v82, v4
	v_mov_b32_e32 v83, v4
	v_mov_b32_e32 v88, v4
	v_mov_b32_e32 v89, v4
	v_mov_b32_e32 v90, v4
	v_mov_b32_e32 v91, v4
	v_mov_b32_e32 v96, v4
	v_mov_b32_e32 v97, v4
	v_mov_b32_e32 v98, v4
	v_mov_b32_e32 v99, v4
	v_mov_b32_e32 v104, v4
	v_mov_b32_e32 v105, v4
	v_mov_b32_e32 v106, v4
	v_mov_b32_e32 v107, v4
	v_mov_b32_e32 v112, v4
	v_mov_b32_e32 v113, v4
	v_mov_b32_e32 v114, v4
	v_mov_b32_e32 v115, v4
	v_mov_b32_e32 v84, v4
	v_mov_b32_e32 v85, v4
	v_mov_b32_e32 v86, v4
	v_mov_b32_e32 v87, v4
	v_mov_b32_e32 v92, v4
	v_mov_b32_e32 v93, v4
	v_mov_b32_e32 v94, v4
	v_mov_b32_e32 v95, v4
	v_mov_b32_e32 v100, v4
	v_mov_b32_e32 v101, v4
	v_mov_b32_e32 v102, v4
	v_mov_b32_e32 v103, v4
	v_mov_b32_e32 v108, v4
	v_mov_b32_e32 v109, v4
	v_mov_b32_e32 v110, v4
	v_mov_b32_e32 v111, v4
	v_mov_b32_e32 v116, v4
	v_mov_b32_e32 v117, v4
	v_mov_b32_e32 v118, v4
	v_mov_b32_e32 v119, v4
	v_mov_b32_e32 v120, v4
	v_mov_b32_e32 v121, v4
	v_mov_b32_e32 v122, v4
	v_mov_b32_e32 v123, v4
	v_mov_b32_e32 v124, v4
	v_mov_b32_e32 v125, v4
	v_mov_b32_e32 v126, v4
	v_mov_b32_e32 v127, v4
	v_mov_b32_e32 v128, v4
	v_mov_b32_e32 v129, v4
	v_mov_b32_e32 v130, v4
	v_mov_b32_e32 v131, v4
	s_cmp_lg_u64 s[28:29], 0
	s_cbranch_scc1 .Lsp_g762
	s_setprio 1
.Lsp_g762:
.LBB0_762:
	s_add_u32 s38, s36, 0xfff00080
	s_addc_u32 s39, s37, -1
	s_add_i32 s55, 0, 0x10000
	s_cmp_eq_u32 s54, 4
	s_cselect_b32 s41, s3, s39
	s_cselect_b32 s40, s49, s38
	v_add_u32_e32 v2, s55, v140
	s_cselect_b32 s39, s50, s53
	s_cselect_b32 s38, s51, s52
	s_add_i32 s58, 0, 0x14000
	ds_read_b128 v[144:147], v2
	ds_read_b128 v[148:151], v2 offset:1024
	ds_read_b128 v[152:155], v2 offset:2048
	ds_read_b128 v[156:159], v2 offset:3072
	v_add_u32_e32 v2, s58, v140
	ds_read_b128 v[160:163], v2
	ds_read_b128 v[164:167], v2 offset:1024
	ds_read_b128 v[178:181], v2 offset:2048
	ds_read_b128 v[182:185], v2 offset:3072
	v_lshl_add_u64 v[168:169], s[36:37], 0, v[136:137]
	s_add_i32 m0, s33, 0xc000
	ds_read_b128 v[186:189], v142
	ds_read_b128 v[190:193], v142 offset:1024
	ds_read_b128 v[194:197], v142 offset:2048
	ds_read_b128 v[208:211], v142 offset:3072
	ds_read_b128 v[212:215], v142 offset:4096
	ds_read_b128 v[216:219], v142 offset:5120
	ds_read_b128 v[220:223], v142 offset:6144
	ds_read_b128 v[224:227], v142 offset:7168
	global_load_lds_dwordx4 v[168:169], off
	v_lshl_add_u64 v[168:169], s[36:37], 0, v[138:139]
	s_add_i32 m0, s33, 0xe000
	s_nop 0
	global_load_lds_dwordx4 v[168:169], off
	s_waitcnt vmcnt(8)
	s_waitcnt lgkmcnt(0)
	s_barrier
	s_waitcnt lgkmcnt(0)
	v_mfma_f32_16x16x32_bf16 v[128:131], v[144:147], v[186:189], v[128:131]
	v_mfma_f32_16x16x32_bf16 v[128:131], v[148:151], v[190:193], v[128:131]
	v_mfma_f32_16x16x32_bf16 v[124:127], v[156:159], v[190:193], v[124:127]
	v_mfma_f32_16x16x32_bf16 v[124:127], v[152:155], v[186:189], v[124:127]
	v_mfma_f32_16x16x32_bf16 v[116:119], v[152:155], v[194:197], v[116:119]
	v_mfma_f32_16x16x32_bf16 v[116:119], v[156:159], v[208:211], v[116:119]
	v_mfma_f32_16x16x32_bf16 v[120:123], v[148:151], v[208:211], v[120:123]
	v_mfma_f32_16x16x32_bf16 v[120:123], v[144:147], v[194:197], v[120:123]
	v_mfma_f32_16x16x32_bf16 v[108:111], v[144:147], v[212:215], v[108:111]
	v_mfma_f32_16x16x32_bf16 v[108:111], v[148:151], v[216:219], v[108:111]
	v_mfma_f32_16x16x32_bf16 v[100:103], v[156:159], v[216:219], v[100:103]
	v_mfma_f32_16x16x32_bf16 v[100:103], v[152:155], v[212:215], v[100:103]
	v_mfma_f32_16x16x32_bf16 v[84:87], v[152:155], v[220:223], v[84:87]
	v_mfma_f32_16x16x32_bf16 v[84:87], v[156:159], v[224:227], v[84:87]
	v_mfma_f32_16x16x32_bf16 v[92:95], v[148:151], v[224:227], v[92:95]
	v_mfma_f32_16x16x32_bf16 v[92:95], v[144:147], v[220:223], v[92:95]
	v_mfma_f32_16x16x32_bf16 v[112:115], v[160:163], v[186:189], v[112:115]
	v_mfma_f32_16x16x32_bf16 v[112:115], v[164:167], v[190:193], v[112:115]
	v_mfma_f32_16x16x32_bf16 v[104:107], v[182:185], v[190:193], v[104:107]
	v_mfma_f32_16x16x32_bf16 v[104:107], v[178:181], v[186:189], v[104:107]
	v_mfma_f32_16x16x32_bf16 v[88:91], v[178:181], v[194:197], v[88:91]
	v_mfma_f32_16x16x32_bf16 v[88:91], v[182:185], v[208:211], v[88:91]
	v_mfma_f32_16x16x32_bf16 v[96:99], v[164:167], v[208:211], v[96:99]
	v_mfma_f32_16x16x32_bf16 v[96:99], v[160:163], v[194:197], v[96:99]
	v_mfma_f32_16x16x32_bf16 v[80:83], v[160:163], v[212:215], v[80:83]
	v_mfma_f32_16x16x32_bf16 v[80:83], v[164:167], v[216:219], v[80:83]
	v_mfma_f32_16x16x32_bf16 v[76:79], v[182:185], v[216:219], v[76:79]
	v_mfma_f32_16x16x32_bf16 v[76:79], v[178:181], v[212:215], v[76:79]
	v_mfma_f32_16x16x32_bf16 v[68:71], v[178:181], v[220:223], v[68:71]
	v_mfma_f32_16x16x32_bf16 v[68:71], v[182:185], v[224:227], v[68:71]
	v_mfma_f32_16x16x32_bf16 v[72:75], v[164:167], v[224:227], v[72:75]
	v_mfma_f32_16x16x32_bf16 v[72:75], v[160:163], v[220:223], v[72:75]
	s_barrier
	s_add_i32 s55, s55, s21
	v_lshl_add_u64 v[168:169], s[38:39], 0, v[134:135]
	s_mov_b32 m0, s55
	ds_read_b128 v[186:189], v142 offset:16384
	ds_read_b128 v[190:193], v142 offset:17408
	ds_read_b128 v[194:197], v142 offset:18432
	ds_read_b128 v[208:211], v142 offset:19456
	ds_read_b128 v[212:215], v142 offset:20480
	ds_read_b128 v[216:219], v142 offset:21504
	ds_read_b128 v[220:223], v142 offset:22528
	ds_read_b128 v[224:227], v142 offset:23552
	global_load_lds_dwordx4 v[168:169], off
	s_add_i32 m0, s55, 0x2000
	s_add_u32 s56, s38, 0x100000
	v_lshl_add_u64 v[228:229], s[38:39], 0, v[132:133]
	s_addc_u32 s57, s39, 0
	s_add_i32 s55, s58, s21
	global_load_lds_dwordx4 v[228:229], off
	v_lshl_add_u64 v[230:231], s[56:57], 0, v[134:135]
	s_mov_b32 m0, s55
	v_lshl_add_u64 v[232:233], s[40:41], 0, v[132:133]
	global_load_lds_dwordx4 v[230:231], off
	v_lshl_add_u64 v[230:231], s[56:57], 0, v[132:133]
	s_add_i32 m0, s55, 0x2000
	s_nop 0
	global_load_lds_dwordx4 v[230:231], off
	v_lshl_add_u64 v[230:231], s[40:41], 0, v[134:135]
	s_mov_b32 m0, s33
	s_nop 0
	global_load_lds_dwordx4 v[230:231], off
	s_mov_b32 m0, s42
	s_nop 0
	global_load_lds_dwordx4 v[232:233], off
	s_waitcnt vmcnt(8)
	s_waitcnt lgkmcnt(0)
	s_barrier
	s_waitcnt lgkmcnt(0)
	v_mfma_f32_16x16x32_bf16 v[64:67], v[144:147], v[186:189], v[64:67]
	v_mfma_f32_16x16x32_bf16 v[64:67], v[148:151], v[190:193], v[64:67]
	v_mfma_f32_16x16x32_bf16 v[60:63], v[156:159], v[190:193], v[60:63]
	v_mfma_f32_16x16x32_bf16 v[60:63], v[152:155], v[186:189], v[60:63]
	v_mfma_f32_16x16x32_bf16 v[52:55], v[152:155], v[194:197], v[52:55]
	v_mfma_f32_16x16x32_bf16 v[52:55], v[156:159], v[208:211], v[52:55]
	v_mfma_f32_16x16x32_bf16 v[56:59], v[148:151], v[208:211], v[56:59]
	v_mfma_f32_16x16x32_bf16 v[56:59], v[144:147], v[194:197], v[56:59]
	v_mfma_f32_16x16x32_bf16 v[40:43], v[144:147], v[212:215], v[40:43]
	v_mfma_f32_16x16x32_bf16 v[40:43], v[148:151], v[216:219], v[40:43]
	v_mfma_f32_16x16x32_bf16 v[36:39], v[156:159], v[216:219], v[36:39]
	v_mfma_f32_16x16x32_bf16 v[36:39], v[152:155], v[212:215], v[36:39]
	v_mfma_f32_16x16x32_bf16 v[20:23], v[152:155], v[220:223], v[20:23]
	v_mfma_f32_16x16x32_bf16 v[20:23], v[156:159], v[224:227], v[20:23]
	v_mfma_f32_16x16x32_bf16 v[24:27], v[148:151], v[224:227], v[24:27]
	v_mfma_f32_16x16x32_bf16 v[24:27], v[144:147], v[220:223], v[24:27]
	v_mfma_f32_16x16x32_bf16 v[48:51], v[160:163], v[186:189], v[48:51]
	v_mfma_f32_16x16x32_bf16 v[48:51], v[164:167], v[190:193], v[48:51]
	v_mfma_f32_16x16x32_bf16 v[44:47], v[182:185], v[190:193], v[44:47]
	v_mfma_f32_16x16x32_bf16 v[44:47], v[178:181], v[186:189], v[44:47]
	v_mfma_f32_16x16x32_bf16 v[28:31], v[178:181], v[194:197], v[28:31]
	v_mfma_f32_16x16x32_bf16 v[28:31], v[182:185], v[208:211], v[28:31]
	v_mfma_f32_16x16x32_bf16 v[32:35], v[164:167], v[208:211], v[32:35]
	v_mfma_f32_16x16x32_bf16 v[32:35], v[160:163], v[194:197], v[32:35]
	v_mfma_f32_16x16x32_bf16 v[16:19], v[160:163], v[212:215], v[16:19]
	v_mfma_f32_16x16x32_bf16 v[16:19], v[164:167], v[216:219], v[16:19]
	v_mfma_f32_16x16x32_bf16 v[12:15], v[182:185], v[216:219], v[12:15]
	v_mfma_f32_16x16x32_bf16 v[12:15], v[178:181], v[212:215], v[12:15]
	v_mfma_f32_16x16x32_bf16 v[4:7], v[178:181], v[220:223], v[4:7]
	v_mfma_f32_16x16x32_bf16 v[4:7], v[182:185], v[224:227], v[4:7]
	v_mfma_f32_16x16x32_bf16 v[8:11], v[164:167], v[224:227], v[8:11]
	v_mfma_f32_16x16x32_bf16 v[8:11], v[160:163], v[220:223], v[8:11]
	s_barrier
	s_add_i32 s55, 0, 0x18000
	v_add_u32_e32 v2, s55, v140
	s_add_i32 s56, 0, 0x1c000
	ds_read_b128 v[144:147], v2
	ds_read_b128 v[148:151], v2 offset:1024
	ds_read_b128 v[152:155], v2 offset:2048
	ds_read_b128 v[156:159], v2 offset:3072
	v_add_u32_e32 v2, s56, v140
	ds_read_b128 v[160:163], v2
	ds_read_b128 v[164:167], v2 offset:1024
	ds_read_b128 v[178:181], v2 offset:2048
	ds_read_b128 v[182:185], v2 offset:3072
	s_add_u32 s40, s40, 0x100000
	s_addc_u32 s41, s41, 0
	s_mov_b32 m0, s43
	v_lshl_add_u64 v[234:235], s[40:41], 0, v[134:135]
	ds_read_b128 v[186:189], v142 offset:32768
	ds_read_b128 v[190:193], v142 offset:33792
	ds_read_b128 v[194:197], v142 offset:34816
	ds_read_b128 v[208:211], v142 offset:35840
	ds_read_b128 v[212:215], v142 offset:36864
	ds_read_b128 v[216:219], v142 offset:37888
	ds_read_b128 v[220:223], v142 offset:38912
	ds_read_b128 v[224:227], v142 offset:39936
	global_load_lds_dwordx4 v[234:235], off
	v_lshl_add_u64 v[234:235], s[40:41], 0, v[132:133]
	s_mov_b32 m0, s44
	s_nop 0
	global_load_lds_dwordx4 v[234:235], off
	s_waitcnt vmcnt(8)
	s_waitcnt lgkmcnt(0)
	s_barrier
	s_waitcnt lgkmcnt(0)
	v_mfma_f32_16x16x32_bf16 v[128:131], v[144:147], v[186:189], v[128:131]
	v_mfma_f32_16x16x32_bf16 v[128:131], v[148:151], v[190:193], v[128:131]
	v_mfma_f32_16x16x32_bf16 v[124:127], v[156:159], v[190:193], v[124:127]
	v_mfma_f32_16x16x32_bf16 v[124:127], v[152:155], v[186:189], v[124:127]
	v_mfma_f32_16x16x32_bf16 v[116:119], v[152:155], v[194:197], v[116:119]
	v_mfma_f32_16x16x32_bf16 v[116:119], v[156:159], v[208:211], v[116:119]
	v_mfma_f32_16x16x32_bf16 v[120:123], v[148:151], v[208:211], v[120:123]
	v_mfma_f32_16x16x32_bf16 v[120:123], v[144:147], v[194:197], v[120:123]
	v_mfma_f32_16x16x32_bf16 v[108:111], v[144:147], v[212:215], v[108:111]
	v_mfma_f32_16x16x32_bf16 v[108:111], v[148:151], v[216:219], v[108:111]
	v_mfma_f32_16x16x32_bf16 v[100:103], v[156:159], v[216:219], v[100:103]
	v_mfma_f32_16x16x32_bf16 v[100:103], v[152:155], v[212:215], v[100:103]
	v_mfma_f32_16x16x32_bf16 v[84:87], v[152:155], v[220:223], v[84:87]
	v_mfma_f32_16x16x32_bf16 v[84:87], v[156:159], v[224:227], v[84:87]
	v_mfma_f32_16x16x32_bf16 v[92:95], v[148:151], v[224:227], v[92:95]
	v_mfma_f32_16x16x32_bf16 v[92:95], v[144:147], v[220:223], v[92:95]
	v_mfma_f32_16x16x32_bf16 v[112:115], v[160:163], v[186:189], v[112:115]
	v_mfma_f32_16x16x32_bf16 v[112:115], v[164:167], v[190:193], v[112:115]
	v_mfma_f32_16x16x32_bf16 v[104:107], v[182:185], v[190:193], v[104:107]
	v_mfma_f32_16x16x32_bf16 v[104:107], v[178:181], v[186:189], v[104:107]
	v_mfma_f32_16x16x32_bf16 v[88:91], v[178:181], v[194:197], v[88:91]
	v_mfma_f32_16x16x32_bf16 v[88:91], v[182:185], v[208:211], v[88:91]
	v_mfma_f32_16x16x32_bf16 v[96:99], v[164:167], v[208:211], v[96:99]
	v_mfma_f32_16x16x32_bf16 v[96:99], v[160:163], v[194:197], v[96:99]
	v_mfma_f32_16x16x32_bf16 v[80:83], v[160:163], v[212:215], v[80:83]
	v_mfma_f32_16x16x32_bf16 v[80:83], v[164:167], v[216:219], v[80:83]
	v_mfma_f32_16x16x32_bf16 v[76:79], v[182:185], v[216:219], v[76:79]
	v_mfma_f32_16x16x32_bf16 v[76:79], v[178:181], v[212:215], v[76:79]
	v_mfma_f32_16x16x32_bf16 v[68:71], v[178:181], v[220:223], v[68:71]
	v_mfma_f32_16x16x32_bf16 v[68:71], v[182:185], v[224:227], v[68:71]
	v_mfma_f32_16x16x32_bf16 v[72:75], v[164:167], v[224:227], v[72:75]
	v_mfma_f32_16x16x32_bf16 v[72:75], v[160:163], v[220:223], v[72:75]
	s_barrier
	s_add_i32 s40, s55, s21
	v_lshl_add_u64 v[168:169], v[168:169], 0, s[18:19]
	s_mov_b32 m0, s40
	ds_read_b128 v[186:189], v142 offset:49152
	ds_read_b128 v[190:193], v142 offset:50176
	ds_read_b128 v[194:197], v142 offset:51200
	ds_read_b128 v[208:211], v142 offset:52224
	ds_read_b128 v[212:215], v142 offset:53248
	ds_read_b128 v[216:219], v142 offset:54272
	ds_read_b128 v[220:223], v142 offset:55296
	ds_read_b128 v[224:227], v142 offset:56320
	global_load_lds_dwordx4 v[168:169], off
	s_add_i32 m0, s40, 0x2000
	s_add_u32 s38, s38, 0x100080
	v_lshl_add_u64 v[168:169], v[228:229], 0, s[18:19]
	s_addc_u32 s39, s39, 0
	s_add_i32 s40, s56, s21
	global_load_lds_dwordx4 v[168:169], off
	v_lshl_add_u64 v[168:169], s[38:39], 0, v[134:135]
	s_mov_b32 m0, s40
	s_nop 0
	global_load_lds_dwordx4 v[168:169], off
	v_lshl_add_u64 v[168:169], s[38:39], 0, v[132:133]
	s_add_i32 m0, s40, 0x2000
	s_nop 0
	global_load_lds_dwordx4 v[168:169], off
	v_lshl_add_u64 v[168:169], v[230:231], 0, s[18:19]
	s_mov_b32 m0, s25
	s_nop 0
	global_load_lds_dwordx4 v[168:169], off
	v_lshl_add_u64 v[168:169], v[232:233], 0, s[18:19]
	s_mov_b32 m0, s45
	s_nop 0
	global_load_lds_dwordx4 v[168:169], off
	s_waitcnt vmcnt(8)
	s_waitcnt lgkmcnt(0)
	s_barrier
	s_waitcnt lgkmcnt(0)
	v_mfma_f32_16x16x32_bf16 v[64:67], v[144:147], v[186:189], v[64:67]
	v_mfma_f32_16x16x32_bf16 v[64:67], v[148:151], v[190:193], v[64:67]
	v_mfma_f32_16x16x32_bf16 v[60:63], v[156:159], v[190:193], v[60:63]
	v_mfma_f32_16x16x32_bf16 v[60:63], v[152:155], v[186:189], v[60:63]
	v_mfma_f32_16x16x32_bf16 v[52:55], v[152:155], v[194:197], v[52:55]
	v_mfma_f32_16x16x32_bf16 v[52:55], v[156:159], v[208:211], v[52:55]
	v_mfma_f32_16x16x32_bf16 v[56:59], v[148:151], v[208:211], v[56:59]
	v_mfma_f32_16x16x32_bf16 v[56:59], v[144:147], v[194:197], v[56:59]
	v_mfma_f32_16x16x32_bf16 v[40:43], v[144:147], v[212:215], v[40:43]
	v_mfma_f32_16x16x32_bf16 v[40:43], v[148:151], v[216:219], v[40:43]
	v_mfma_f32_16x16x32_bf16 v[36:39], v[156:159], v[216:219], v[36:39]
	v_mfma_f32_16x16x32_bf16 v[36:39], v[152:155], v[212:215], v[36:39]
	v_mfma_f32_16x16x32_bf16 v[20:23], v[152:155], v[220:223], v[20:23]
	v_mfma_f32_16x16x32_bf16 v[20:23], v[156:159], v[224:227], v[20:23]
	v_mfma_f32_16x16x32_bf16 v[24:27], v[148:151], v[224:227], v[24:27]
	v_mfma_f32_16x16x32_bf16 v[24:27], v[144:147], v[220:223], v[24:27]
	v_mfma_f32_16x16x32_bf16 v[48:51], v[160:163], v[186:189], v[48:51]
	v_mfma_f32_16x16x32_bf16 v[48:51], v[164:167], v[190:193], v[48:51]
	v_mfma_f32_16x16x32_bf16 v[44:47], v[182:185], v[190:193], v[44:47]
	v_mfma_f32_16x16x32_bf16 v[44:47], v[178:181], v[186:189], v[44:47]
	v_mfma_f32_16x16x32_bf16 v[28:31], v[178:181], v[194:197], v[28:31]
	v_mfma_f32_16x16x32_bf16 v[28:31], v[182:185], v[208:211], v[28:31]
	v_mfma_f32_16x16x32_bf16 v[32:35], v[164:167], v[208:211], v[32:35]
	v_mfma_f32_16x16x32_bf16 v[32:35], v[160:163], v[194:197], v[32:35]
	v_mfma_f32_16x16x32_bf16 v[16:19], v[160:163], v[212:215], v[16:19]
	v_mfma_f32_16x16x32_bf16 v[16:19], v[164:167], v[216:219], v[16:19]
	v_mfma_f32_16x16x32_bf16 v[12:15], v[182:185], v[216:219], v[12:15]
	v_mfma_f32_16x16x32_bf16 v[12:15], v[178:181], v[212:215], v[12:15]
	v_mfma_f32_16x16x32_bf16 v[4:7], v[178:181], v[220:223], v[4:7]
	v_mfma_f32_16x16x32_bf16 v[4:7], v[182:185], v[224:227], v[4:7]
	v_mfma_f32_16x16x32_bf16 v[8:11], v[164:167], v[224:227], v[8:11]
	v_mfma_f32_16x16x32_bf16 v[8:11], v[160:163], v[220:223], v[8:11]
	s_barrier
	s_add_i32 s54, s54, 2
	s_add_u32 s36, s36, 0x100
	s_addc_u32 s37, s37, 0
	s_add_u32 s52, s52, 0x100
	s_addc_u32 s53, s53, 0
	s_cmp_gt_u32 s54, 5
	s_cbranch_scc0 .LBB0_762
	s_setprio 0
	s_and_b64 vcc, exec, s[28:29]
	s_cbranch_vccz .LBB0_765
	s_barrier

.LBB0_900:
	s_ashr_i32 s49, s48, 31
	s_lshl_b64 s[10:11], s[48:49], 20
	s_add_u32 s50, s34, s10
	s_addc_u32 s51, s35, s11
	s_and_b64 s[10:11], s[38:39], exec
	s_cselect_b32 s5, s51, s9
	s_cselect_b32 s7, s50, s8
	s_ashr_i32 s47, s46, 31
	s_lshl_b64 s[10:11], s[46:47], 20
	s_add_u32 s52, s37, s10
	s_addc_u32 s53, s54, s11
	s_and_b64 s[10:11], s[38:39], exec
	s_cselect_b32 s10, s53, s13
	s_cselect_b32 s11, s52, s12
	s_add_u32 s8, s8, 0x80080
	s_addc_u32 s9, s9, 0
	s_add_u32 s21, s12, 0x100
	v_mov_b32_e32 v4, 0
	s_addc_u32 s22, s13, 0
	s_mov_b32 s33, -2
	v_mov_b32_e32 v5, v4
	v_mov_b32_e32 v6, v4
	v_mov_b32_e32 v7, v4
	v_mov_b32_e32 v8, v4
	v_mov_b32_e32 v9, v4
	v_mov_b32_e32 v10, v4
	v_mov_b32_e32 v11, v4
	v_mov_b32_e32 v20, v4
	v_mov_b32_e32 v21, v4
	v_mov_b32_e32 v22, v4
	v_mov_b32_e32 v23, v4
	v_mov_b32_e32 v24, v4
	v_mov_b32_e32 v25, v4
	v_mov_b32_e32 v26, v4
	v_mov_b32_e32 v27, v4
	v_mov_b32_e32 v36, v4
	v_mov_b32_e32 v37, v4
	v_mov_b32_e32 v38, v4
	v_mov_b32_e32 v39, v4
	v_mov_b32_e32 v40, v4
	v_mov_b32_e32 v41, v4
	v_mov_b32_e32 v42, v4
	v_mov_b32_e32 v43, v4
	v_mov_b32_e32 v52, v4
	v_mov_b32_e32 v53, v4
	v_mov_b32_e32 v54, v4
	v_mov_b32_e32 v55, v4
	v_mov_b32_e32 v56, v4
	v_mov_b32_e32 v57, v4
	v_mov_b32_e32 v58, v4
	v_mov_b32_e32 v59, v4
	v_mov_b32_e32 v12, v4
	v_mov_b32_e32 v13, v4
	v_mov_b32_e32 v14, v4
	v_mov_b32_e32 v15, v4
	v_mov_b32_e32 v16, v4
	v_mov_b32_e32 v17, v4
	v_mov_b32_e32 v18, v4
	v_mov_b32_e32 v19, v4
	v_mov_b32_e32 v28, v4
	v_mov_b32_e32 v29, v4
	v_mov_b32_e32 v30, v4
	v_mov_b32_e32 v31, v4
	v_mov_b32_e32 v32, v4
	v_mov_b32_e32 v33, v4
	v_mov_b32_e32 v34, v4
	v_mov_b32_e32 v35, v4
	v_mov_b32_e32 v44, v4
	v_mov_b32_e32 v45, v4
	v_mov_b32_e32 v46, v4
	v_mov_b32_e32 v47, v4
	v_mov_b32_e32 v48, v4
	v_mov_b32_e32 v49, v4
	v_mov_b32_e32 v50, v4
	v_mov_b32_e32 v51, v4
	v_mov_b32_e32 v60, v4
	v_mov_b32_e32 v61, v4
	v_mov_b32_e32 v62, v4
	v_mov_b32_e32 v63, v4
	v_mov_b32_e32 v64, v4
	v_mov_b32_e32 v65, v4
	v_mov_b32_e32 v66, v4
	v_mov_b32_e32 v67, v4
	v_mov_b32_e32 v68, v4
	v_mov_b32_e32 v69, v4
	v_mov_b32_e32 v70, v4
	v_mov_b32_e32 v71, v4
	v_mov_b32_e32 v72, v4
	v_mov_b32_e32 v73, v4
	v_mov_b32_e32 v74, v4
	v_mov_b32_e32 v75, v4
	v_mov_b32_e32 v84, v4
	v_mov_b32_e32 v85, v4
	v_mov_b32_e32 v86, v4
	v_mov_b32_e32 v87, v4
	v_mov_b32_e32 v88, v4
	v_mov_b32_e32 v89, v4
	v_mov_b32_e32 v90, v4
	v_mov_b32_e32 v91, v4
	v_mov_b32_e32 v100, v4
	v_mov_b32_e32 v101, v4
	v_mov_b32_e32 v102, v4
	v_mov_b32_e32 v103, v4
	v_mov_b32_e32 v104, v4
	v_mov_b32_e32 v105, v4
	v_mov_b32_e32 v106, v4
	v_mov_b32_e32 v107, v4
	v_mov_b32_e32 v116, v4
	v_mov_b32_e32 v117, v4
	v_mov_b32_e32 v118, v4
	v_mov_b32_e32 v119, v4
	v_mov_b32_e32 v120, v4
	v_mov_b32_e32 v121, v4
	v_mov_b32_e32 v122, v4
	v_mov_b32_e32 v123, v4
	v_mov_b32_e32 v76, v4
	v_mov_b32_e32 v77, v4
	v_mov_b32_e32 v78, v4
	v_mov_b32_e32 v79, v4
	v_mov_b32_e32 v80, v4
	v_mov_b32_e32 v81, v4
	v_mov_b32_e32 v82, v4
	v_mov_b32_e32 v83, v4
	v_mov_b32_e32 v92, v4
	v_mov_b32_e32 v93, v4
	v_mov_b32_e32 v94, v4
	v_mov_b32_e32 v95, v4
	v_mov_b32_e32 v96, v4
	v_mov_b32_e32 v97, v4
	v_mov_b32_e32 v98, v4
	v_mov_b32_e32 v99, v4
	v_mov_b32_e32 v108, v4
	v_mov_b32_e32 v109, v4
	v_mov_b32_e32 v110, v4
	v_mov_b32_e32 v111, v4
	v_mov_b32_e32 v112, v4
	v_mov_b32_e32 v113, v4
	v_mov_b32_e32 v114, v4
	v_mov_b32_e32 v115, v4
	v_mov_b32_e32 v124, v4
	v_mov_b32_e32 v125, v4
	v_mov_b32_e32 v126, v4
	v_mov_b32_e32 v127, v4
	v_mov_b32_e32 v128, v4
	v_mov_b32_e32 v129, v4
	v_mov_b32_e32 v130, v4
	v_mov_b32_e32 v131, v4
	v_lshl_add_u32 v148, s4, 8, v150
	v_ashrrev_i32_e32 v149, 31, v148
	v_lshl_add_u64 v[144:145], v[148:149], 2, s[40:41]
	global_load_dword v244, v[144:145], off
	global_load_dword v245, v[144:145], off offset:64
	global_load_dword v246, v[144:145], off offset:128
	global_load_dword v247, v[144:145], off offset:192
	global_load_dword v248, v[144:145], off offset:512
	global_load_dword v249, v[144:145], off offset:576
	global_load_dword v250, v[144:145], off offset:640
	global_load_dword v251, v[144:145], off offset:704
	s_cmp_lg_u64 s[44:45], 0
	s_cbranch_scc1 .Lsp_g901
	s_setprio 1
.Lsp_g901:
.LBB0_901:
	s_add_u32 s12, s8, 0xfff80080
	s_addc_u32 s13, s9, -1
	s_add_i32 s47, 0, 0x10000
	s_cmp_eq_u32 s33, 28
	s_cselect_b32 s27, s5, s13
	s_cselect_b32 s26, s7, s12
	s_cselect_b32 s13, s10, s22
	s_cselect_b32 s12, s11, s21
	s_add_i32 s49, 0, 0x14000
	v_add_u32_e32 v158, s47, v151
	v_add_u32_e32 v182, s49, v151
	ds_read_b128 v[142:145], v158
	ds_read_b128 v[146:149], v158 offset:1024
	ds_read_b128 v[154:157], v158 offset:2048
	ds_read_b128 v[158:161], v158 offset:3072
	ds_read_b128 v[162:165], v182
	ds_read_b128 v[166:169], v182 offset:1024
	ds_read_b128 v[178:181], v182 offset:2048
	ds_read_b128 v[182:185], v182 offset:3072
	v_lshl_add_u64 v[228:229], s[8:9], 0, v[138:139]
	s_add_i32 m0, s57, 0xc000
	ds_read_b128 v[186:189], v153
	ds_read_b128 v[190:193], v153 offset:1024
	ds_read_b128 v[194:197], v153 offset:2048
	ds_read_b128 v[208:211], v153 offset:3072
	ds_read_b128 v[212:215], v153 offset:4096
	ds_read_b128 v[216:219], v153 offset:5120
	ds_read_b128 v[220:223], v153 offset:6144
	ds_read_b128 v[224:227], v153 offset:7168
	global_load_lds_dwordx4 v[228:229], off
	v_lshl_add_u64 v[228:229], s[8:9], 0, v[140:141]
	s_add_i32 m0, s57, 0xe000
	s_nop 0
	global_load_lds_dwordx4 v[228:229], off
	s_waitcnt vmcnt(8)
	s_waitcnt lgkmcnt(0)
	s_barrier
	s_waitcnt lgkmcnt(0)
	v_mfma_f32_16x16x32_bf16 v[128:131], v[142:145], v[186:189], v[128:131]
	v_mfma_f32_16x16x32_bf16 v[128:131], v[146:149], v[190:193], v[128:131]
	v_mfma_f32_16x16x32_bf16 v[124:127], v[158:161], v[190:193], v[124:127]
	v_mfma_f32_16x16x32_bf16 v[124:127], v[154:157], v[186:189], v[124:127]
	v_mfma_f32_16x16x32_bf16 v[108:111], v[154:157], v[194:197], v[108:111]
	v_mfma_f32_16x16x32_bf16 v[108:111], v[158:161], v[208:211], v[108:111]
	v_mfma_f32_16x16x32_bf16 v[112:115], v[146:149], v[208:211], v[112:115]
	v_mfma_f32_16x16x32_bf16 v[112:115], v[142:145], v[194:197], v[112:115]
	v_mfma_f32_16x16x32_bf16 v[96:99], v[142:145], v[212:215], v[96:99]
	v_mfma_f32_16x16x32_bf16 v[96:99], v[146:149], v[216:219], v[96:99]
	v_mfma_f32_16x16x32_bf16 v[92:95], v[158:161], v[216:219], v[92:95]
	v_mfma_f32_16x16x32_bf16 v[92:95], v[154:157], v[212:215], v[92:95]
	v_mfma_f32_16x16x32_bf16 v[76:79], v[154:157], v[220:223], v[76:79]
	v_mfma_f32_16x16x32_bf16 v[76:79], v[158:161], v[224:227], v[76:79]
	v_mfma_f32_16x16x32_bf16 v[80:83], v[146:149], v[224:227], v[80:83]
	v_mfma_f32_16x16x32_bf16 v[80:83], v[142:145], v[220:223], v[80:83]
	v_mfma_f32_16x16x32_bf16 v[120:123], v[162:165], v[186:189], v[120:123]
	v_mfma_f32_16x16x32_bf16 v[120:123], v[166:169], v[190:193], v[120:123]
	v_mfma_f32_16x16x32_bf16 v[116:119], v[182:185], v[190:193], v[116:119]
	v_mfma_f32_16x16x32_bf16 v[116:119], v[178:181], v[186:189], v[116:119]
	v_mfma_f32_16x16x32_bf16 v[100:103], v[178:181], v[194:197], v[100:103]
	v_mfma_f32_16x16x32_bf16 v[100:103], v[182:185], v[208:211], v[100:103]
	v_mfma_f32_16x16x32_bf16 v[104:107], v[166:169], v[208:211], v[104:107]
	v_mfma_f32_16x16x32_bf16 v[104:107], v[162:165], v[194:197], v[104:107]
	v_mfma_f32_16x16x32_bf16 v[88:91], v[162:165], v[212:215], v[88:91]
	v_mfma_f32_16x16x32_bf16 v[88:91], v[166:169], v[216:219], v[88:91]
	v_mfma_f32_16x16x32_bf16 v[84:87], v[182:185], v[216:219], v[84:87]
	v_mfma_f32_16x16x32_bf16 v[84:87], v[178:181], v[212:215], v[84:87]
	v_mfma_f32_16x16x32_bf16 v[68:71], v[178:181], v[220:223], v[68:71]
	v_mfma_f32_16x16x32_bf16 v[68:71], v[182:185], v[224:227], v[68:71]
	v_mfma_f32_16x16x32_bf16 v[72:75], v[166:169], v[224:227], v[72:75]
	v_mfma_f32_16x16x32_bf16 v[72:75], v[162:165], v[220:223], v[72:75]
	s_barrier
	s_add_i32 s47, s47, s55
	v_lshl_add_u64 v[228:229], s[12:13], 0, v[2:3]
	s_mov_b32 m0, s47
	ds_read_b128 v[186:189], v153 offset:16384
	ds_read_b128 v[190:193], v153 offset:17408
	ds_read_b128 v[194:197], v153 offset:18432
	ds_read_b128 v[208:211], v153 offset:19456
	ds_read_b128 v[212:215], v153 offset:20480
	ds_read_b128 v[216:219], v153 offset:21504
	ds_read_b128 v[220:223], v153 offset:22528
	ds_read_b128 v[224:227], v153 offset:23552
	global_load_lds_dwordx4 v[228:229], off
	s_add_i32 m0, s47, 0x2000
	s_add_u32 s66, s12, 0x80000
	v_lshl_add_u64 v[230:231], s[12:13], 0, v[132:133]
	s_addc_u32 s67, s13, 0
	s_add_i32 s47, s49, s55
	global_load_lds_dwordx4 v[230:231], off
	v_lshl_add_u64 v[232:233], s[66:67], 0, v[2:3]
	s_mov_b32 m0, s47
	v_lshl_add_u64 v[234:235], s[26:27], 0, v[134:135]
	global_load_lds_dwordx4 v[232:233], off
	v_lshl_add_u64 v[232:233], s[66:67], 0, v[132:133]
	s_add_i32 m0, s47, 0x2000
	s_nop 0
	global_load_lds_dwordx4 v[232:233], off
	v_lshl_add_u64 v[232:233], s[26:27], 0, v[136:137]
	s_mov_b32 m0, s57
	s_nop 0
	global_load_lds_dwordx4 v[232:233], off
	s_mov_b32 m0, s58
	s_nop 0
	global_load_lds_dwordx4 v[234:235], off
	s_waitcnt vmcnt(8)
	s_waitcnt lgkmcnt(0)
	s_barrier
	s_waitcnt lgkmcnt(0)
	v_mfma_f32_16x16x32_bf16 v[64:67], v[142:145], v[186:189], v[64:67]
	v_mfma_f32_16x16x32_bf16 v[64:67], v[146:149], v[190:193], v[64:67]
	v_mfma_f32_16x16x32_bf16 v[60:63], v[158:161], v[190:193], v[60:63]
	v_mfma_f32_16x16x32_bf16 v[60:63], v[154:157], v[186:189], v[60:63]
	v_mfma_f32_16x16x32_bf16 v[44:47], v[154:157], v[194:197], v[44:47]
	v_mfma_f32_16x16x32_bf16 v[44:47], v[158:161], v[208:211], v[44:47]
	v_mfma_f32_16x16x32_bf16 v[48:51], v[146:149], v[208:211], v[48:51]
	v_mfma_f32_16x16x32_bf16 v[48:51], v[142:145], v[194:197], v[48:51]
	v_mfma_f32_16x16x32_bf16 v[32:35], v[142:145], v[212:215], v[32:35]
	v_mfma_f32_16x16x32_bf16 v[32:35], v[146:149], v[216:219], v[32:35]
	v_mfma_f32_16x16x32_bf16 v[28:31], v[158:161], v[216:219], v[28:31]
	v_mfma_f32_16x16x32_bf16 v[28:31], v[154:157], v[212:215], v[28:31]
	v_mfma_f32_16x16x32_bf16 v[12:15], v[154:157], v[220:223], v[12:15]
	v_mfma_f32_16x16x32_bf16 v[12:15], v[158:161], v[224:227], v[12:15]
	v_mfma_f32_16x16x32_bf16 v[16:19], v[146:149], v[224:227], v[16:19]
	v_mfma_f32_16x16x32_bf16 v[16:19], v[142:145], v[220:223], v[16:19]
	v_mfma_f32_16x16x32_bf16 v[56:59], v[162:165], v[186:189], v[56:59]
	v_mfma_f32_16x16x32_bf16 v[56:59], v[166:169], v[190:193], v[56:59]
	v_mfma_f32_16x16x32_bf16 v[52:55], v[182:185], v[190:193], v[52:55]
	v_mfma_f32_16x16x32_bf16 v[52:55], v[178:181], v[186:189], v[52:55]
	v_mfma_f32_16x16x32_bf16 v[36:39], v[178:181], v[194:197], v[36:39]
	v_mfma_f32_16x16x32_bf16 v[36:39], v[182:185], v[208:211], v[36:39]
	v_mfma_f32_16x16x32_bf16 v[40:43], v[166:169], v[208:211], v[40:43]
	v_mfma_f32_16x16x32_bf16 v[40:43], v[162:165], v[194:197], v[40:43]
	v_mfma_f32_16x16x32_bf16 v[24:27], v[162:165], v[212:215], v[24:27]
	v_mfma_f32_16x16x32_bf16 v[24:27], v[166:169], v[216:219], v[24:27]
	v_mfma_f32_16x16x32_bf16 v[20:23], v[182:185], v[216:219], v[20:23]
	v_mfma_f32_16x16x32_bf16 v[20:23], v[178:181], v[212:215], v[20:23]
	v_mfma_f32_16x16x32_bf16 v[4:7], v[178:181], v[220:223], v[4:7]
	v_mfma_f32_16x16x32_bf16 v[4:7], v[182:185], v[224:227], v[4:7]
	v_mfma_f32_16x16x32_bf16 v[8:11], v[166:169], v[224:227], v[8:11]
	v_mfma_f32_16x16x32_bf16 v[8:11], v[162:165], v[220:223], v[8:11]
	s_barrier
	s_add_i32 s47, 0, 0x18000
	s_add_i32 s49, 0, 0x1c000
	v_add_u32_e32 v158, s47, v151
	v_add_u32_e32 v182, s49, v151
	ds_read_b128 v[142:145], v158
	ds_read_b128 v[146:149], v158 offset:1024
	ds_read_b128 v[154:157], v158 offset:2048
	ds_read_b128 v[158:161], v158 offset:3072
	ds_read_b128 v[162:165], v182
	ds_read_b128 v[166:169], v182 offset:1024
	ds_read_b128 v[178:181], v182 offset:2048
	ds_read_b128 v[182:185], v182 offset:3072
	s_add_u32 s26, s26, 0x80000
	s_addc_u32 s27, s27, 0
	s_mov_b32 m0, s59
	v_lshl_add_u64 v[236:237], s[26:27], 0, v[136:137]
	ds_read_b128 v[186:189], v153 offset:32768
	ds_read_b128 v[190:193], v153 offset:33792
	ds_read_b128 v[194:197], v153 offset:34816
	ds_read_b128 v[208:211], v153 offset:35840
	ds_read_b128 v[212:215], v153 offset:36864
	ds_read_b128 v[216:219], v153 offset:37888
	ds_read_b128 v[220:223], v153 offset:38912
	ds_read_b128 v[224:227], v153 offset:39936
	global_load_lds_dwordx4 v[236:237], off
	v_lshl_add_u64 v[236:237], s[26:27], 0, v[134:135]
	s_mov_b32 m0, s60
	s_nop 0
	global_load_lds_dwordx4 v[236:237], off
	s_waitcnt vmcnt(8)
	s_waitcnt lgkmcnt(0)
	s_barrier
	s_waitcnt lgkmcnt(0)
	v_mfma_f32_16x16x32_bf16 v[128:131], v[142:145], v[186:189], v[128:131]
	v_mfma_f32_16x16x32_bf16 v[128:131], v[146:149], v[190:193], v[128:131]
	v_mfma_f32_16x16x32_bf16 v[124:127], v[158:161], v[190:193], v[124:127]
	v_mfma_f32_16x16x32_bf16 v[124:127], v[154:157], v[186:189], v[124:127]
	v_mfma_f32_16x16x32_bf16 v[108:111], v[154:157], v[194:197], v[108:111]
	v_mfma_f32_16x16x32_bf16 v[108:111], v[158:161], v[208:211], v[108:111]
	v_mfma_f32_16x16x32_bf16 v[112:115], v[146:149], v[208:211], v[112:115]
	v_mfma_f32_16x16x32_bf16 v[112:115], v[142:145], v[194:197], v[112:115]
	v_mfma_f32_16x16x32_bf16 v[96:99], v[142:145], v[212:215], v[96:99]
	v_mfma_f32_16x16x32_bf16 v[96:99], v[146:149], v[216:219], v[96:99]
	v_mfma_f32_16x16x32_bf16 v[92:95], v[158:161], v[216:219], v[92:95]
	v_mfma_f32_16x16x32_bf16 v[92:95], v[154:157], v[212:215], v[92:95]
	v_mfma_f32_16x16x32_bf16 v[76:79], v[154:157], v[220:223], v[76:79]
	v_mfma_f32_16x16x32_bf16 v[76:79], v[158:161], v[224:227], v[76:79]
	v_mfma_f32_16x16x32_bf16 v[80:83], v[146:149], v[224:227], v[80:83]
	v_mfma_f32_16x16x32_bf16 v[80:83], v[142:145], v[220:223], v[80:83]
	v_mfma_f32_16x16x32_bf16 v[120:123], v[162:165], v[186:189], v[120:123]
	v_mfma_f32_16x16x32_bf16 v[120:123], v[166:169], v[190:193], v[120:123]
	v_mfma_f32_16x16x32_bf16 v[116:119], v[182:185], v[190:193], v[116:119]
	v_mfma_f32_16x16x32_bf16 v[116:119], v[178:181], v[186:189], v[116:119]
	v_mfma_f32_16x16x32_bf16 v[100:103], v[178:181], v[194:197], v[100:103]
	v_mfma_f32_16x16x32_bf16 v[100:103], v[182:185], v[208:211], v[100:103]
	v_mfma_f32_16x16x32_bf16 v[104:107], v[166:169], v[208:211], v[104:107]
	v_mfma_f32_16x16x32_bf16 v[104:107], v[162:165], v[194:197], v[104:107]
	v_mfma_f32_16x16x32_bf16 v[88:91], v[162:165], v[212:215], v[88:91]
	v_mfma_f32_16x16x32_bf16 v[88:91], v[166:169], v[216:219], v[88:91]
	v_mfma_f32_16x16x32_bf16 v[84:87], v[182:185], v[216:219], v[84:87]
	v_mfma_f32_16x16x32_bf16 v[84:87], v[178:181], v[212:215], v[84:87]
	v_mfma_f32_16x16x32_bf16 v[68:71], v[178:181], v[220:223], v[68:71]
	v_mfma_f32_16x16x32_bf16 v[68:71], v[182:185], v[224:227], v[68:71]
	v_mfma_f32_16x16x32_bf16 v[72:75], v[166:169], v[224:227], v[72:75]
	v_mfma_f32_16x16x32_bf16 v[72:75], v[162:165], v[220:223], v[72:75]
	s_barrier
	s_add_i32 s26, s47, s55
	v_lshl_add_u64 v[228:229], v[228:229], 0, s[18:19]
	s_mov_b32 m0, s26
	ds_read_b128 v[186:189], v153 offset:49152
	ds_read_b128 v[190:193], v153 offset:50176
	ds_read_b128 v[194:197], v153 offset:51200
	ds_read_b128 v[208:211], v153 offset:52224
	ds_read_b128 v[212:215], v153 offset:53248
	ds_read_b128 v[216:219], v153 offset:54272
	ds_read_b128 v[220:223], v153 offset:55296
	ds_read_b128 v[224:227], v153 offset:56320
	global_load_lds_dwordx4 v[228:229], off
	s_add_i32 m0, s26, 0x2000
	s_add_u32 s12, s12, 0x80080
	v_lshl_add_u64 v[228:229], v[230:231], 0, s[18:19]
	s_addc_u32 s13, s13, 0
	s_add_i32 s26, s49, s55
	global_load_lds_dwordx4 v[228:229], off
	v_lshl_add_u64 v[228:229], s[12:13], 0, v[2:3]
	s_mov_b32 m0, s26
	s_nop 0
	global_load_lds_dwordx4 v[228:229], off
	v_lshl_add_u64 v[228:229], s[12:13], 0, v[132:133]
	s_add_i32 m0, s26, 0x2000
	s_nop 0
	global_load_lds_dwordx4 v[228:229], off
	v_lshl_add_u64 v[228:229], v[232:233], 0, s[18:19]
	s_mov_b32 m0, s14
	s_nop 0
	global_load_lds_dwordx4 v[228:229], off
	v_lshl_add_u64 v[228:229], v[234:235], 0, s[18:19]
	s_mov_b32 m0, s61
	s_nop 0
	global_load_lds_dwordx4 v[228:229], off
	s_waitcnt vmcnt(8)
	s_waitcnt lgkmcnt(0)
	s_barrier
	s_waitcnt lgkmcnt(0)
	v_mfma_f32_16x16x32_bf16 v[64:67], v[142:145], v[186:189], v[64:67]
	v_mfma_f32_16x16x32_bf16 v[64:67], v[146:149], v[190:193], v[64:67]
	v_mfma_f32_16x16x32_bf16 v[60:63], v[158:161], v[190:193], v[60:63]
	v_mfma_f32_16x16x32_bf16 v[60:63], v[154:157], v[186:189], v[60:63]
	v_mfma_f32_16x16x32_bf16 v[44:47], v[154:157], v[194:197], v[44:47]
	v_mfma_f32_16x16x32_bf16 v[44:47], v[158:161], v[208:211], v[44:47]
	v_mfma_f32_16x16x32_bf16 v[48:51], v[146:149], v[208:211], v[48:51]
	v_mfma_f32_16x16x32_bf16 v[48:51], v[142:145], v[194:197], v[48:51]
	v_mfma_f32_16x16x32_bf16 v[32:35], v[142:145], v[212:215], v[32:35]
	v_mfma_f32_16x16x32_bf16 v[32:35], v[146:149], v[216:219], v[32:35]
	v_mfma_f32_16x16x32_bf16 v[28:31], v[158:161], v[216:219], v[28:31]
	v_mfma_f32_16x16x32_bf16 v[28:31], v[154:157], v[212:215], v[28:31]
	v_mfma_f32_16x16x32_bf16 v[12:15], v[154:157], v[220:223], v[12:15]
	v_mfma_f32_16x16x32_bf16 v[12:15], v[158:161], v[224:227], v[12:15]
	v_mfma_f32_16x16x32_bf16 v[16:19], v[146:149], v[224:227], v[16:19]
	v_mfma_f32_16x16x32_bf16 v[16:19], v[142:145], v[220:223], v[16:19]
	v_mfma_f32_16x16x32_bf16 v[56:59], v[162:165], v[186:189], v[56:59]
	v_mfma_f32_16x16x32_bf16 v[56:59], v[166:169], v[190:193], v[56:59]
	v_mfma_f32_16x16x32_bf16 v[52:55], v[182:185], v[190:193], v[52:55]
	v_mfma_f32_16x16x32_bf16 v[52:55], v[178:181], v[186:189], v[52:55]
	v_mfma_f32_16x16x32_bf16 v[36:39], v[178:181], v[194:197], v[36:39]
	v_mfma_f32_16x16x32_bf16 v[36:39], v[182:185], v[208:211], v[36:39]
	v_mfma_f32_16x16x32_bf16 v[40:43], v[166:169], v[208:211], v[40:43]
	v_mfma_f32_16x16x32_bf16 v[40:43], v[162:165], v[194:197], v[40:43]
	v_mfma_f32_16x16x32_bf16 v[24:27], v[162:165], v[212:215], v[24:27]
	v_mfma_f32_16x16x32_bf16 v[24:27], v[166:169], v[216:219], v[24:27]
	v_mfma_f32_16x16x32_bf16 v[20:23], v[182:185], v[216:219], v[20:23]
	v_mfma_f32_16x16x32_bf16 v[20:23], v[178:181], v[212:215], v[20:23]
	v_mfma_f32_16x16x32_bf16 v[4:7], v[178:181], v[220:223], v[4:7]
	v_mfma_f32_16x16x32_bf16 v[4:7], v[182:185], v[224:227], v[4:7]
	v_mfma_f32_16x16x32_bf16 v[8:11], v[166:169], v[224:227], v[8:11]
	v_mfma_f32_16x16x32_bf16 v[8:11], v[162:165], v[220:223], v[8:11]
	s_barrier
	s_add_i32 s33, s33, 2
	s_add_u32 s8, s8, 0x100
	s_addc_u32 s9, s9, 0
	s_add_u32 s21, s21, 0x100
	s_addc_u32 s22, s22, 0
	s_cmp_gt_u32 s33, 29
	s_cbranch_scc0 .LBB0_901
	s_setprio 0
	s_and_b64 vcc, exec, s[44:45]
	s_cbranch_vccz .LBB0_904
	s_barrier

.LBB0_1073:
	s_ashr_i32 s27, s26, 31
	s_lshl_b64 s[34:35], s[26:27], 22
	s_add_u32 s34, s22, s34
	s_addc_u32 s35, s25, s35
	s_and_b64 s[36:37], s[38:39], exec
	s_cselect_b32 s27, s35, s41
	s_cselect_b32 s54, s34, s40
	s_ashr_i32 s13, s12, 31
	s_lshl_b64 s[36:37], s[12:13], 22
	s_add_u32 s36, s10, s36
	s_addc_u32 s37, s11, s37
	s_and_b64 s[44:45], s[38:39], exec
	s_cselect_b32 s13, s37, s43
	s_cselect_b32 s55, s36, s42
	s_add_u32 s40, s40, 0x200080
	s_addc_u32 s41, s41, 0
	s_add_u32 s56, s42, 0x100
	v_mov_b32_e32 v4, 0
	s_addc_u32 s57, s43, 0
	s_mov_b32 s58, -2
	v_mov_b32_e32 v5, v4
	v_mov_b32_e32 v6, v4
	v_mov_b32_e32 v7, v4
	v_mov_b32_e32 v8, v4
	v_mov_b32_e32 v9, v4
	v_mov_b32_e32 v10, v4
	v_mov_b32_e32 v11, v4
	v_mov_b32_e32 v12, v4
	v_mov_b32_e32 v13, v4
	v_mov_b32_e32 v14, v4
	v_mov_b32_e32 v15, v4
	v_mov_b32_e32 v20, v4
	v_mov_b32_e32 v21, v4
	v_mov_b32_e32 v22, v4
	v_mov_b32_e32 v23, v4
	v_mov_b32_e32 v28, v4
	v_mov_b32_e32 v29, v4
	v_mov_b32_e32 v30, v4
	v_mov_b32_e32 v31, v4
	v_mov_b32_e32 v36, v4
	v_mov_b32_e32 v37, v4
	v_mov_b32_e32 v38, v4
	v_mov_b32_e32 v39, v4
	v_mov_b32_e32 v44, v4
	v_mov_b32_e32 v45, v4
	v_mov_b32_e32 v46, v4
	v_mov_b32_e32 v47, v4
	v_mov_b32_e32 v52, v4
	v_mov_b32_e32 v53, v4
	v_mov_b32_e32 v54, v4
	v_mov_b32_e32 v55, v4
	v_mov_b32_e32 v16, v4
	v_mov_b32_e32 v17, v4
	v_mov_b32_e32 v18, v4
	v_mov_b32_e32 v19, v4
	v_mov_b32_e32 v24, v4
	v_mov_b32_e32 v25, v4
	v_mov_b32_e32 v26, v4
	v_mov_b32_e32 v27, v4
	v_mov_b32_e32 v32, v4
	v_mov_b32_e32 v33, v4
	v_mov_b32_e32 v34, v4
	v_mov_b32_e32 v35, v4
	v_mov_b32_e32 v40, v4
	v_mov_b32_e32 v41, v4
	v_mov_b32_e32 v42, v4
	v_mov_b32_e32 v43, v4
	v_mov_b32_e32 v48, v4
	v_mov_b32_e32 v49, v4
	v_mov_b32_e32 v50, v4
	v_mov_b32_e32 v51, v4
	v_mov_b32_e32 v56, v4
	v_mov_b32_e32 v57, v4
	v_mov_b32_e32 v58, v4
	v_mov_b32_e32 v59, v4
	v_mov_b32_e32 v60, v4
	v_mov_b32_e32 v61, v4
	v_mov_b32_e32 v62, v4
	v_mov_b32_e32 v63, v4
	v_mov_b32_e32 v64, v4
	v_mov_b32_e32 v65, v4
	v_mov_b32_e32 v66, v4
	v_mov_b32_e32 v67, v4
	v_mov_b32_e32 v68, v4
	v_mov_b32_e32 v69, v4
	v_mov_b32_e32 v70, v4
	v_mov_b32_e32 v71, v4
	v_mov_b32_e32 v72, v4
	v_mov_b32_e32 v73, v4
	v_mov_b32_e32 v74, v4
	v_mov_b32_e32 v75, v4
	v_mov_b32_e32 v76, v4
	v_mov_b32_e32 v77, v4
	v_mov_b32_e32 v78, v4
	v_mov_b32_e32 v79, v4
	v_mov_b32_e32 v84, v4
	v_mov_b32_e32 v85, v4
	v_mov_b32_e32 v86, v4
	v_mov_b32_e32 v87, v4
	v_mov_b32_e32 v92, v4
	v_mov_b32_e32 v93, v4
	v_mov_b32_e32 v94, v4
	v_mov_b32_e32 v95, v4
	v_mov_b32_e32 v100, v4
	v_mov_b32_e32 v101, v4
	v_mov_b32_e32 v102, v4
	v_mov_b32_e32 v103, v4
	v_mov_b32_e32 v108, v4
	v_mov_b32_e32 v109, v4
	v_mov_b32_e32 v110, v4
	v_mov_b32_e32 v111, v4
	v_mov_b32_e32 v116, v4
	v_mov_b32_e32 v117, v4
	v_mov_b32_e32 v118, v4
	v_mov_b32_e32 v119, v4
	v_mov_b32_e32 v80, v4
	v_mov_b32_e32 v81, v4
	v_mov_b32_e32 v82, v4
	v_mov_b32_e32 v83, v4
	v_mov_b32_e32 v88, v4
	v_mov_b32_e32 v89, v4
	v_mov_b32_e32 v90, v4
	v_mov_b32_e32 v91, v4
	v_mov_b32_e32 v96, v4
	v_mov_b32_e32 v97, v4
	v_mov_b32_e32 v98, v4
	v_mov_b32_e32 v99, v4
	v_mov_b32_e32 v104, v4
	v_mov_b32_e32 v105, v4
	v_mov_b32_e32 v106, v4
	v_mov_b32_e32 v107, v4
	v_mov_b32_e32 v112, v4
	v_mov_b32_e32 v113, v4
	v_mov_b32_e32 v114, v4
	v_mov_b32_e32 v115, v4
	v_mov_b32_e32 v120, v4
	v_mov_b32_e32 v121, v4
	v_mov_b32_e32 v122, v4
	v_mov_b32_e32 v123, v4
	v_mov_b32_e32 v124, v4
	v_mov_b32_e32 v125, v4
	v_mov_b32_e32 v126, v4
	v_mov_b32_e32 v127, v4
	v_mov_b32_e32 v128, v4
	v_mov_b32_e32 v129, v4
	v_mov_b32_e32 v130, v4
	v_mov_b32_e32 v131, v4
	s_cmp_lg_u64 s[8:9], 0
	s_cbranch_scc1 .Lsp_g1074
	s_setprio 1
.Lsp_g1074:
.LBB0_1074:
	s_add_u32 s42, s40, 0xffe00080
	s_addc_u32 s43, s41, -1
	s_add_i32 s59, 0, 0x10000
	s_cmpk_eq_i32 s58, 0x7c
	s_cselect_b32 s45, s27, s43
	s_cselect_b32 s44, s54, s42
	v_add_u32_e32 v142, s59, v144
	s_cselect_b32 s43, s13, s57
	s_cselect_b32 s42, s55, s56
	s_add_i32 s62, 0, 0x14000
	ds_read_b128 v[148:151], v142
	ds_read_b128 v[152:155], v142 offset:1024
	ds_read_b128 v[156:159], v142 offset:2048
	ds_read_b128 v[160:163], v142 offset:3072
	v_add_u32_e32 v142, s62, v144
	ds_read_b128 v[164:167], v142
	ds_read_b128 v[178:181], v142 offset:1024
	ds_read_b128 v[182:185], v142 offset:2048
	ds_read_b128 v[186:189], v142 offset:3072
	v_lshl_add_u64 v[142:143], s[40:41], 0, v[138:139]
	s_add_i32 m0, s46, 0xc000
	ds_read_b128 v[190:193], v146
	ds_read_b128 v[194:197], v146 offset:1024
	ds_read_b128 v[208:211], v146 offset:2048
	ds_read_b128 v[212:215], v146 offset:3072
	ds_read_b128 v[216:219], v146 offset:4096
	ds_read_b128 v[220:223], v146 offset:5120
	ds_read_b128 v[224:227], v146 offset:6144
	ds_read_b128 v[228:231], v146 offset:7168
	global_load_lds_dwordx4 v[142:143], off
	v_lshl_add_u64 v[142:143], s[40:41], 0, v[140:141]
	s_add_i32 m0, s46, 0xe000
	s_nop 0
	global_load_lds_dwordx4 v[142:143], off
	s_waitcnt vmcnt(8)
	s_waitcnt lgkmcnt(0)
	s_barrier
	s_waitcnt lgkmcnt(0)
	v_mfma_f32_16x16x32_bf16 v[128:131], v[148:151], v[190:193], v[128:131]
	v_mfma_f32_16x16x32_bf16 v[128:131], v[152:155], v[194:197], v[128:131]
	v_mfma_f32_16x16x32_bf16 v[124:127], v[160:163], v[194:197], v[124:127]
	v_mfma_f32_16x16x32_bf16 v[124:127], v[156:159], v[190:193], v[124:127]
	v_mfma_f32_16x16x32_bf16 v[112:115], v[156:159], v[208:211], v[112:115]
	v_mfma_f32_16x16x32_bf16 v[112:115], v[160:163], v[212:215], v[112:115]
	v_mfma_f32_16x16x32_bf16 v[120:123], v[152:155], v[212:215], v[120:123]
	v_mfma_f32_16x16x32_bf16 v[120:123], v[148:151], v[208:211], v[120:123]
	v_mfma_f32_16x16x32_bf16 v[104:107], v[148:151], v[216:219], v[104:107]
	v_mfma_f32_16x16x32_bf16 v[104:107], v[152:155], v[220:223], v[104:107]
	v_mfma_f32_16x16x32_bf16 v[96:99], v[160:163], v[220:223], v[96:99]
	v_mfma_f32_16x16x32_bf16 v[96:99], v[156:159], v[216:219], v[96:99]
	v_mfma_f32_16x16x32_bf16 v[80:83], v[156:159], v[224:227], v[80:83]
	v_mfma_f32_16x16x32_bf16 v[80:83], v[160:163], v[228:231], v[80:83]
	v_mfma_f32_16x16x32_bf16 v[88:91], v[152:155], v[228:231], v[88:91]
	v_mfma_f32_16x16x32_bf16 v[88:91], v[148:151], v[224:227], v[88:91]
	v_mfma_f32_16x16x32_bf16 v[116:119], v[164:167], v[190:193], v[116:119]
	v_mfma_f32_16x16x32_bf16 v[116:119], v[178:181], v[194:197], v[116:119]
	v_mfma_f32_16x16x32_bf16 v[108:111], v[186:189], v[194:197], v[108:111]
	v_mfma_f32_16x16x32_bf16 v[108:111], v[182:185], v[190:193], v[108:111]
	v_mfma_f32_16x16x32_bf16 v[92:95], v[182:185], v[208:211], v[92:95]
	v_mfma_f32_16x16x32_bf16 v[92:95], v[186:189], v[212:215], v[92:95]
	v_mfma_f32_16x16x32_bf16 v[100:103], v[178:181], v[212:215], v[100:103]
	v_mfma_f32_16x16x32_bf16 v[100:103], v[164:167], v[208:211], v[100:103]
	v_mfma_f32_16x16x32_bf16 v[84:87], v[164:167], v[216:219], v[84:87]
	v_mfma_f32_16x16x32_bf16 v[84:87], v[178:181], v[220:223], v[84:87]
	v_mfma_f32_16x16x32_bf16 v[76:79], v[186:189], v[220:223], v[76:79]
	v_mfma_f32_16x16x32_bf16 v[76:79], v[182:185], v[216:219], v[76:79]
	v_mfma_f32_16x16x32_bf16 v[68:71], v[182:185], v[224:227], v[68:71]
	v_mfma_f32_16x16x32_bf16 v[68:71], v[186:189], v[228:231], v[68:71]
	v_mfma_f32_16x16x32_bf16 v[72:75], v[178:181], v[228:231], v[72:75]
	v_mfma_f32_16x16x32_bf16 v[72:75], v[164:167], v[224:227], v[72:75]
	s_barrier
	s_add_i32 s59, s59, s33
	v_lshl_add_u64 v[142:143], s[42:43], 0, v[2:3]
	s_mov_b32 m0, s59
	ds_read_b128 v[190:193], v146 offset:16384
	ds_read_b128 v[194:197], v146 offset:17408
	ds_read_b128 v[208:211], v146 offset:18432
	ds_read_b128 v[212:215], v146 offset:19456
	ds_read_b128 v[216:219], v146 offset:20480
	ds_read_b128 v[220:223], v146 offset:21504
	ds_read_b128 v[224:227], v146 offset:22528
	ds_read_b128 v[228:231], v146 offset:23552
	global_load_lds_dwordx4 v[142:143], off
	s_add_i32 m0, s59, 0x2000
	s_add_u32 s60, s42, 0x200000
	v_lshl_add_u64 v[168:169], s[42:43], 0, v[136:137]
	s_addc_u32 s61, s43, 0
	s_add_i32 s59, s62, s33
	global_load_lds_dwordx4 v[168:169], off
	v_lshl_add_u64 v[232:233], s[60:61], 0, v[2:3]
	s_mov_b32 m0, s59
	v_lshl_add_u64 v[234:235], s[44:45], 0, v[134:135]
	global_load_lds_dwordx4 v[232:233], off
	v_lshl_add_u64 v[232:233], s[60:61], 0, v[136:137]
	s_add_i32 m0, s59, 0x2000
	s_nop 0
	global_load_lds_dwordx4 v[232:233], off
	v_lshl_add_u64 v[232:233], s[44:45], 0, v[132:133]
	s_mov_b32 m0, s46
	s_nop 0
	global_load_lds_dwordx4 v[232:233], off
	s_mov_b32 m0, s47
	s_nop 0
	global_load_lds_dwordx4 v[234:235], off
	s_waitcnt vmcnt(8)
	s_waitcnt lgkmcnt(0)
	s_barrier
	s_waitcnt lgkmcnt(0)
	v_mfma_f32_16x16x32_bf16 v[64:67], v[148:151], v[190:193], v[64:67]
	v_mfma_f32_16x16x32_bf16 v[64:67], v[152:155], v[194:197], v[64:67]
	v_mfma_f32_16x16x32_bf16 v[60:63], v[160:163], v[194:197], v[60:63]
	v_mfma_f32_16x16x32_bf16 v[60:63], v[156:159], v[190:193], v[60:63]
	v_mfma_f32_16x16x32_bf16 v[48:51], v[156:159], v[208:211], v[48:51]
	v_mfma_f32_16x16x32_bf16 v[48:51], v[160:163], v[212:215], v[48:51]
	v_mfma_f32_16x16x32_bf16 v[56:59], v[152:155], v[212:215], v[56:59]
	v_mfma_f32_16x16x32_bf16 v[56:59], v[148:151], v[208:211], v[56:59]
	v_mfma_f32_16x16x32_bf16 v[40:43], v[148:151], v[216:219], v[40:43]
	v_mfma_f32_16x16x32_bf16 v[40:43], v[152:155], v[220:223], v[40:43]
	v_mfma_f32_16x16x32_bf16 v[32:35], v[160:163], v[220:223], v[32:35]
	v_mfma_f32_16x16x32_bf16 v[32:35], v[156:159], v[216:219], v[32:35]
	v_mfma_f32_16x16x32_bf16 v[16:19], v[156:159], v[224:227], v[16:19]
	v_mfma_f32_16x16x32_bf16 v[16:19], v[160:163], v[228:231], v[16:19]
	v_mfma_f32_16x16x32_bf16 v[24:27], v[152:155], v[228:231], v[24:27]
	v_mfma_f32_16x16x32_bf16 v[24:27], v[148:151], v[224:227], v[24:27]
	v_mfma_f32_16x16x32_bf16 v[52:55], v[164:167], v[190:193], v[52:55]
	v_mfma_f32_16x16x32_bf16 v[52:55], v[178:181], v[194:197], v[52:55]
	v_mfma_f32_16x16x32_bf16 v[44:47], v[186:189], v[194:197], v[44:47]
	v_mfma_f32_16x16x32_bf16 v[44:47], v[182:185], v[190:193], v[44:47]
	v_mfma_f32_16x16x32_bf16 v[28:31], v[182:185], v[208:211], v[28:31]
	v_mfma_f32_16x16x32_bf16 v[28:31], v[186:189], v[212:215], v[28:31]
	v_mfma_f32_16x16x32_bf16 v[36:39], v[178:181], v[212:215], v[36:39]
	v_mfma_f32_16x16x32_bf16 v[36:39], v[164:167], v[208:211], v[36:39]
	v_mfma_f32_16x16x32_bf16 v[20:23], v[164:167], v[216:219], v[20:23]
	v_mfma_f32_16x16x32_bf16 v[20:23], v[178:181], v[220:223], v[20:23]
	v_mfma_f32_16x16x32_bf16 v[12:15], v[186:189], v[220:223], v[12:15]
	v_mfma_f32_16x16x32_bf16 v[12:15], v[182:185], v[216:219], v[12:15]
	v_mfma_f32_16x16x32_bf16 v[4:7], v[182:185], v[224:227], v[4:7]
	v_mfma_f32_16x16x32_bf16 v[4:7], v[186:189], v[228:231], v[4:7]
	v_mfma_f32_16x16x32_bf16 v[8:11], v[178:181], v[228:231], v[8:11]
	v_mfma_f32_16x16x32_bf16 v[8:11], v[164:167], v[224:227], v[8:11]
	s_barrier
	s_add_i32 s59, 0, 0x18000
	v_add_u32_e32 v147, s59, v144
	s_add_i32 s60, 0, 0x1c000
	ds_read_b128 v[148:151], v147
	ds_read_b128 v[152:155], v147 offset:1024
	ds_read_b128 v[156:159], v147 offset:2048
	ds_read_b128 v[160:163], v147 offset:3072
	v_add_u32_e32 v147, s60, v144
	ds_read_b128 v[164:167], v147
	ds_read_b128 v[178:181], v147 offset:1024
	ds_read_b128 v[182:185], v147 offset:2048
	ds_read_b128 v[186:189], v147 offset:3072
	s_add_u32 s44, s44, 0x200000
	s_addc_u32 s45, s45, 0
	s_mov_b32 m0, s48
	v_lshl_add_u64 v[236:237], s[44:45], 0, v[132:133]
	ds_read_b128 v[190:193], v146 offset:32768
	ds_read_b128 v[194:197], v146 offset:33792
	ds_read_b128 v[208:211], v146 offset:34816
	ds_read_b128 v[212:215], v146 offset:35840
	ds_read_b128 v[216:219], v146 offset:36864
	ds_read_b128 v[220:223], v146 offset:37888
	ds_read_b128 v[224:227], v146 offset:38912
	ds_read_b128 v[228:231], v146 offset:39936
	global_load_lds_dwordx4 v[236:237], off
	v_lshl_add_u64 v[236:237], s[44:45], 0, v[134:135]
	s_mov_b32 m0, s49
	s_nop 0
	global_load_lds_dwordx4 v[236:237], off
	s_waitcnt vmcnt(8)
	s_waitcnt lgkmcnt(0)
	s_barrier
	s_waitcnt lgkmcnt(0)
	v_mfma_f32_16x16x32_bf16 v[128:131], v[148:151], v[190:193], v[128:131]
	v_mfma_f32_16x16x32_bf16 v[128:131], v[152:155], v[194:197], v[128:131]
	v_mfma_f32_16x16x32_bf16 v[124:127], v[160:163], v[194:197], v[124:127]
	v_mfma_f32_16x16x32_bf16 v[124:127], v[156:159], v[190:193], v[124:127]
	v_mfma_f32_16x16x32_bf16 v[112:115], v[156:159], v[208:211], v[112:115]
	v_mfma_f32_16x16x32_bf16 v[112:115], v[160:163], v[212:215], v[112:115]
	v_mfma_f32_16x16x32_bf16 v[120:123], v[152:155], v[212:215], v[120:123]
	v_mfma_f32_16x16x32_bf16 v[120:123], v[148:151], v[208:211], v[120:123]
	v_mfma_f32_16x16x32_bf16 v[104:107], v[148:151], v[216:219], v[104:107]
	v_mfma_f32_16x16x32_bf16 v[104:107], v[152:155], v[220:223], v[104:107]
	v_mfma_f32_16x16x32_bf16 v[96:99], v[160:163], v[220:223], v[96:99]
	v_mfma_f32_16x16x32_bf16 v[96:99], v[156:159], v[216:219], v[96:99]
	v_mfma_f32_16x16x32_bf16 v[80:83], v[156:159], v[224:227], v[80:83]
	v_mfma_f32_16x16x32_bf16 v[80:83], v[160:163], v[228:231], v[80:83]
	v_mfma_f32_16x16x32_bf16 v[88:91], v[152:155], v[228:231], v[88:91]
	v_mfma_f32_16x16x32_bf16 v[88:91], v[148:151], v[224:227], v[88:91]
	v_mfma_f32_16x16x32_bf16 v[116:119], v[164:167], v[190:193], v[116:119]
	v_mfma_f32_16x16x32_bf16 v[116:119], v[178:181], v[194:197], v[116:119]
	v_mfma_f32_16x16x32_bf16 v[108:111], v[186:189], v[194:197], v[108:111]
	v_mfma_f32_16x16x32_bf16 v[108:111], v[182:185], v[190:193], v[108:111]
	v_mfma_f32_16x16x32_bf16 v[92:95], v[182:185], v[208:211], v[92:95]
	v_mfma_f32_16x16x32_bf16 v[92:95], v[186:189], v[212:215], v[92:95]
	v_mfma_f32_16x16x32_bf16 v[100:103], v[178:181], v[212:215], v[100:103]
	v_mfma_f32_16x16x32_bf16 v[100:103], v[164:167], v[208:211], v[100:103]
	v_mfma_f32_16x16x32_bf16 v[84:87], v[164:167], v[216:219], v[84:87]
	v_mfma_f32_16x16x32_bf16 v[84:87], v[178:181], v[220:223], v[84:87]
	v_mfma_f32_16x16x32_bf16 v[76:79], v[186:189], v[220:223], v[76:79]
	v_mfma_f32_16x16x32_bf16 v[76:79], v[182:185], v[216:219], v[76:79]
	v_mfma_f32_16x16x32_bf16 v[68:71], v[182:185], v[224:227], v[68:71]
	v_mfma_f32_16x16x32_bf16 v[68:71], v[186:189], v[228:231], v[68:71]
	v_mfma_f32_16x16x32_bf16 v[72:75], v[178:181], v[228:231], v[72:75]
	v_mfma_f32_16x16x32_bf16 v[72:75], v[164:167], v[224:227], v[72:75]
	s_barrier
	s_add_i32 s44, s59, s33
	v_lshl_add_u64 v[142:143], v[142:143], 0, s[18:19]
	s_mov_b32 m0, s44
	ds_read_b128 v[190:193], v146 offset:49152
	ds_read_b128 v[194:197], v146 offset:50176
	ds_read_b128 v[208:211], v146 offset:51200
	ds_read_b128 v[212:215], v146 offset:52224
	ds_read_b128 v[216:219], v146 offset:53248
	ds_read_b128 v[220:223], v146 offset:54272
	ds_read_b128 v[224:227], v146 offset:55296
	ds_read_b128 v[228:231], v146 offset:56320
	global_load_lds_dwordx4 v[142:143], off
	s_add_i32 m0, s44, 0x2000
	s_add_u32 s42, s42, 0x200080
	v_lshl_add_u64 v[142:143], v[168:169], 0, s[18:19]
	s_addc_u32 s43, s43, 0
	s_add_i32 s44, s60, s33
	global_load_lds_dwordx4 v[142:143], off
	v_lshl_add_u64 v[142:143], s[42:43], 0, v[2:3]
	s_mov_b32 m0, s44
	s_nop 0
	global_load_lds_dwordx4 v[142:143], off
	v_lshl_add_u64 v[142:143], s[42:43], 0, v[136:137]
	s_add_i32 m0, s44, 0x2000
	s_nop 0
	global_load_lds_dwordx4 v[142:143], off
	v_lshl_add_u64 v[142:143], v[232:233], 0, s[18:19]
	s_mov_b32 m0, s50
	s_nop 0
	global_load_lds_dwordx4 v[142:143], off
	v_lshl_add_u64 v[142:143], v[234:235], 0, s[18:19]
	s_mov_b32 m0, s51
	s_nop 0
	global_load_lds_dwordx4 v[142:143], off
	s_waitcnt vmcnt(8)
	s_waitcnt lgkmcnt(0)
	s_barrier
	s_waitcnt lgkmcnt(0)
	v_mfma_f32_16x16x32_bf16 v[64:67], v[148:151], v[190:193], v[64:67]
	v_mfma_f32_16x16x32_bf16 v[64:67], v[152:155], v[194:197], v[64:67]
	v_mfma_f32_16x16x32_bf16 v[60:63], v[160:163], v[194:197], v[60:63]
	v_mfma_f32_16x16x32_bf16 v[60:63], v[156:159], v[190:193], v[60:63]
	v_mfma_f32_16x16x32_bf16 v[48:51], v[156:159], v[208:211], v[48:51]
	v_mfma_f32_16x16x32_bf16 v[48:51], v[160:163], v[212:215], v[48:51]
	v_mfma_f32_16x16x32_bf16 v[56:59], v[152:155], v[212:215], v[56:59]
	v_mfma_f32_16x16x32_bf16 v[56:59], v[148:151], v[208:211], v[56:59]
	v_mfma_f32_16x16x32_bf16 v[40:43], v[148:151], v[216:219], v[40:43]
	v_mfma_f32_16x16x32_bf16 v[40:43], v[152:155], v[220:223], v[40:43]
	v_mfma_f32_16x16x32_bf16 v[32:35], v[160:163], v[220:223], v[32:35]
	v_mfma_f32_16x16x32_bf16 v[32:35], v[156:159], v[216:219], v[32:35]
	v_mfma_f32_16x16x32_bf16 v[16:19], v[156:159], v[224:227], v[16:19]
	v_mfma_f32_16x16x32_bf16 v[16:19], v[160:163], v[228:231], v[16:19]
	v_mfma_f32_16x16x32_bf16 v[24:27], v[152:155], v[228:231], v[24:27]
	v_mfma_f32_16x16x32_bf16 v[24:27], v[148:151], v[224:227], v[24:27]
	v_mfma_f32_16x16x32_bf16 v[52:55], v[164:167], v[190:193], v[52:55]
	v_mfma_f32_16x16x32_bf16 v[52:55], v[178:181], v[194:197], v[52:55]
	v_mfma_f32_16x16x32_bf16 v[44:47], v[186:189], v[194:197], v[44:47]
	v_mfma_f32_16x16x32_bf16 v[44:47], v[182:185], v[190:193], v[44:47]
	v_mfma_f32_16x16x32_bf16 v[28:31], v[182:185], v[208:211], v[28:31]
	v_mfma_f32_16x16x32_bf16 v[28:31], v[186:189], v[212:215], v[28:31]
	v_mfma_f32_16x16x32_bf16 v[36:39], v[178:181], v[212:215], v[36:39]
	v_mfma_f32_16x16x32_bf16 v[36:39], v[164:167], v[208:211], v[36:39]
	v_mfma_f32_16x16x32_bf16 v[20:23], v[164:167], v[216:219], v[20:23]
	v_mfma_f32_16x16x32_bf16 v[20:23], v[178:181], v[220:223], v[20:23]
	v_mfma_f32_16x16x32_bf16 v[12:15], v[186:189], v[220:223], v[12:15]
	v_mfma_f32_16x16x32_bf16 v[12:15], v[182:185], v[216:219], v[12:15]
	v_mfma_f32_16x16x32_bf16 v[4:7], v[182:185], v[224:227], v[4:7]
	v_mfma_f32_16x16x32_bf16 v[4:7], v[186:189], v[228:231], v[4:7]
	v_mfma_f32_16x16x32_bf16 v[8:11], v[178:181], v[228:231], v[8:11]
	v_mfma_f32_16x16x32_bf16 v[8:11], v[164:167], v[224:227], v[8:11]
	s_barrier
	s_add_i32 s58, s58, 2
	s_add_u32 s40, s40, 0x100
	s_addc_u32 s41, s41, 0
	s_add_u32 s56, s56, 0x100
	s_addc_u32 s57, s57, 0
	s_cmpk_gt_u32 s58, 0x7d
	s_cbranch_scc0 .LBB0_1074
	s_setprio 0
	s_and_b64 vcc, exec, s[8:9]
	s_cbranch_vccz .LBB0_1077
	s_barrier

.LBB0_1087:
	s_add_i32 s46, s46, 1
	s_mov_b32 s48, s2
	s_mul_i32 s2, s46, s24
	s_add_i32 s2, s2, s23
	s_cmpk_lt_i32 s2, 0x100
	s_mov_b32 s47, s33
	s_cselect_b64 s[34:35], -1, 0
	s_bfe_u32 s33, s2, 0x30003
	s_ashr_i32 s2, s2, 6
	s_ashr_i32 s3, s2, 31
	s_mov_b64 s[38:39], s[4:5]
	s_lshl_b64 s[4:5], s[2:3], 22
	s_mov_b64 s[36:37], s[8:9]
	s_add_u32 s8, s21, s4
	s_addc_u32 s9, s22, s5
	s_and_b64 s[4:5], s[34:35], exec
	s_cselect_b32 s3, s9, s37
	s_cselect_b32 s49, s8, s36
	s_lshl_b32 s4, s33, 22
	s_add_u32 s4, s10, s4
	s_addc_u32 s5, s11, 0
	s_and_b64 s[40:41], s[34:35], exec
	s_cselect_b32 s50, s5, s39
	s_cselect_b32 s51, s4, s38
	s_add_u32 s36, s36, 0x200080
	s_addc_u32 s37, s37, 0
	s_add_u32 s52, s38, 0x100
	v_mov_b32_e32 v4, 0
	s_addc_u32 s53, s39, 0
	s_mov_b32 s54, -2
	v_mov_b32_e32 v5, v4
	v_mov_b32_e32 v6, v4
	v_mov_b32_e32 v7, v4
	v_mov_b32_e32 v8, v4
	v_mov_b32_e32 v9, v4
	v_mov_b32_e32 v10, v4
	v_mov_b32_e32 v11, v4
	v_mov_b32_e32 v12, v4
	v_mov_b32_e32 v13, v4
	v_mov_b32_e32 v14, v4
	v_mov_b32_e32 v15, v4
	v_mov_b32_e32 v16, v4
	v_mov_b32_e32 v17, v4
	v_mov_b32_e32 v18, v4
	v_mov_b32_e32 v19, v4
	v_mov_b32_e32 v28, v4
	v_mov_b32_e32 v29, v4
	v_mov_b32_e32 v30, v4
	v_mov_b32_e32 v31, v4
	v_mov_b32_e32 v32, v4
	v_mov_b32_e32 v33, v4
	v_mov_b32_e32 v34, v4
	v_mov_b32_e32 v35, v4
	v_mov_b32_e32 v44, v4
	v_mov_b32_e32 v45, v4
	v_mov_b32_e32 v46, v4
	v_mov_b32_e32 v47, v4
	v_mov_b32_e32 v48, v4
	v_mov_b32_e32 v49, v4
	v_mov_b32_e32 v50, v4
	v_mov_b32_e32 v51, v4
	v_mov_b32_e32 v20, v4
	v_mov_b32_e32 v21, v4
	v_mov_b32_e32 v22, v4
	v_mov_b32_e32 v23, v4
	v_mov_b32_e32 v24, v4
	v_mov_b32_e32 v25, v4
	v_mov_b32_e32 v26, v4
	v_mov_b32_e32 v27, v4
	v_mov_b32_e32 v36, v4
	v_mov_b32_e32 v37, v4
	v_mov_b32_e32 v38, v4
	v_mov_b32_e32 v39, v4
	v_mov_b32_e32 v40, v4
	v_mov_b32_e32 v41, v4
	v_mov_b32_e32 v42, v4
	v_mov_b32_e32 v43, v4
	v_mov_b32_e32 v52, v4
	v_mov_b32_e32 v53, v4
	v_mov_b32_e32 v54, v4
	v_mov_b32_e32 v55, v4
	v_mov_b32_e32 v56, v4
	v_mov_b32_e32 v57, v4
	v_mov_b32_e32 v58, v4
	v_mov_b32_e32 v59, v4
	v_mov_b32_e32 v60, v4
	v_mov_b32_e32 v61, v4
	v_mov_b32_e32 v62, v4
	v_mov_b32_e32 v63, v4
	v_mov_b32_e32 v64, v4
	v_mov_b32_e32 v65, v4
	v_mov_b32_e32 v66, v4
	v_mov_b32_e32 v67, v4
	v_mov_b32_e32 v68, v4
	v_mov_b32_e32 v69, v4
	v_mov_b32_e32 v70, v4
	v_mov_b32_e32 v71, v4
	v_mov_b32_e32 v72, v4
	v_mov_b32_e32 v73, v4
	v_mov_b32_e32 v74, v4
	v_mov_b32_e32 v75, v4
	v_mov_b32_e32 v76, v4
	v_mov_b32_e32 v77, v4
	v_mov_b32_e32 v78, v4
	v_mov_b32_e32 v79, v4
	v_mov_b32_e32 v80, v4
	v_mov_b32_e32 v81, v4
	v_mov_b32_e32 v82, v4
	v_mov_b32_e32 v83, v4
	v_mov_b32_e32 v88, v4
	v_mov_b32_e32 v89, v4
	v_mov_b32_e32 v90, v4
	v_mov_b32_e32 v91, v4
	v_mov_b32_e32 v96, v4
	v_mov_b32_e32 v97, v4
	v_mov_b32_e32 v98, v4
	v_mov_b32_e32 v99, v4
	v_mov_b32_e32 v104, v4
	v_mov_b32_e32 v105, v4
	v_mov_b32_e32 v106, v4
	v_mov_b32_e32 v107, v4
	v_mov_b32_e32 v112, v4
	v_mov_b32_e32 v113, v4
	v_mov_b32_e32 v114, v4
	v_mov_b32_e32 v115, v4
	v_mov_b32_e32 v84, v4
	v_mov_b32_e32 v85, v4
	v_mov_b32_e32 v86, v4
	v_mov_b32_e32 v87, v4
	v_mov_b32_e32 v92, v4
	v_mov_b32_e32 v93, v4
	v_mov_b32_e32 v94, v4
	v_mov_b32_e32 v95, v4
	v_mov_b32_e32 v100, v4
	v_mov_b32_e32 v101, v4
	v_mov_b32_e32 v102, v4
	v_mov_b32_e32 v103, v4
	v_mov_b32_e32 v108, v4
	v_mov_b32_e32 v109, v4
	v_mov_b32_e32 v110, v4
	v_mov_b32_e32 v111, v4
	v_mov_b32_e32 v116, v4
	v_mov_b32_e32 v117, v4
	v_mov_b32_e32 v118, v4
	v_mov_b32_e32 v119, v4
	v_mov_b32_e32 v120, v4
	v_mov_b32_e32 v121, v4
	v_mov_b32_e32 v122, v4
	v_mov_b32_e32 v123, v4
	v_mov_b32_e32 v124, v4
	v_mov_b32_e32 v125, v4
	v_mov_b32_e32 v126, v4
	v_mov_b32_e32 v127, v4
	v_mov_b32_e32 v128, v4
	v_mov_b32_e32 v129, v4
	v_mov_b32_e32 v130, v4
	v_mov_b32_e32 v131, v4
	s_cmp_lg_u64 s[28:29], 0
	s_cbranch_scc1 .Lsp_g1088
	s_setprio 1
.Lsp_g1088:
.LBB0_1088:
	s_add_u32 s38, s36, 0xffe00080
	s_addc_u32 s39, s37, -1
	s_add_i32 s55, 0, 0x10000
	s_cmp_eq_u32 s54, 12
	s_cselect_b32 s41, s3, s39
	s_cselect_b32 s40, s49, s38
	v_add_u32_e32 v2, s55, v140
	s_cselect_b32 s39, s50, s53
	s_cselect_b32 s38, s51, s52
	s_add_i32 s58, 0, 0x14000
	ds_read_b128 v[144:147], v2
	ds_read_b128 v[148:151], v2 offset:1024
	ds_read_b128 v[152:155], v2 offset:2048
	ds_read_b128 v[156:159], v2 offset:3072
	v_add_u32_e32 v2, s58, v140
	ds_read_b128 v[160:163], v2
	ds_read_b128 v[164:167], v2 offset:1024
	ds_read_b128 v[178:181], v2 offset:2048
	ds_read_b128 v[182:185], v2 offset:3072
	v_lshl_add_u64 v[168:169], s[36:37], 0, v[136:137]
	s_add_i32 m0, s42, 0xc000
	ds_read_b128 v[186:189], v142
	ds_read_b128 v[190:193], v142 offset:1024
	ds_read_b128 v[194:197], v142 offset:2048
	ds_read_b128 v[208:211], v142 offset:3072
	ds_read_b128 v[212:215], v142 offset:4096
	ds_read_b128 v[216:219], v142 offset:5120
	ds_read_b128 v[220:223], v142 offset:6144
	ds_read_b128 v[224:227], v142 offset:7168
	global_load_lds_dwordx4 v[168:169], off
	v_lshl_add_u64 v[168:169], s[36:37], 0, v[138:139]
	s_add_i32 m0, s42, 0xe000
	s_nop 0
	global_load_lds_dwordx4 v[168:169], off
	s_waitcnt vmcnt(8)
	s_waitcnt lgkmcnt(0)
	s_barrier
	s_waitcnt lgkmcnt(0)
	v_mfma_f32_16x16x32_bf16 v[128:131], v[144:147], v[186:189], v[128:131]
	v_mfma_f32_16x16x32_bf16 v[128:131], v[148:151], v[190:193], v[128:131]
	v_mfma_f32_16x16x32_bf16 v[124:127], v[156:159], v[190:193], v[124:127]
	v_mfma_f32_16x16x32_bf16 v[124:127], v[152:155], v[186:189], v[124:127]
	v_mfma_f32_16x16x32_bf16 v[116:119], v[152:155], v[194:197], v[116:119]
	v_mfma_f32_16x16x32_bf16 v[116:119], v[156:159], v[208:211], v[116:119]
	v_mfma_f32_16x16x32_bf16 v[120:123], v[148:151], v[208:211], v[120:123]
	v_mfma_f32_16x16x32_bf16 v[120:123], v[144:147], v[194:197], v[120:123]
	v_mfma_f32_16x16x32_bf16 v[108:111], v[144:147], v[212:215], v[108:111]
	v_mfma_f32_16x16x32_bf16 v[108:111], v[148:151], v[216:219], v[108:111]
	v_mfma_f32_16x16x32_bf16 v[100:103], v[156:159], v[216:219], v[100:103]
	v_mfma_f32_16x16x32_bf16 v[100:103], v[152:155], v[212:215], v[100:103]
	v_mfma_f32_16x16x32_bf16 v[84:87], v[152:155], v[220:223], v[84:87]
	v_mfma_f32_16x16x32_bf16 v[84:87], v[156:159], v[224:227], v[84:87]
	v_mfma_f32_16x16x32_bf16 v[92:95], v[148:151], v[224:227], v[92:95]
	v_mfma_f32_16x16x32_bf16 v[92:95], v[144:147], v[220:223], v[92:95]
	v_mfma_f32_16x16x32_bf16 v[112:115], v[160:163], v[186:189], v[112:115]
	v_mfma_f32_16x16x32_bf16 v[112:115], v[164:167], v[190:193], v[112:115]
	v_mfma_f32_16x16x32_bf16 v[104:107], v[182:185], v[190:193], v[104:107]
	v_mfma_f32_16x16x32_bf16 v[104:107], v[178:181], v[186:189], v[104:107]
	v_mfma_f32_16x16x32_bf16 v[88:91], v[178:181], v[194:197], v[88:91]
	v_mfma_f32_16x16x32_bf16 v[88:91], v[182:185], v[208:211], v[88:91]
	v_mfma_f32_16x16x32_bf16 v[96:99], v[164:167], v[208:211], v[96:99]
	v_mfma_f32_16x16x32_bf16 v[96:99], v[160:163], v[194:197], v[96:99]
	v_mfma_f32_16x16x32_bf16 v[80:83], v[160:163], v[212:215], v[80:83]
	v_mfma_f32_16x16x32_bf16 v[80:83], v[164:167], v[216:219], v[80:83]
	v_mfma_f32_16x16x32_bf16 v[76:79], v[182:185], v[216:219], v[76:79]
	v_mfma_f32_16x16x32_bf16 v[76:79], v[178:181], v[212:215], v[76:79]
	v_mfma_f32_16x16x32_bf16 v[68:71], v[178:181], v[220:223], v[68:71]
	v_mfma_f32_16x16x32_bf16 v[68:71], v[182:185], v[224:227], v[68:71]
	v_mfma_f32_16x16x32_bf16 v[72:75], v[164:167], v[224:227], v[72:75]
	v_mfma_f32_16x16x32_bf16 v[72:75], v[160:163], v[220:223], v[72:75]
	s_barrier
	s_add_i32 s55, s55, s25
	v_lshl_add_u64 v[168:169], s[38:39], 0, v[134:135]
	s_mov_b32 m0, s55
	ds_read_b128 v[186:189], v142 offset:16384
	ds_read_b128 v[190:193], v142 offset:17408
	ds_read_b128 v[194:197], v142 offset:18432
	ds_read_b128 v[208:211], v142 offset:19456
	ds_read_b128 v[212:215], v142 offset:20480
	ds_read_b128 v[216:219], v142 offset:21504
	ds_read_b128 v[220:223], v142 offset:22528
	ds_read_b128 v[224:227], v142 offset:23552
	global_load_lds_dwordx4 v[168:169], off
	s_add_i32 m0, s55, 0x2000
	s_add_u32 s56, s38, 0x200000
	v_lshl_add_u64 v[228:229], s[38:39], 0, v[132:133]
	s_addc_u32 s57, s39, 0
	s_add_i32 s55, s58, s25
	global_load_lds_dwordx4 v[228:229], off
	v_lshl_add_u64 v[230:231], s[56:57], 0, v[134:135]
	s_mov_b32 m0, s55
	v_lshl_add_u64 v[232:233], s[40:41], 0, v[132:133]
	global_load_lds_dwordx4 v[230:231], off
	v_lshl_add_u64 v[230:231], s[56:57], 0, v[132:133]
	s_add_i32 m0, s55, 0x2000
	s_nop 0
	global_load_lds_dwordx4 v[230:231], off
	v_lshl_add_u64 v[230:231], s[40:41], 0, v[134:135]
	s_mov_b32 m0, s42
	s_nop 0
	global_load_lds_dwordx4 v[230:231], off
	s_mov_b32 m0, s43
	s_nop 0
	global_load_lds_dwordx4 v[232:233], off
	s_waitcnt vmcnt(8)
	s_waitcnt lgkmcnt(0)
	s_barrier
	s_waitcnt lgkmcnt(0)
	v_mfma_f32_16x16x32_bf16 v[64:67], v[144:147], v[186:189], v[64:67]
	v_mfma_f32_16x16x32_bf16 v[64:67], v[148:151], v[190:193], v[64:67]
	v_mfma_f32_16x16x32_bf16 v[60:63], v[156:159], v[190:193], v[60:63]
	v_mfma_f32_16x16x32_bf16 v[60:63], v[152:155], v[186:189], v[60:63]
	v_mfma_f32_16x16x32_bf16 v[52:55], v[152:155], v[194:197], v[52:55]
	v_mfma_f32_16x16x32_bf16 v[52:55], v[156:159], v[208:211], v[52:55]
	v_mfma_f32_16x16x32_bf16 v[56:59], v[148:151], v[208:211], v[56:59]
	v_mfma_f32_16x16x32_bf16 v[56:59], v[144:147], v[194:197], v[56:59]
	v_mfma_f32_16x16x32_bf16 v[40:43], v[144:147], v[212:215], v[40:43]
	v_mfma_f32_16x16x32_bf16 v[40:43], v[148:151], v[216:219], v[40:43]
	v_mfma_f32_16x16x32_bf16 v[36:39], v[156:159], v[216:219], v[36:39]
	v_mfma_f32_16x16x32_bf16 v[36:39], v[152:155], v[212:215], v[36:39]
	v_mfma_f32_16x16x32_bf16 v[20:23], v[152:155], v[220:223], v[20:23]
	v_mfma_f32_16x16x32_bf16 v[20:23], v[156:159], v[224:227], v[20:23]
	v_mfma_f32_16x16x32_bf16 v[24:27], v[148:151], v[224:227], v[24:27]
	v_mfma_f32_16x16x32_bf16 v[24:27], v[144:147], v[220:223], v[24:27]
	v_mfma_f32_16x16x32_bf16 v[48:51], v[160:163], v[186:189], v[48:51]
	v_mfma_f32_16x16x32_bf16 v[48:51], v[164:167], v[190:193], v[48:51]
	v_mfma_f32_16x16x32_bf16 v[44:47], v[182:185], v[190:193], v[44:47]
	v_mfma_f32_16x16x32_bf16 v[44:47], v[178:181], v[186:189], v[44:47]
	v_mfma_f32_16x16x32_bf16 v[28:31], v[178:181], v[194:197], v[28:31]
	v_mfma_f32_16x16x32_bf16 v[28:31], v[182:185], v[208:211], v[28:31]
	v_mfma_f32_16x16x32_bf16 v[32:35], v[164:167], v[208:211], v[32:35]
	v_mfma_f32_16x16x32_bf16 v[32:35], v[160:163], v[194:197], v[32:35]
	v_mfma_f32_16x16x32_bf16 v[16:19], v[160:163], v[212:215], v[16:19]
	v_mfma_f32_16x16x32_bf16 v[16:19], v[164:167], v[216:219], v[16:19]
	v_mfma_f32_16x16x32_bf16 v[12:15], v[182:185], v[216:219], v[12:15]
	v_mfma_f32_16x16x32_bf16 v[12:15], v[178:181], v[212:215], v[12:15]
	v_mfma_f32_16x16x32_bf16 v[4:7], v[178:181], v[220:223], v[4:7]
	v_mfma_f32_16x16x32_bf16 v[4:7], v[182:185], v[224:227], v[4:7]
	v_mfma_f32_16x16x32_bf16 v[8:11], v[164:167], v[224:227], v[8:11]
	v_mfma_f32_16x16x32_bf16 v[8:11], v[160:163], v[220:223], v[8:11]
	s_barrier
	s_add_i32 s55, 0, 0x18000
	v_add_u32_e32 v2, s55, v140
	s_add_i32 s56, 0, 0x1c000
	ds_read_b128 v[144:147], v2
	ds_read_b128 v[148:151], v2 offset:1024
	ds_read_b128 v[152:155], v2 offset:2048
	ds_read_b128 v[156:159], v2 offset:3072
	v_add_u32_e32 v2, s56, v140
	ds_read_b128 v[160:163], v2
	ds_read_b128 v[164:167], v2 offset:1024
	ds_read_b128 v[178:181], v2 offset:2048
	ds_read_b128 v[182:185], v2 offset:3072
	s_add_u32 s40, s40, 0x200000
	s_addc_u32 s41, s41, 0
	s_mov_b32 m0, s44
	v_lshl_add_u64 v[234:235], s[40:41], 0, v[134:135]
	ds_read_b128 v[186:189], v142 offset:32768
	ds_read_b128 v[190:193], v142 offset:33792
	ds_read_b128 v[194:197], v142 offset:34816
	ds_read_b128 v[208:211], v142 offset:35840
	ds_read_b128 v[212:215], v142 offset:36864
	ds_read_b128 v[216:219], v142 offset:37888
	ds_read_b128 v[220:223], v142 offset:38912
	ds_read_b128 v[224:227], v142 offset:39936
	global_load_lds_dwordx4 v[234:235], off
	v_lshl_add_u64 v[234:235], s[40:41], 0, v[132:133]
	s_mov_b32 m0, s45
	s_nop 0
	global_load_lds_dwordx4 v[234:235], off
	s_waitcnt vmcnt(8)
	s_waitcnt lgkmcnt(0)
	s_barrier
	s_waitcnt lgkmcnt(0)
	v_mfma_f32_16x16x32_bf16 v[128:131], v[144:147], v[186:189], v[128:131]
	v_mfma_f32_16x16x32_bf16 v[128:131], v[148:151], v[190:193], v[128:131]
	v_mfma_f32_16x16x32_bf16 v[124:127], v[156:159], v[190:193], v[124:127]
	v_mfma_f32_16x16x32_bf16 v[124:127], v[152:155], v[186:189], v[124:127]
	v_mfma_f32_16x16x32_bf16 v[116:119], v[152:155], v[194:197], v[116:119]
	v_mfma_f32_16x16x32_bf16 v[116:119], v[156:159], v[208:211], v[116:119]
	v_mfma_f32_16x16x32_bf16 v[120:123], v[148:151], v[208:211], v[120:123]
	v_mfma_f32_16x16x32_bf16 v[120:123], v[144:147], v[194:197], v[120:123]
	v_mfma_f32_16x16x32_bf16 v[108:111], v[144:147], v[212:215], v[108:111]
	v_mfma_f32_16x16x32_bf16 v[108:111], v[148:151], v[216:219], v[108:111]
	v_mfma_f32_16x16x32_bf16 v[100:103], v[156:159], v[216:219], v[100:103]
	v_mfma_f32_16x16x32_bf16 v[100:103], v[152:155], v[212:215], v[100:103]
	v_mfma_f32_16x16x32_bf16 v[84:87], v[152:155], v[220:223], v[84:87]
	v_mfma_f32_16x16x32_bf16 v[84:87], v[156:159], v[224:227], v[84:87]
	v_mfma_f32_16x16x32_bf16 v[92:95], v[148:151], v[224:227], v[92:95]
	v_mfma_f32_16x16x32_bf16 v[92:95], v[144:147], v[220:223], v[92:95]
	v_mfma_f32_16x16x32_bf16 v[112:115], v[160:163], v[186:189], v[112:115]
	v_mfma_f32_16x16x32_bf16 v[112:115], v[164:167], v[190:193], v[112:115]
	v_mfma_f32_16x16x32_bf16 v[104:107], v[182:185], v[190:193], v[104:107]
	v_mfma_f32_16x16x32_bf16 v[104:107], v[178:181], v[186:189], v[104:107]
	v_mfma_f32_16x16x32_bf16 v[88:91], v[178:181], v[194:197], v[88:91]
	v_mfma_f32_16x16x32_bf16 v[88:91], v[182:185], v[208:211], v[88:91]
	v_mfma_f32_16x16x32_bf16 v[96:99], v[164:167], v[208:211], v[96:99]
	v_mfma_f32_16x16x32_bf16 v[96:99], v[160:163], v[194:197], v[96:99]
	v_mfma_f32_16x16x32_bf16 v[80:83], v[160:163], v[212:215], v[80:83]
	v_mfma_f32_16x16x32_bf16 v[80:83], v[164:167], v[216:219], v[80:83]
	v_mfma_f32_16x16x32_bf16 v[76:79], v[182:185], v[216:219], v[76:79]
	v_mfma_f32_16x16x32_bf16 v[76:79], v[178:181], v[212:215], v[76:79]
	v_mfma_f32_16x16x32_bf16 v[68:71], v[178:181], v[220:223], v[68:71]
	v_mfma_f32_16x16x32_bf16 v[68:71], v[182:185], v[224:227], v[68:71]
	v_mfma_f32_16x16x32_bf16 v[72:75], v[164:167], v[224:227], v[72:75]
	v_mfma_f32_16x16x32_bf16 v[72:75], v[160:163], v[220:223], v[72:75]
	s_barrier
	s_add_i32 s40, s55, s25
	v_lshl_add_u64 v[168:169], v[168:169], 0, s[18:19]
	s_mov_b32 m0, s40
	ds_read_b128 v[186:189], v142 offset:49152
	ds_read_b128 v[190:193], v142 offset:50176
	ds_read_b128 v[194:197], v142 offset:51200
	ds_read_b128 v[208:211], v142 offset:52224
	ds_read_b128 v[212:215], v142 offset:53248
	ds_read_b128 v[216:219], v142 offset:54272
	ds_read_b128 v[220:223], v142 offset:55296
	ds_read_b128 v[224:227], v142 offset:56320
	global_load_lds_dwordx4 v[168:169], off
	s_add_i32 m0, s40, 0x2000
	s_add_u32 s38, s38, 0x200080
	v_lshl_add_u64 v[168:169], v[228:229], 0, s[18:19]
	s_addc_u32 s39, s39, 0
	s_add_i32 s40, s56, s25
	global_load_lds_dwordx4 v[168:169], off
	v_lshl_add_u64 v[168:169], s[38:39], 0, v[134:135]
	s_mov_b32 m0, s40
	s_nop 0
	global_load_lds_dwordx4 v[168:169], off
	v_lshl_add_u64 v[168:169], s[38:39], 0, v[132:133]
	s_add_i32 m0, s40, 0x2000
	s_nop 0
	global_load_lds_dwordx4 v[168:169], off
	v_lshl_add_u64 v[168:169], v[230:231], 0, s[18:19]
	s_mov_b32 m0, s1
	s_nop 0
	global_load_lds_dwordx4 v[168:169], off
	v_lshl_add_u64 v[168:169], v[232:233], 0, s[18:19]
	s_mov_b32 m0, s7
	s_nop 0
	global_load_lds_dwordx4 v[168:169], off
	s_waitcnt vmcnt(8)
	s_waitcnt lgkmcnt(0)
	s_barrier
	s_waitcnt lgkmcnt(0)
	v_mfma_f32_16x16x32_bf16 v[64:67], v[144:147], v[186:189], v[64:67]
	v_mfma_f32_16x16x32_bf16 v[64:67], v[148:151], v[190:193], v[64:67]
	v_mfma_f32_16x16x32_bf16 v[60:63], v[156:159], v[190:193], v[60:63]
	v_mfma_f32_16x16x32_bf16 v[60:63], v[152:155], v[186:189], v[60:63]
	v_mfma_f32_16x16x32_bf16 v[52:55], v[152:155], v[194:197], v[52:55]
	v_mfma_f32_16x16x32_bf16 v[52:55], v[156:159], v[208:211], v[52:55]
	v_mfma_f32_16x16x32_bf16 v[56:59], v[148:151], v[208:211], v[56:59]
	v_mfma_f32_16x16x32_bf16 v[56:59], v[144:147], v[194:197], v[56:59]
	v_mfma_f32_16x16x32_bf16 v[40:43], v[144:147], v[212:215], v[40:43]
	v_mfma_f32_16x16x32_bf16 v[40:43], v[148:151], v[216:219], v[40:43]
	v_mfma_f32_16x16x32_bf16 v[36:39], v[156:159], v[216:219], v[36:39]
	v_mfma_f32_16x16x32_bf16 v[36:39], v[152:155], v[212:215], v[36:39]
	v_mfma_f32_16x16x32_bf16 v[20:23], v[152:155], v[220:223], v[20:23]
	v_mfma_f32_16x16x32_bf16 v[20:23], v[156:159], v[224:227], v[20:23]
	v_mfma_f32_16x16x32_bf16 v[24:27], v[148:151], v[224:227], v[24:27]
	v_mfma_f32_16x16x32_bf16 v[24:27], v[144:147], v[220:223], v[24:27]
	v_mfma_f32_16x16x32_bf16 v[48:51], v[160:163], v[186:189], v[48:51]
	v_mfma_f32_16x16x32_bf16 v[48:51], v[164:167], v[190:193], v[48:51]
	v_mfma_f32_16x16x32_bf16 v[44:47], v[182:185], v[190:193], v[44:47]
	v_mfma_f32_16x16x32_bf16 v[44:47], v[178:181], v[186:189], v[44:47]
	v_mfma_f32_16x16x32_bf16 v[28:31], v[178:181], v[194:197], v[28:31]
	v_mfma_f32_16x16x32_bf16 v[28:31], v[182:185], v[208:211], v[28:31]
	v_mfma_f32_16x16x32_bf16 v[32:35], v[164:167], v[208:211], v[32:35]
	v_mfma_f32_16x16x32_bf16 v[32:35], v[160:163], v[194:197], v[32:35]
	v_mfma_f32_16x16x32_bf16 v[16:19], v[160:163], v[212:215], v[16:19]
	v_mfma_f32_16x16x32_bf16 v[16:19], v[164:167], v[216:219], v[16:19]
	v_mfma_f32_16x16x32_bf16 v[12:15], v[182:185], v[216:219], v[12:15]
	v_mfma_f32_16x16x32_bf16 v[12:15], v[178:181], v[212:215], v[12:15]
	v_mfma_f32_16x16x32_bf16 v[4:7], v[178:181], v[220:223], v[4:7]
	v_mfma_f32_16x16x32_bf16 v[4:7], v[182:185], v[224:227], v[4:7]
	v_mfma_f32_16x16x32_bf16 v[8:11], v[164:167], v[224:227], v[8:11]
	v_mfma_f32_16x16x32_bf16 v[8:11], v[160:163], v[220:223], v[8:11]
	s_barrier
	s_add_i32 s54, s54, 2
	s_add_u32 s36, s36, 0x100
	s_addc_u32 s37, s37, 0
	s_add_u32 s52, s52, 0x100
	s_addc_u32 s53, s53, 0
	s_cmp_gt_u32 s54, 13
	s_cbranch_scc0 .LBB0_1088
	s_setprio 0
	s_and_b64 vcc, exec, s[28:29]
	s_cbranch_vccz .LBB0_1091
	s_barrier

.LBB0_1183:
	s_ashr_i32 s59, s58, 31
	s_lshl_b64 s[10:11], s[58:59], 20
	s_add_u32 s60, s34, s10
	s_addc_u32 s61, s35, s11
	s_and_b64 s[10:11], s[40:41], exec
	s_cselect_b32 s1, s61, s5
	s_cselect_b32 s3, s60, s4
	s_ashr_i32 s57, s56, 31
	s_lshl_b64 s[10:11], s[56:57], 20
	s_add_u32 s62, s36, s10
	s_addc_u32 s63, s37, s11
	s_and_b64 s[10:11], s[40:41], exec
	s_cselect_b32 s7, s63, s9
	s_cselect_b32 s10, s62, s8
	s_add_u32 s4, s4, 0x80080
	s_addc_u32 s5, s5, 0
	s_add_u32 s11, s8, 0x100
	v_mov_b32_e32 v4, 0
	s_addc_u32 s21, s9, 0
	s_mov_b32 s22, -2
	v_mov_b32_e32 v5, v4
	v_mov_b32_e32 v6, v4
	v_mov_b32_e32 v7, v4
	v_mov_b32_e32 v8, v4
	v_mov_b32_e32 v9, v4
	v_mov_b32_e32 v10, v4
	v_mov_b32_e32 v11, v4
	v_mov_b32_e32 v20, v4
	v_mov_b32_e32 v21, v4
	v_mov_b32_e32 v22, v4
	v_mov_b32_e32 v23, v4
	v_mov_b32_e32 v24, v4
	v_mov_b32_e32 v25, v4
	v_mov_b32_e32 v26, v4
	v_mov_b32_e32 v27, v4
	v_mov_b32_e32 v36, v4
	v_mov_b32_e32 v37, v4
	v_mov_b32_e32 v38, v4
	v_mov_b32_e32 v39, v4
	v_mov_b32_e32 v40, v4
	v_mov_b32_e32 v41, v4
	v_mov_b32_e32 v42, v4
	v_mov_b32_e32 v43, v4
	v_mov_b32_e32 v52, v4
	v_mov_b32_e32 v53, v4
	v_mov_b32_e32 v54, v4
	v_mov_b32_e32 v55, v4
	v_mov_b32_e32 v56, v4
	v_mov_b32_e32 v57, v4
	v_mov_b32_e32 v58, v4
	v_mov_b32_e32 v59, v4
	v_mov_b32_e32 v12, v4
	v_mov_b32_e32 v13, v4
	v_mov_b32_e32 v14, v4
	v_mov_b32_e32 v15, v4
	v_mov_b32_e32 v16, v4
	v_mov_b32_e32 v17, v4
	v_mov_b32_e32 v18, v4
	v_mov_b32_e32 v19, v4
	v_mov_b32_e32 v28, v4
	v_mov_b32_e32 v29, v4
	v_mov_b32_e32 v30, v4
	v_mov_b32_e32 v31, v4
	v_mov_b32_e32 v32, v4
	v_mov_b32_e32 v33, v4
	v_mov_b32_e32 v34, v4
	v_mov_b32_e32 v35, v4
	v_mov_b32_e32 v44, v4
	v_mov_b32_e32 v45, v4
	v_mov_b32_e32 v46, v4
	v_mov_b32_e32 v47, v4
	v_mov_b32_e32 v48, v4
	v_mov_b32_e32 v49, v4
	v_mov_b32_e32 v50, v4
	v_mov_b32_e32 v51, v4
	v_mov_b32_e32 v60, v4
	v_mov_b32_e32 v61, v4
	v_mov_b32_e32 v62, v4
	v_mov_b32_e32 v63, v4
	v_mov_b32_e32 v64, v4
	v_mov_b32_e32 v65, v4
	v_mov_b32_e32 v66, v4
	v_mov_b32_e32 v67, v4
	v_mov_b32_e32 v68, v4
	v_mov_b32_e32 v69, v4
	v_mov_b32_e32 v70, v4
	v_mov_b32_e32 v71, v4
	v_mov_b32_e32 v72, v4
	v_mov_b32_e32 v73, v4
	v_mov_b32_e32 v74, v4
	v_mov_b32_e32 v75, v4
	v_mov_b32_e32 v84, v4
	v_mov_b32_e32 v85, v4
	v_mov_b32_e32 v86, v4
	v_mov_b32_e32 v87, v4
	v_mov_b32_e32 v88, v4
	v_mov_b32_e32 v89, v4
	v_mov_b32_e32 v90, v4
	v_mov_b32_e32 v91, v4
	v_mov_b32_e32 v100, v4
	v_mov_b32_e32 v101, v4
	v_mov_b32_e32 v102, v4
	v_mov_b32_e32 v103, v4
	v_mov_b32_e32 v104, v4
	v_mov_b32_e32 v105, v4
	v_mov_b32_e32 v106, v4
	v_mov_b32_e32 v107, v4
	v_mov_b32_e32 v116, v4
	v_mov_b32_e32 v117, v4
	v_mov_b32_e32 v118, v4
	v_mov_b32_e32 v119, v4
	v_mov_b32_e32 v120, v4
	v_mov_b32_e32 v121, v4
	v_mov_b32_e32 v122, v4
	v_mov_b32_e32 v123, v4
	v_mov_b32_e32 v76, v4
	v_mov_b32_e32 v77, v4
	v_mov_b32_e32 v78, v4
	v_mov_b32_e32 v79, v4
	v_mov_b32_e32 v80, v4
	v_mov_b32_e32 v81, v4
	v_mov_b32_e32 v82, v4
	v_mov_b32_e32 v83, v4
	v_mov_b32_e32 v92, v4
	v_mov_b32_e32 v93, v4
	v_mov_b32_e32 v94, v4
	v_mov_b32_e32 v95, v4
	v_mov_b32_e32 v96, v4
	v_mov_b32_e32 v97, v4
	v_mov_b32_e32 v98, v4
	v_mov_b32_e32 v99, v4
	v_mov_b32_e32 v108, v4
	v_mov_b32_e32 v109, v4
	v_mov_b32_e32 v110, v4
	v_mov_b32_e32 v111, v4
	v_mov_b32_e32 v112, v4
	v_mov_b32_e32 v113, v4
	v_mov_b32_e32 v114, v4
	v_mov_b32_e32 v115, v4
	v_mov_b32_e32 v124, v4
	v_mov_b32_e32 v125, v4
	v_mov_b32_e32 v126, v4
	v_mov_b32_e32 v127, v4
	v_mov_b32_e32 v128, v4
	v_mov_b32_e32 v129, v4
	v_mov_b32_e32 v130, v4
	v_mov_b32_e32 v131, v4
	v_lshl_add_u32 v148, s2, 8, v161
	v_ashrrev_i32_e32 v149, 31, v148
	v_lshl_add_u64 v[152:153], v[148:149], 2, s[50:51]
	global_load_dword v246, v[152:153], off
	global_load_dword v247, v[152:153], off offset:64
	global_load_dword v248, v[152:153], off offset:128
	global_load_dword v249, v[152:153], off offset:192
	global_load_dword v250, v[152:153], off offset:512
	global_load_dword v251, v[152:153], off offset:576
	global_load_dword v254, v[152:153], off offset:640
	global_load_dword v255, v[152:153], off offset:704
	s_cmp_lg_u64 s[54:55], 0
	s_cbranch_scc1 .Lsp_g1184
	s_setprio 1
.Lsp_g1184:
.LBB0_1184:
	s_add_u32 s8, s4, 0xfff80080
	s_addc_u32 s9, s5, -1
	s_add_i32 s26, 0, 0x10000
	s_cmp_eq_u32 s22, 28
	s_cselect_b32 s13, s1, s9
	s_cselect_b32 s12, s3, s8
	v_add_u32_e32 v1, s26, v162
	s_cselect_b32 s9, s7, s21
	s_cselect_b32 s8, s10, s11
	s_add_i32 s33, 0, 0x14000
	ds_read_b128 v[148:151], v1
	ds_read_b128 v[152:155], v1 offset:1024
	ds_read_b128 v[156:159], v1 offset:2048
	ds_read_b128 v[166:169], v1 offset:3072
	v_add_u32_e32 v1, s33, v162
	ds_read_b128 v[178:181], v1
	ds_read_b128 v[182:185], v1 offset:1024
	ds_read_b128 v[186:189], v1 offset:2048
	ds_read_b128 v[190:193], v1 offset:3072
	v_lshl_add_u64 v[236:237], s[4:5], 0, v[144:145]
	s_add_i32 m0, s47, 0xc000
	ds_read_b128 v[194:197], v165
	ds_read_b128 v[208:211], v165 offset:1024
	ds_read_b128 v[212:215], v165 offset:2048
	ds_read_b128 v[216:219], v165 offset:3072
	ds_read_b128 v[220:223], v165 offset:4096
	ds_read_b128 v[224:227], v165 offset:5120
	ds_read_b128 v[228:231], v165 offset:6144
	ds_read_b128 v[232:235], v165 offset:7168
	global_load_lds_dwordx4 v[236:237], off
	v_lshl_add_u64 v[236:237], s[4:5], 0, v[146:147]
	s_add_i32 m0, s47, 0xe000
	s_nop 0
	global_load_lds_dwordx4 v[236:237], off
	s_waitcnt vmcnt(8)
	s_waitcnt lgkmcnt(0)
	s_barrier
	s_waitcnt lgkmcnt(0)
	v_mfma_f32_16x16x32_bf16 v[128:131], v[148:151], v[194:197], v[128:131]
	v_mfma_f32_16x16x32_bf16 v[128:131], v[152:155], v[208:211], v[128:131]
	v_mfma_f32_16x16x32_bf16 v[124:127], v[166:169], v[208:211], v[124:127]
	v_mfma_f32_16x16x32_bf16 v[124:127], v[156:159], v[194:197], v[124:127]
	v_mfma_f32_16x16x32_bf16 v[108:111], v[156:159], v[212:215], v[108:111]
	v_mfma_f32_16x16x32_bf16 v[108:111], v[166:169], v[216:219], v[108:111]
	v_mfma_f32_16x16x32_bf16 v[112:115], v[152:155], v[216:219], v[112:115]
	v_mfma_f32_16x16x32_bf16 v[112:115], v[148:151], v[212:215], v[112:115]
	v_mfma_f32_16x16x32_bf16 v[96:99], v[148:151], v[220:223], v[96:99]
	v_mfma_f32_16x16x32_bf16 v[96:99], v[152:155], v[224:227], v[96:99]
	v_mfma_f32_16x16x32_bf16 v[92:95], v[166:169], v[224:227], v[92:95]
	v_mfma_f32_16x16x32_bf16 v[92:95], v[156:159], v[220:223], v[92:95]
	v_mfma_f32_16x16x32_bf16 v[76:79], v[156:159], v[228:231], v[76:79]
	v_mfma_f32_16x16x32_bf16 v[76:79], v[166:169], v[232:235], v[76:79]
	v_mfma_f32_16x16x32_bf16 v[80:83], v[152:155], v[232:235], v[80:83]
	v_mfma_f32_16x16x32_bf16 v[80:83], v[148:151], v[228:231], v[80:83]
	v_mfma_f32_16x16x32_bf16 v[120:123], v[178:181], v[194:197], v[120:123]
	v_mfma_f32_16x16x32_bf16 v[120:123], v[182:185], v[208:211], v[120:123]
	v_mfma_f32_16x16x32_bf16 v[116:119], v[190:193], v[208:211], v[116:119]
	v_mfma_f32_16x16x32_bf16 v[116:119], v[186:189], v[194:197], v[116:119]
	v_mfma_f32_16x16x32_bf16 v[100:103], v[186:189], v[212:215], v[100:103]
	v_mfma_f32_16x16x32_bf16 v[100:103], v[190:193], v[216:219], v[100:103]
	v_mfma_f32_16x16x32_bf16 v[104:107], v[182:185], v[216:219], v[104:107]
	v_mfma_f32_16x16x32_bf16 v[104:107], v[178:181], v[212:215], v[104:107]
	v_mfma_f32_16x16x32_bf16 v[88:91], v[178:181], v[220:223], v[88:91]
	v_mfma_f32_16x16x32_bf16 v[88:91], v[182:185], v[224:227], v[88:91]
	v_mfma_f32_16x16x32_bf16 v[84:87], v[190:193], v[224:227], v[84:87]
	v_mfma_f32_16x16x32_bf16 v[84:87], v[186:189], v[220:223], v[84:87]
	v_mfma_f32_16x16x32_bf16 v[68:71], v[186:189], v[228:231], v[68:71]
	v_mfma_f32_16x16x32_bf16 v[68:71], v[190:193], v[232:235], v[68:71]
	v_mfma_f32_16x16x32_bf16 v[72:75], v[182:185], v[232:235], v[72:75]
	v_mfma_f32_16x16x32_bf16 v[72:75], v[178:181], v[228:231], v[72:75]
	s_barrier
	s_add_i32 s26, s26, s65
	v_lshl_add_u64 v[236:237], s[8:9], 0, v[134:135]
	s_mov_b32 m0, s26
	ds_read_b128 v[194:197], v165 offset:16384
	ds_read_b128 v[208:211], v165 offset:17408
	ds_read_b128 v[212:215], v165 offset:18432
	ds_read_b128 v[216:219], v165 offset:19456
	ds_read_b128 v[220:223], v165 offset:20480
	ds_read_b128 v[224:227], v165 offset:21504
	ds_read_b128 v[228:231], v165 offset:22528
	ds_read_b128 v[232:235], v165 offset:23552
	global_load_lds_dwordx4 v[236:237], off
	s_add_i32 m0, s26, 0x2000
	s_add_u32 s26, s8, 0x80000
	v_lshl_add_u64 v[238:239], s[8:9], 0, v[138:139]
	s_addc_u32 s27, s9, 0
	s_add_i32 s33, s33, s65
	global_load_lds_dwordx4 v[238:239], off
	v_lshl_add_u64 v[240:241], s[26:27], 0, v[134:135]
	s_mov_b32 m0, s33
	v_lshl_add_u64 v[242:243], s[12:13], 0, v[136:137]
	global_load_lds_dwordx4 v[240:241], off
	v_lshl_add_u64 v[240:241], s[26:27], 0, v[138:139]
	s_add_i32 m0, s33, 0x2000
	s_nop 0
	global_load_lds_dwordx4 v[240:241], off
	v_lshl_add_u64 v[240:241], s[12:13], 0, v[132:133]
	s_mov_b32 m0, s47
	s_nop 0
	global_load_lds_dwordx4 v[240:241], off
	s_mov_b32 m0, s66
	s_nop 0
	global_load_lds_dwordx4 v[242:243], off
	s_waitcnt vmcnt(8)
	s_waitcnt lgkmcnt(0)
	s_barrier
	s_waitcnt lgkmcnt(0)
	v_mfma_f32_16x16x32_bf16 v[64:67], v[148:151], v[194:197], v[64:67]
	v_mfma_f32_16x16x32_bf16 v[64:67], v[152:155], v[208:211], v[64:67]
	v_mfma_f32_16x16x32_bf16 v[60:63], v[166:169], v[208:211], v[60:63]
	v_mfma_f32_16x16x32_bf16 v[60:63], v[156:159], v[194:197], v[60:63]
	v_mfma_f32_16x16x32_bf16 v[44:47], v[156:159], v[212:215], v[44:47]
	v_mfma_f32_16x16x32_bf16 v[44:47], v[166:169], v[216:219], v[44:47]
	v_mfma_f32_16x16x32_bf16 v[48:51], v[152:155], v[216:219], v[48:51]
	v_mfma_f32_16x16x32_bf16 v[48:51], v[148:151], v[212:215], v[48:51]
	v_mfma_f32_16x16x32_bf16 v[32:35], v[148:151], v[220:223], v[32:35]
	v_mfma_f32_16x16x32_bf16 v[32:35], v[152:155], v[224:227], v[32:35]
	v_mfma_f32_16x16x32_bf16 v[28:31], v[166:169], v[224:227], v[28:31]
	v_mfma_f32_16x16x32_bf16 v[28:31], v[156:159], v[220:223], v[28:31]
	v_mfma_f32_16x16x32_bf16 v[12:15], v[156:159], v[228:231], v[12:15]
	v_mfma_f32_16x16x32_bf16 v[12:15], v[166:169], v[232:235], v[12:15]
	v_mfma_f32_16x16x32_bf16 v[16:19], v[152:155], v[232:235], v[16:19]
	v_mfma_f32_16x16x32_bf16 v[16:19], v[148:151], v[228:231], v[16:19]
	v_mfma_f32_16x16x32_bf16 v[56:59], v[178:181], v[194:197], v[56:59]
	v_mfma_f32_16x16x32_bf16 v[56:59], v[182:185], v[208:211], v[56:59]
	v_mfma_f32_16x16x32_bf16 v[52:55], v[190:193], v[208:211], v[52:55]
	v_mfma_f32_16x16x32_bf16 v[52:55], v[186:189], v[194:197], v[52:55]
	v_mfma_f32_16x16x32_bf16 v[36:39], v[186:189], v[212:215], v[36:39]
	v_mfma_f32_16x16x32_bf16 v[36:39], v[190:193], v[216:219], v[36:39]
	v_mfma_f32_16x16x32_bf16 v[40:43], v[182:185], v[216:219], v[40:43]
	v_mfma_f32_16x16x32_bf16 v[40:43], v[178:181], v[212:215], v[40:43]
	v_mfma_f32_16x16x32_bf16 v[24:27], v[178:181], v[220:223], v[24:27]
	v_mfma_f32_16x16x32_bf16 v[24:27], v[182:185], v[224:227], v[24:27]
	v_mfma_f32_16x16x32_bf16 v[20:23], v[190:193], v[224:227], v[20:23]
	v_mfma_f32_16x16x32_bf16 v[20:23], v[186:189], v[220:223], v[20:23]
	v_mfma_f32_16x16x32_bf16 v[4:7], v[186:189], v[228:231], v[4:7]
	v_mfma_f32_16x16x32_bf16 v[4:7], v[190:193], v[232:235], v[4:7]
	v_mfma_f32_16x16x32_bf16 v[8:11], v[182:185], v[232:235], v[8:11]
	v_mfma_f32_16x16x32_bf16 v[8:11], v[178:181], v[228:231], v[8:11]
	s_barrier
	s_add_i32 s26, 0, 0x18000
	v_add_u32_e32 v1, s26, v162
	s_add_i32 s27, 0, 0x1c000
	ds_read_b128 v[148:151], v1
	ds_read_b128 v[152:155], v1 offset:1024
	ds_read_b128 v[156:159], v1 offset:2048
	ds_read_b128 v[166:169], v1 offset:3072
	v_add_u32_e32 v1, s27, v162
	ds_read_b128 v[178:181], v1
	ds_read_b128 v[182:185], v1 offset:1024
	ds_read_b128 v[186:189], v1 offset:2048
	ds_read_b128 v[190:193], v1 offset:3072
	s_add_u32 s12, s12, 0x80000
	s_addc_u32 s13, s13, 0
	s_mov_b32 m0, s67
	v_lshl_add_u64 v[244:245], s[12:13], 0, v[132:133]
	ds_read_b128 v[194:197], v165 offset:32768
	ds_read_b128 v[208:211], v165 offset:33792
	ds_read_b128 v[212:215], v165 offset:34816
	ds_read_b128 v[216:219], v165 offset:35840
	ds_read_b128 v[220:223], v165 offset:36864
	ds_read_b128 v[224:227], v165 offset:37888
	ds_read_b128 v[228:231], v165 offset:38912
	ds_read_b128 v[232:235], v165 offset:39936
	global_load_lds_dwordx4 v[244:245], off
	v_lshl_add_u64 v[244:245], s[12:13], 0, v[136:137]
	s_mov_b32 m0, s68
	s_nop 0
	global_load_lds_dwordx4 v[244:245], off
	s_waitcnt vmcnt(8)
	s_waitcnt lgkmcnt(0)
	s_barrier
	s_waitcnt lgkmcnt(0)
	v_mfma_f32_16x16x32_bf16 v[128:131], v[148:151], v[194:197], v[128:131]
	v_mfma_f32_16x16x32_bf16 v[128:131], v[152:155], v[208:211], v[128:131]
	v_mfma_f32_16x16x32_bf16 v[124:127], v[166:169], v[208:211], v[124:127]
	v_mfma_f32_16x16x32_bf16 v[124:127], v[156:159], v[194:197], v[124:127]
	v_mfma_f32_16x16x32_bf16 v[108:111], v[156:159], v[212:215], v[108:111]
	v_mfma_f32_16x16x32_bf16 v[108:111], v[166:169], v[216:219], v[108:111]
	v_mfma_f32_16x16x32_bf16 v[112:115], v[152:155], v[216:219], v[112:115]
	v_mfma_f32_16x16x32_bf16 v[112:115], v[148:151], v[212:215], v[112:115]
	v_mfma_f32_16x16x32_bf16 v[96:99], v[148:151], v[220:223], v[96:99]
	v_mfma_f32_16x16x32_bf16 v[96:99], v[152:155], v[224:227], v[96:99]
	v_mfma_f32_16x16x32_bf16 v[92:95], v[166:169], v[224:227], v[92:95]
	v_mfma_f32_16x16x32_bf16 v[92:95], v[156:159], v[220:223], v[92:95]
	v_mfma_f32_16x16x32_bf16 v[76:79], v[156:159], v[228:231], v[76:79]
	v_mfma_f32_16x16x32_bf16 v[76:79], v[166:169], v[232:235], v[76:79]
	v_mfma_f32_16x16x32_bf16 v[80:83], v[152:155], v[232:235], v[80:83]
	v_mfma_f32_16x16x32_bf16 v[80:83], v[148:151], v[228:231], v[80:83]
	v_mfma_f32_16x16x32_bf16 v[120:123], v[178:181], v[194:197], v[120:123]
	v_mfma_f32_16x16x32_bf16 v[120:123], v[182:185], v[208:211], v[120:123]
	v_mfma_f32_16x16x32_bf16 v[116:119], v[190:193], v[208:211], v[116:119]
	v_mfma_f32_16x16x32_bf16 v[116:119], v[186:189], v[194:197], v[116:119]
	v_mfma_f32_16x16x32_bf16 v[100:103], v[186:189], v[212:215], v[100:103]
	v_mfma_f32_16x16x32_bf16 v[100:103], v[190:193], v[216:219], v[100:103]
	v_mfma_f32_16x16x32_bf16 v[104:107], v[182:185], v[216:219], v[104:107]
	v_mfma_f32_16x16x32_bf16 v[104:107], v[178:181], v[212:215], v[104:107]
	v_mfma_f32_16x16x32_bf16 v[88:91], v[178:181], v[220:223], v[88:91]
	v_mfma_f32_16x16x32_bf16 v[88:91], v[182:185], v[224:227], v[88:91]
	v_mfma_f32_16x16x32_bf16 v[84:87], v[190:193], v[224:227], v[84:87]
	v_mfma_f32_16x16x32_bf16 v[84:87], v[186:189], v[220:223], v[84:87]
	v_mfma_f32_16x16x32_bf16 v[68:71], v[186:189], v[228:231], v[68:71]
	v_mfma_f32_16x16x32_bf16 v[68:71], v[190:193], v[232:235], v[68:71]
	v_mfma_f32_16x16x32_bf16 v[72:75], v[182:185], v[232:235], v[72:75]
	v_mfma_f32_16x16x32_bf16 v[72:75], v[178:181], v[228:231], v[72:75]
	s_barrier
	s_add_i32 s12, s26, s65
	v_lshl_add_u64 v[236:237], v[236:237], 0, s[18:19]
	s_mov_b32 m0, s12
	ds_read_b128 v[194:197], v165 offset:49152
	ds_read_b128 v[208:211], v165 offset:50176
	ds_read_b128 v[212:215], v165 offset:51200
	ds_read_b128 v[216:219], v165 offset:52224
	ds_read_b128 v[220:223], v165 offset:53248
	ds_read_b128 v[224:227], v165 offset:54272
	ds_read_b128 v[228:231], v165 offset:55296
	ds_read_b128 v[232:235], v165 offset:56320
	global_load_lds_dwordx4 v[236:237], off
	s_add_i32 m0, s12, 0x2000
	s_add_u32 s8, s8, 0x80080
	v_lshl_add_u64 v[236:237], v[238:239], 0, s[18:19]
	s_addc_u32 s9, s9, 0
	s_add_i32 s12, s27, s65
	global_load_lds_dwordx4 v[236:237], off
	v_lshl_add_u64 v[236:237], s[8:9], 0, v[134:135]
	s_mov_b32 m0, s12
	s_nop 0
	global_load_lds_dwordx4 v[236:237], off
	v_lshl_add_u64 v[236:237], s[8:9], 0, v[138:139]
	s_add_i32 m0, s12, 0x2000
	s_nop 0
	global_load_lds_dwordx4 v[236:237], off
	v_lshl_add_u64 v[236:237], v[240:241], 0, s[18:19]
	s_mov_b32 m0, s82
	s_nop 0
	global_load_lds_dwordx4 v[236:237], off
	v_lshl_add_u64 v[236:237], v[242:243], 0, s[18:19]
	s_mov_b32 m0, s83
	s_nop 0
	global_load_lds_dwordx4 v[236:237], off
	s_waitcnt vmcnt(8)
	s_waitcnt lgkmcnt(0)
	s_barrier
	s_waitcnt lgkmcnt(0)
	v_mfma_f32_16x16x32_bf16 v[64:67], v[148:151], v[194:197], v[64:67]
	v_mfma_f32_16x16x32_bf16 v[64:67], v[152:155], v[208:211], v[64:67]
	v_mfma_f32_16x16x32_bf16 v[60:63], v[166:169], v[208:211], v[60:63]
	v_mfma_f32_16x16x32_bf16 v[60:63], v[156:159], v[194:197], v[60:63]
	v_mfma_f32_16x16x32_bf16 v[44:47], v[156:159], v[212:215], v[44:47]
	v_mfma_f32_16x16x32_bf16 v[44:47], v[166:169], v[216:219], v[44:47]
	v_mfma_f32_16x16x32_bf16 v[48:51], v[152:155], v[216:219], v[48:51]
	v_mfma_f32_16x16x32_bf16 v[48:51], v[148:151], v[212:215], v[48:51]
	v_mfma_f32_16x16x32_bf16 v[32:35], v[148:151], v[220:223], v[32:35]
	v_mfma_f32_16x16x32_bf16 v[32:35], v[152:155], v[224:227], v[32:35]
	v_mfma_f32_16x16x32_bf16 v[28:31], v[166:169], v[224:227], v[28:31]
	v_mfma_f32_16x16x32_bf16 v[28:31], v[156:159], v[220:223], v[28:31]
	v_mfma_f32_16x16x32_bf16 v[12:15], v[156:159], v[228:231], v[12:15]
	v_mfma_f32_16x16x32_bf16 v[12:15], v[166:169], v[232:235], v[12:15]
	v_mfma_f32_16x16x32_bf16 v[16:19], v[152:155], v[232:235], v[16:19]
	v_mfma_f32_16x16x32_bf16 v[16:19], v[148:151], v[228:231], v[16:19]
	v_mfma_f32_16x16x32_bf16 v[56:59], v[178:181], v[194:197], v[56:59]
	v_mfma_f32_16x16x32_bf16 v[56:59], v[182:185], v[208:211], v[56:59]
	v_mfma_f32_16x16x32_bf16 v[52:55], v[190:193], v[208:211], v[52:55]
	v_mfma_f32_16x16x32_bf16 v[52:55], v[186:189], v[194:197], v[52:55]
	v_mfma_f32_16x16x32_bf16 v[36:39], v[186:189], v[212:215], v[36:39]
	v_mfma_f32_16x16x32_bf16 v[36:39], v[190:193], v[216:219], v[36:39]
	v_mfma_f32_16x16x32_bf16 v[40:43], v[182:185], v[216:219], v[40:43]
	v_mfma_f32_16x16x32_bf16 v[40:43], v[178:181], v[212:215], v[40:43]
	v_mfma_f32_16x16x32_bf16 v[24:27], v[178:181], v[220:223], v[24:27]
	v_mfma_f32_16x16x32_bf16 v[24:27], v[182:185], v[224:227], v[24:27]
	v_mfma_f32_16x16x32_bf16 v[20:23], v[190:193], v[224:227], v[20:23]
	v_mfma_f32_16x16x32_bf16 v[20:23], v[186:189], v[220:223], v[20:23]
	v_mfma_f32_16x16x32_bf16 v[4:7], v[186:189], v[228:231], v[4:7]
	v_mfma_f32_16x16x32_bf16 v[4:7], v[190:193], v[232:235], v[4:7]
	v_mfma_f32_16x16x32_bf16 v[8:11], v[182:185], v[232:235], v[8:11]
	v_mfma_f32_16x16x32_bf16 v[8:11], v[178:181], v[228:231], v[8:11]
	s_barrier
	s_add_i32 s22, s22, 2
	s_add_u32 s4, s4, 0x100
	s_addc_u32 s5, s5, 0
	s_add_u32 s11, s11, 0x100
	s_addc_u32 s21, s21, 0
	s_cmp_gt_u32 s22, 29
	s_cbranch_scc0 .LBB0_1184
	s_setprio 0
	s_and_b64 vcc, exec, s[54:55]
	s_cbranch_vccz .LBB0_1187
	s_barrier
